# GEMM K-loops: loop-counter/pointer SALU block rotated ahead of the loop-back barrier (back-edge rotation)
# baseline (speedup 1.0000x reference)
; #define PG8_STAGE(bufoff, gbase, voff) do { _Pragma("unroll") for (int _i = 0; _i < 2; ++_i) \
;         __builtin_amdgcn_global_load_lds((const unsigned*)((const char*)(gbase) + (voff)[_i]), (LAS unsigned*)(lds + (bufoff) + ldsw + _i * 8192), 16, 0, 0); } while (0)
; #define PG8_LDA(dst, b, h) do { _Pragma("unroll") for (int m = 0; m < 4; ++m) _Pragma("unroll") for (int k = 0; k < 2; ++k) dst[m][k] = *(const LAS bf16x8*)(lds + PG8_SA(b, h) + aoff + m * 2048 + k * 1024); } while (0)
; #define PG8_LDB(dst, b, h) do { _Pragma("unroll") for (int n = 0; n < 2; ++n) _Pragma("unroll") for (int k = 0; k < 2; ++k) dst[n][k] = *(const LAS bf16x8*)(lds + PG8_SB(b, h) + boff + n * 2048 + k * 1024); } while (0)
; #define PG8_MMA(ai, bj, At, Bt) do { __builtin_amdgcn_s_setprio(1); _Pragma("unroll") for (int m = 0; m < 4; ++m) _Pragma("unroll") for (int n = 0; n < 2; ++n) _Pragma("unroll") for (int k = 0; k < 2; ++k) \
;         acc[ai][bj][m][n] = __builtin_amdgcn_mfma_f32_16x16x32_bf16(Bt[n][k], At[m][k], acc[ai][bj][m][n], 0, 0, 0); __builtin_amdgcn_s_setprio(0); } while (0)
; #define PG8_WAIT_V(n) asm volatile("s_waitcnt vmcnt(" #n ")" ::: "memory")
; #define PG8_WAIT_L(n) asm volatile("s_waitcnt lgkmcnt(" #n ")" ::: "memory")
; template <class Epi, class Sched, bool ALIGN_EPI, bool LAST_FUSED = false, bool PERM = false, bool CARRY = false>
; __device__ __forceinline__ void gemm_phase(LAS unsigned char* lds, const int tid, const int K, const int lda, const int ldb, const Sched& S, const Epi& E) {
;     ...
;         for (int t = 0; t < nt; t += 2) {
;             const bool last = (t == nt - 2);
;             const char* a1 = cA + (size_t)(t + 1) * kstep;
;             const char* a2 = last ? nA : cA + (size_t)(t + 2) * kstep; const char* b2 = last ? nB : cB + (size_t)(t + 2) * kstep;
;             const char* a3 = a2 + kstep; const char* b3 = b2 + kstep;
;             PG8_LDB(B0, 0, 0); PG8_LDB(B1, 0, 1); PG8_SCHED; PG8_LDA(At, 0, 0); PG8_STAGE(PG8_SA(1, 1), a1 + hstepA, voffA);
;             PG8_WAIT_V(8); PG8_WAIT_L(0); PG8_BAR; PG8_MMA(0, 0, At, B0); PG8_MMA(0, 1, At, B1); PG8_BAR; PG8_SCHED;
;             PG8_LDA(At, 0, 1); PG8_STAGE(PG8_SB(0, 0), b2, voffB); PG8_STAGE(PG8_SB(0, 1), b2 + hstepB, voffB); PG8_STAGE(PG8_SA(0, 0), a2, voffA);
;             PG8_WAIT_V(8); PG8_WAIT_L(0); PG8_BAR; PG8_MMA(1, 0, At, B0); PG8_MMA(1, 1, At, B1); PG8_BAR; PG8_SCHED;
.LBB0_279:
	s_add_u32 s4, s2, 0xfff80080
	s_addc_u32 s5, s3, -1
	s_add_i32 s28, 0, 0x10000
	s_cmp_eq_u32 s27, 28
	s_cselect_b32 s37, s43, s5
	s_cselect_b32 s36, s42, s4
	s_cselect_b32 s5, s71, s23
	s_cselect_b32 s4, s70, s22
	s_add_i32 s31, 0, 0x14000
	v_add_u32_e32 v154, s28, v144
	v_add_u32_e32 v170, s31, v144
	ds_read_b128 v[136:139], v154
	ds_read_b128 v[146:149], v154 offset:1024
	ds_read_b128 v[150:153], v154 offset:2048
	ds_read_b128 v[154:157], v154 offset:3072
	ds_read_b128 v[158:161], v170
	ds_read_b128 v[162:165], v170 offset:1024
	ds_read_b128 v[166:169], v170 offset:2048
	ds_read_b128 v[170:173], v170 offset:3072
	v_lshl_add_u64 v[206:207], s[2:3], 0, v[132:133]
	s_add_i32 m0, s52, 0xc000
	ds_read_b128 v[174:177], v145
	ds_read_b128 v[178:181], v145 offset:1024
	ds_read_b128 v[182:185], v145 offset:2048
	ds_read_b128 v[186:189], v145 offset:3072
	ds_read_b128 v[190:193], v145 offset:4096
	ds_read_b128 v[194:197], v145 offset:5120
	ds_read_b128 v[198:201], v145 offset:6144
	ds_read_b128 v[202:205], v145 offset:7168
	global_load_lds_dwordx4 v[206:207], off
	v_lshl_add_u64 v[206:207], s[2:3], 0, v[134:135]
	s_add_i32 m0, s52, 0xe000
	s_nop 0
	global_load_lds_dwordx4 v[206:207], off
	s_waitcnt vmcnt(8)
	s_waitcnt lgkmcnt(0)
	s_barrier
	s_setprio 1
	s_waitcnt lgkmcnt(0)
	v_mfma_f32_16x16x32_bf16 v[126:129], v[136:139], v[174:177], v[126:129]
	v_mfma_f32_16x16x32_bf16 v[122:125], v[150:153], v[174:177], v[122:125]
	v_mfma_f32_16x16x32_bf16 v[110:113], v[136:139], v[182:185], v[110:113]
	v_mfma_f32_16x16x32_bf16 v[106:109], v[150:153], v[182:185], v[106:109]
	v_mfma_f32_16x16x32_bf16 v[94:97], v[136:139], v[190:193], v[94:97]
	v_mfma_f32_16x16x32_bf16 v[90:93], v[150:153], v[190:193], v[90:93]
	v_mfma_f32_16x16x32_bf16 v[78:81], v[136:139], v[198:201], v[78:81]
	v_mfma_f32_16x16x32_bf16 v[74:77], v[150:153], v[198:201], v[74:77]
	v_mfma_f32_16x16x32_bf16 v[126:129], v[146:149], v[178:181], v[126:129]
	v_mfma_f32_16x16x32_bf16 v[122:125], v[154:157], v[178:181], v[122:125]
	v_mfma_f32_16x16x32_bf16 v[110:113], v[146:149], v[186:189], v[110:113]
	v_mfma_f32_16x16x32_bf16 v[106:109], v[154:157], v[186:189], v[106:109]
	v_mfma_f32_16x16x32_bf16 v[94:97], v[146:149], v[194:197], v[94:97]
	v_mfma_f32_16x16x32_bf16 v[90:93], v[154:157], v[194:197], v[90:93]
	v_mfma_f32_16x16x32_bf16 v[78:81], v[146:149], v[202:205], v[78:81]
	v_mfma_f32_16x16x32_bf16 v[74:77], v[154:157], v[202:205], v[74:77]
	s_setprio 0
	s_setprio 1
	v_mfma_f32_16x16x32_bf16 v[118:121], v[158:161], v[174:177], v[118:121]
	v_mfma_f32_16x16x32_bf16 v[114:117], v[166:169], v[174:177], v[114:117]
	v_mfma_f32_16x16x32_bf16 v[102:105], v[158:161], v[182:185], v[102:105]
	v_mfma_f32_16x16x32_bf16 v[98:101], v[166:169], v[182:185], v[98:101]
	v_mfma_f32_16x16x32_bf16 v[86:89], v[158:161], v[190:193], v[86:89]
	v_mfma_f32_16x16x32_bf16 v[82:85], v[166:169], v[190:193], v[82:85]
	v_mfma_f32_16x16x32_bf16 v[70:73], v[158:161], v[198:201], v[70:73]
	v_mfma_f32_16x16x32_bf16 v[66:69], v[166:169], v[198:201], v[66:69]
	v_mfma_f32_16x16x32_bf16 v[118:121], v[162:165], v[178:181], v[118:121]
	v_mfma_f32_16x16x32_bf16 v[114:117], v[170:173], v[178:181], v[114:117]
	v_mfma_f32_16x16x32_bf16 v[102:105], v[162:165], v[186:189], v[102:105]
	v_mfma_f32_16x16x32_bf16 v[98:101], v[170:173], v[186:189], v[98:101]
	v_mfma_f32_16x16x32_bf16 v[86:89], v[162:165], v[194:197], v[86:89]
	v_mfma_f32_16x16x32_bf16 v[82:85], v[170:173], v[194:197], v[82:85]
	v_mfma_f32_16x16x32_bf16 v[70:73], v[162:165], v[202:205], v[70:73]
	v_mfma_f32_16x16x32_bf16 v[66:69], v[170:173], v[202:205], v[66:69]
	s_setprio 0
	s_barrier
	s_add_i32 s28, s28, s51
	v_lshl_add_u64 v[206:207], s[4:5], 0, v[0:1]
	s_mov_b32 m0, s28
	ds_read_b128 v[174:177], v145 offset:16384
	ds_read_b128 v[178:181], v145 offset:17408
	ds_read_b128 v[182:185], v145 offset:18432
	ds_read_b128 v[186:189], v145 offset:19456
	ds_read_b128 v[190:193], v145 offset:20480
	ds_read_b128 v[194:197], v145 offset:21504
	ds_read_b128 v[198:201], v145 offset:22528
	ds_read_b128 v[202:205], v145 offset:23552
	global_load_lds_dwordx4 v[206:207], off
	s_add_i32 m0, s28, 0x2000
	s_add_u32 s28, s4, 0x80000
	v_lshl_add_u64 v[208:209], s[4:5], 0, v[130:131]
	s_addc_u32 s29, s5, 0
	s_add_i32 s31, s31, s51
	global_load_lds_dwordx4 v[208:209], off
	v_lshl_add_u64 v[210:211], s[28:29], 0, v[0:1]
	s_mov_b32 m0, s31
	v_lshl_add_u64 v[212:213], s[36:37], 0, v[130:131]
	global_load_lds_dwordx4 v[210:211], off
	v_lshl_add_u64 v[210:211], s[28:29], 0, v[130:131]
	s_add_i32 m0, s31, 0x2000
	s_nop 0
	global_load_lds_dwordx4 v[210:211], off
	v_lshl_add_u64 v[210:211], s[36:37], 0, v[0:1]
	s_mov_b32 m0, s52
	s_nop 0
	global_load_lds_dwordx4 v[210:211], off
	s_mov_b32 m0, s53
	s_nop 0
	global_load_lds_dwordx4 v[212:213], off
	s_waitcnt vmcnt(8)
	s_waitcnt lgkmcnt(0)
	s_barrier
; #define PG8_STAGE(bufoff, gbase, voff) do { _Pragma("unroll") for (int _i = 0; _i < 2; ++_i) \
;         __builtin_amdgcn_global_load_lds((const unsigned*)((const char*)(gbase) + (voff)[_i]), (LAS unsigned*)(lds + (bufoff) + ldsw + _i * 8192), 16, 0, 0); } while (0)
; #define PG8_LDA(dst, b, h) do { _Pragma("unroll") for (int m = 0; m < 4; ++m) _Pragma("unroll") for (int k = 0; k < 2; ++k) dst[m][k] = *(const LAS bf16x8*)(lds + PG8_SA(b, h) + aoff + m * 2048 + k * 1024); } while (0)
; #define PG8_LDB(dst, b, h) do { _Pragma("unroll") for (int n = 0; n < 2; ++n) _Pragma("unroll") for (int k = 0; k < 2; ++k) dst[n][k] = *(const LAS bf16x8*)(lds + PG8_SB(b, h) + boff + n * 2048 + k * 1024); } while (0)
; #define PG8_MMA(ai, bj, At, Bt) do { __builtin_amdgcn_s_setprio(1); _Pragma("unroll") for (int m = 0; m < 4; ++m) _Pragma("unroll") for (int n = 0; n < 2; ++n) _Pragma("unroll") for (int k = 0; k < 2; ++k) \
;         acc[ai][bj][m][n] = __builtin_amdgcn_mfma_f32_16x16x32_bf16(Bt[n][k], At[m][k], acc[ai][bj][m][n], 0, 0, 0); __builtin_amdgcn_s_setprio(0); } while (0)
; #define PG8_WAIT_V(n) asm volatile("s_waitcnt vmcnt(" #n ")" ::: "memory")
; #define PG8_WAIT_L(n) asm volatile("s_waitcnt lgkmcnt(" #n ")" ::: "memory")
; #define PG8_BAR __builtin_amdgcn_s_barrier()
; #define PG8_SCHED __builtin_amdgcn_sched_barrier(0)
; template <class Epi, class Sched, bool ALIGN_EPI, bool LAST_FUSED = false, bool PERM = false, bool CARRY = false>
; __device__ __forceinline__ void gemm_phase(LAS unsigned char* lds, const int tid, const int K, const int lda, const int ldb, const Sched& S, const Epi& E) {
;     ...
;             PG8_WAIT_V(8); PG8_WAIT_L(0); PG8_BAR; PG8_MMA(1, 0, At, B0); PG8_MMA(1, 1, At, B1); PG8_BAR; PG8_SCHED;
;             PG8_LDB(B0, 1, 0); PG8_LDB(B1, 1, 1); PG8_SCHED; PG8_LDA(At, 1, 0); PG8_STAGE(PG8_SA(0, 1), a2 + hstepA, voffA);
;             PG8_WAIT_V(8); PG8_WAIT_L(0); PG8_BAR; PG8_MMA(0, 0, At, B0); PG8_MMA(0, 1, At, B1); PG8_BAR; PG8_SCHED;
	s_setprio 1
	s_waitcnt lgkmcnt(0)
	v_mfma_f32_16x16x32_bf16 v[62:65], v[136:139], v[174:177], v[62:65]
	v_mfma_f32_16x16x32_bf16 v[58:61], v[150:153], v[174:177], v[58:61]
	v_mfma_f32_16x16x32_bf16 v[46:49], v[136:139], v[182:185], v[46:49]
	v_mfma_f32_16x16x32_bf16 v[42:45], v[150:153], v[182:185], v[42:45]
	v_mfma_f32_16x16x32_bf16 v[30:33], v[136:139], v[190:193], v[30:33]
	v_mfma_f32_16x16x32_bf16 v[26:29], v[150:153], v[190:193], v[26:29]
	v_mfma_f32_16x16x32_bf16 v[14:17], v[136:139], v[198:201], v[14:17]
	v_mfma_f32_16x16x32_bf16 v[10:13], v[150:153], v[198:201], v[10:13]
	v_mfma_f32_16x16x32_bf16 v[62:65], v[146:149], v[178:181], v[62:65]
	v_mfma_f32_16x16x32_bf16 v[58:61], v[154:157], v[178:181], v[58:61]
	v_mfma_f32_16x16x32_bf16 v[46:49], v[146:149], v[186:189], v[46:49]
	v_mfma_f32_16x16x32_bf16 v[42:45], v[154:157], v[186:189], v[42:45]
	v_mfma_f32_16x16x32_bf16 v[30:33], v[146:149], v[194:197], v[30:33]
	v_mfma_f32_16x16x32_bf16 v[26:29], v[154:157], v[194:197], v[26:29]
	v_mfma_f32_16x16x32_bf16 v[14:17], v[146:149], v[202:205], v[14:17]
	v_mfma_f32_16x16x32_bf16 v[10:13], v[154:157], v[202:205], v[10:13]
	s_setprio 0
	s_setprio 1
	v_mfma_f32_16x16x32_bf16 v[54:57], v[158:161], v[174:177], v[54:57]
	v_mfma_f32_16x16x32_bf16 v[50:53], v[166:169], v[174:177], v[50:53]
	v_mfma_f32_16x16x32_bf16 v[38:41], v[158:161], v[182:185], v[38:41]
	v_mfma_f32_16x16x32_bf16 v[34:37], v[166:169], v[182:185], v[34:37]
	v_mfma_f32_16x16x32_bf16 v[22:25], v[158:161], v[190:193], v[22:25]
	v_mfma_f32_16x16x32_bf16 v[18:21], v[166:169], v[190:193], v[18:21]
	v_mfma_f32_16x16x32_bf16 v[6:9], v[158:161], v[198:201], v[6:9]
	v_mfma_f32_16x16x32_bf16 v[2:5], v[166:169], v[198:201], v[2:5]
	v_mfma_f32_16x16x32_bf16 v[54:57], v[162:165], v[178:181], v[54:57]
	v_mfma_f32_16x16x32_bf16 v[50:53], v[170:173], v[178:181], v[50:53]
	v_mfma_f32_16x16x32_bf16 v[38:41], v[162:165], v[186:189], v[38:41]
	v_mfma_f32_16x16x32_bf16 v[34:37], v[170:173], v[186:189], v[34:37]
	v_mfma_f32_16x16x32_bf16 v[22:25], v[162:165], v[194:197], v[22:25]
	v_mfma_f32_16x16x32_bf16 v[18:21], v[170:173], v[194:197], v[18:21]
	v_mfma_f32_16x16x32_bf16 v[6:9], v[162:165], v[202:205], v[6:9]
	v_mfma_f32_16x16x32_bf16 v[2:5], v[170:173], v[202:205], v[2:5]
	s_setprio 0
	s_barrier
	s_add_i32 s31, 0, 0x18000
	s_add_i32 s35, 0, 0x1c000
	v_add_u32_e32 v154, s31, v144
	v_add_u32_e32 v170, s35, v144
	ds_read_b128 v[136:139], v154
	ds_read_b128 v[146:149], v154 offset:1024
	ds_read_b128 v[150:153], v154 offset:2048
	ds_read_b128 v[154:157], v154 offset:3072
	ds_read_b128 v[158:161], v170
	ds_read_b128 v[162:165], v170 offset:1024
	ds_read_b128 v[166:169], v170 offset:2048
	ds_read_b128 v[170:173], v170 offset:3072
	s_add_u32 s28, s36, 0x80000
	s_addc_u32 s29, s37, 0
	s_mov_b32 m0, s54
	v_lshl_add_u64 v[214:215], s[28:29], 0, v[0:1]
	ds_read_b128 v[174:177], v145 offset:32768
	ds_read_b128 v[178:181], v145 offset:33792
	ds_read_b128 v[182:185], v145 offset:34816
	ds_read_b128 v[186:189], v145 offset:35840
	ds_read_b128 v[190:193], v145 offset:36864
	ds_read_b128 v[194:197], v145 offset:37888
	ds_read_b128 v[198:201], v145 offset:38912
	ds_read_b128 v[202:205], v145 offset:39936
	global_load_lds_dwordx4 v[214:215], off
	v_lshl_add_u64 v[214:215], s[28:29], 0, v[130:131]
	s_mov_b32 m0, s55
	s_nop 0
	global_load_lds_dwordx4 v[214:215], off
	s_waitcnt vmcnt(8)
	s_waitcnt lgkmcnt(0)
	s_barrier
	s_setprio 1
	s_waitcnt lgkmcnt(0)
	v_mfma_f32_16x16x32_bf16 v[126:129], v[136:139], v[174:177], v[126:129]
	v_mfma_f32_16x16x32_bf16 v[122:125], v[150:153], v[174:177], v[122:125]
	v_mfma_f32_16x16x32_bf16 v[110:113], v[136:139], v[182:185], v[110:113]
	v_mfma_f32_16x16x32_bf16 v[106:109], v[150:153], v[182:185], v[106:109]
	v_mfma_f32_16x16x32_bf16 v[94:97], v[136:139], v[190:193], v[94:97]
	v_mfma_f32_16x16x32_bf16 v[90:93], v[150:153], v[190:193], v[90:93]
	v_mfma_f32_16x16x32_bf16 v[78:81], v[136:139], v[198:201], v[78:81]
	v_mfma_f32_16x16x32_bf16 v[74:77], v[150:153], v[198:201], v[74:77]
	v_mfma_f32_16x16x32_bf16 v[126:129], v[146:149], v[178:181], v[126:129]
	v_mfma_f32_16x16x32_bf16 v[122:125], v[154:157], v[178:181], v[122:125]
	v_mfma_f32_16x16x32_bf16 v[110:113], v[146:149], v[186:189], v[110:113]
	v_mfma_f32_16x16x32_bf16 v[106:109], v[154:157], v[186:189], v[106:109]
	v_mfma_f32_16x16x32_bf16 v[94:97], v[146:149], v[194:197], v[94:97]
	v_mfma_f32_16x16x32_bf16 v[90:93], v[154:157], v[194:197], v[90:93]
	v_mfma_f32_16x16x32_bf16 v[78:81], v[146:149], v[202:205], v[78:81]
	v_mfma_f32_16x16x32_bf16 v[74:77], v[154:157], v[202:205], v[74:77]
	s_setprio 0
	s_setprio 1
	v_mfma_f32_16x16x32_bf16 v[118:121], v[158:161], v[174:177], v[118:121]
	v_mfma_f32_16x16x32_bf16 v[114:117], v[166:169], v[174:177], v[114:117]
	v_mfma_f32_16x16x32_bf16 v[102:105], v[158:161], v[182:185], v[102:105]
	v_mfma_f32_16x16x32_bf16 v[98:101], v[166:169], v[182:185], v[98:101]
	v_mfma_f32_16x16x32_bf16 v[86:89], v[158:161], v[190:193], v[86:89]
	v_mfma_f32_16x16x32_bf16 v[82:85], v[166:169], v[190:193], v[82:85]
	v_mfma_f32_16x16x32_bf16 v[70:73], v[158:161], v[198:201], v[70:73]
	v_mfma_f32_16x16x32_bf16 v[66:69], v[166:169], v[198:201], v[66:69]
	v_mfma_f32_16x16x32_bf16 v[118:121], v[162:165], v[178:181], v[118:121]
	v_mfma_f32_16x16x32_bf16 v[114:117], v[170:173], v[178:181], v[114:117]
	v_mfma_f32_16x16x32_bf16 v[102:105], v[162:165], v[186:189], v[102:105]
	v_mfma_f32_16x16x32_bf16 v[98:101], v[170:173], v[186:189], v[98:101]
	v_mfma_f32_16x16x32_bf16 v[86:89], v[162:165], v[194:197], v[86:89]
	v_mfma_f32_16x16x32_bf16 v[82:85], v[170:173], v[194:197], v[82:85]
	v_mfma_f32_16x16x32_bf16 v[70:73], v[162:165], v[202:205], v[70:73]
	v_mfma_f32_16x16x32_bf16 v[66:69], v[170:173], v[202:205], v[66:69]
	s_setprio 0
	s_barrier
; #define PG8_STAGE(bufoff, gbase, voff) do { _Pragma("unroll") for (int _i = 0; _i < 2; ++_i) \
;         __builtin_amdgcn_global_load_lds((const unsigned*)((const char*)(gbase) + (voff)[_i]), (LAS unsigned*)(lds + (bufoff) + ldsw + _i * 8192), 16, 0, 0); } while (0)
; #define PG8_LDA(dst, b, h) do { _Pragma("unroll") for (int m = 0; m < 4; ++m) _Pragma("unroll") for (int k = 0; k < 2; ++k) dst[m][k] = *(const LAS bf16x8*)(lds + PG8_SA(b, h) + aoff + m * 2048 + k * 1024); } while (0)
; #define PG8_MMA(ai, bj, At, Bt) do { __builtin_amdgcn_s_setprio(1); _Pragma("unroll") for (int m = 0; m < 4; ++m) _Pragma("unroll") for (int n = 0; n < 2; ++n) _Pragma("unroll") for (int k = 0; k < 2; ++k) \
;         acc[ai][bj][m][n] = __builtin_amdgcn_mfma_f32_16x16x32_bf16(Bt[n][k], At[m][k], acc[ai][bj][m][n], 0, 0, 0); __builtin_amdgcn_s_setprio(0); } while (0)
; #define PG8_WAIT_V(n) asm volatile("s_waitcnt vmcnt(" #n ")" ::: "memory")
; #define PG8_WAIT_L(n) asm volatile("s_waitcnt lgkmcnt(" #n ")" ::: "memory")
; #define PG8_BAR __builtin_amdgcn_s_barrier()
; #define PG8_SCHED __builtin_amdgcn_sched_barrier(0)
; template <class Epi, class Sched, bool ALIGN_EPI, bool LAST_FUSED = false, bool PERM = false, bool CARRY = false>
; __device__ __forceinline__ void gemm_phase(LAS unsigned char* lds, const int tid, const int K, const int lda, const int ldb, const Sched& S, const Epi& E) {
;     ...
;             PG8_LDA(At, 1, 1); PG8_STAGE(PG8_SB(1, 0), b3, voffB); PG8_STAGE(PG8_SB(1, 1), b3 + hstepB, voffB); PG8_STAGE(PG8_SA(1, 0), a3, voffA);
;             PG8_WAIT_V(8); PG8_WAIT_L(0); PG8_BAR; PG8_MMA(1, 0, At, B0); PG8_MMA(1, 1, At, B1); PG8_BAR; PG8_SCHED;
;         }
	s_add_i32 s28, s31, s51
	v_lshl_add_u64 v[206:207], v[206:207], 0, s[68:69]
	s_mov_b32 m0, s28
	ds_read_b128 v[174:177], v145 offset:49152
	ds_read_b128 v[178:181], v145 offset:50176
	ds_read_b128 v[182:185], v145 offset:51200
	ds_read_b128 v[186:189], v145 offset:52224
	ds_read_b128 v[190:193], v145 offset:53248
	ds_read_b128 v[194:197], v145 offset:54272
	ds_read_b128 v[198:201], v145 offset:55296
	ds_read_b128 v[202:205], v145 offset:56320
	global_load_lds_dwordx4 v[206:207], off
	s_add_i32 m0, s28, 0x2000
	s_add_u32 s4, s4, 0x80080
	v_lshl_add_u64 v[206:207], v[208:209], 0, s[68:69]
	s_addc_u32 s5, s5, 0
	s_add_i32 s28, s35, s51
	global_load_lds_dwordx4 v[206:207], off
	v_lshl_add_u64 v[206:207], s[4:5], 0, v[0:1]
	s_mov_b32 m0, s28
	s_nop 0
	global_load_lds_dwordx4 v[206:207], off
	v_lshl_add_u64 v[206:207], s[4:5], 0, v[130:131]
	s_add_i32 m0, s28, 0x2000
	s_nop 0
	global_load_lds_dwordx4 v[206:207], off
	v_lshl_add_u64 v[206:207], v[210:211], 0, s[68:69]
	s_mov_b32 m0, s57
	s_nop 0
	global_load_lds_dwordx4 v[206:207], off
	v_lshl_add_u64 v[206:207], v[212:213], 0, s[68:69]
	s_mov_b32 m0, s58
	s_nop 0
	global_load_lds_dwordx4 v[206:207], off
	s_waitcnt vmcnt(8)
	s_waitcnt lgkmcnt(0)
	s_barrier
	s_setprio 1
	s_waitcnt lgkmcnt(0)
	v_mfma_f32_16x16x32_bf16 v[62:65], v[136:139], v[174:177], v[62:65]
	v_mfma_f32_16x16x32_bf16 v[58:61], v[150:153], v[174:177], v[58:61]
	v_mfma_f32_16x16x32_bf16 v[46:49], v[136:139], v[182:185], v[46:49]
	v_mfma_f32_16x16x32_bf16 v[42:45], v[150:153], v[182:185], v[42:45]
	v_mfma_f32_16x16x32_bf16 v[30:33], v[136:139], v[190:193], v[30:33]
	v_mfma_f32_16x16x32_bf16 v[26:29], v[150:153], v[190:193], v[26:29]
	v_mfma_f32_16x16x32_bf16 v[14:17], v[136:139], v[198:201], v[14:17]
	v_mfma_f32_16x16x32_bf16 v[10:13], v[150:153], v[198:201], v[10:13]
	v_mfma_f32_16x16x32_bf16 v[62:65], v[146:149], v[178:181], v[62:65]
	v_mfma_f32_16x16x32_bf16 v[58:61], v[154:157], v[178:181], v[58:61]
	v_mfma_f32_16x16x32_bf16 v[46:49], v[146:149], v[186:189], v[46:49]
	v_mfma_f32_16x16x32_bf16 v[42:45], v[154:157], v[186:189], v[42:45]
	v_mfma_f32_16x16x32_bf16 v[30:33], v[146:149], v[194:197], v[30:33]
	v_mfma_f32_16x16x32_bf16 v[26:29], v[154:157], v[194:197], v[26:29]
	v_mfma_f32_16x16x32_bf16 v[14:17], v[146:149], v[202:205], v[14:17]
	v_mfma_f32_16x16x32_bf16 v[10:13], v[154:157], v[202:205], v[10:13]
	s_setprio 0
	s_setprio 1
	v_mfma_f32_16x16x32_bf16 v[54:57], v[158:161], v[174:177], v[54:57]
	v_mfma_f32_16x16x32_bf16 v[50:53], v[166:169], v[174:177], v[50:53]
	v_mfma_f32_16x16x32_bf16 v[38:41], v[158:161], v[182:185], v[38:41]
	v_mfma_f32_16x16x32_bf16 v[34:37], v[166:169], v[182:185], v[34:37]
	v_mfma_f32_16x16x32_bf16 v[22:25], v[158:161], v[190:193], v[22:25]
	v_mfma_f32_16x16x32_bf16 v[18:21], v[166:169], v[190:193], v[18:21]
	v_mfma_f32_16x16x32_bf16 v[6:9], v[158:161], v[198:201], v[6:9]
	v_mfma_f32_16x16x32_bf16 v[2:5], v[166:169], v[198:201], v[2:5]
	v_mfma_f32_16x16x32_bf16 v[54:57], v[162:165], v[178:181], v[54:57]
	v_mfma_f32_16x16x32_bf16 v[50:53], v[170:173], v[178:181], v[50:53]
	v_mfma_f32_16x16x32_bf16 v[38:41], v[162:165], v[186:189], v[38:41]
	v_mfma_f32_16x16x32_bf16 v[34:37], v[170:173], v[186:189], v[34:37]
	v_mfma_f32_16x16x32_bf16 v[22:25], v[162:165], v[194:197], v[22:25]
	v_mfma_f32_16x16x32_bf16 v[18:21], v[170:173], v[194:197], v[18:21]
	v_mfma_f32_16x16x32_bf16 v[6:9], v[162:165], v[202:205], v[6:9]
	v_mfma_f32_16x16x32_bf16 v[2:5], v[170:173], v[202:205], v[2:5]
	s_add_i32 s27, s27, 2
	s_add_u32 s2, s2, 0x100
	s_addc_u32 s3, s3, 0
	s_add_u32 s22, s22, 0x100
	s_addc_u32 s23, s23, 0
	s_cmp_gt_u32 s27, 29
	s_setprio 0
	s_barrier
	s_cbranch_scc0 .LBB0_279
	s_and_b64 vcc, exec, s[18:19]
	s_cbranch_vccz .LBB0_282
	s_barrier

; #define PG8_STAGE(bufoff, gbase, voff) do { _Pragma("unroll") for (int _i = 0; _i < 2; ++_i) \
;         __builtin_amdgcn_global_load_lds((const unsigned*)((const char*)(gbase) + (voff)[_i]), (LAS unsigned*)(lds + (bufoff) + ldsw + _i * 8192), 16, 0, 0); } while (0)
; #define PG8_LDA(dst, b, h) do { _Pragma("unroll") for (int m = 0; m < 4; ++m) _Pragma("unroll") for (int k = 0; k < 2; ++k) dst[m][k] = *(const LAS bf16x8*)(lds + PG8_SA(b, h) + aoff + m * 2048 + k * 1024); } while (0)
; #define PG8_LDB(dst, b, h) do { _Pragma("unroll") for (int n = 0; n < 2; ++n) _Pragma("unroll") for (int k = 0; k < 2; ++k) dst[n][k] = *(const LAS bf16x8*)(lds + PG8_SB(b, h) + boff + n * 2048 + k * 1024); } while (0)
; #define PG8_MMA(ai, bj, At, Bt) do { __builtin_amdgcn_s_setprio(1); _Pragma("unroll") for (int m = 0; m < 4; ++m) _Pragma("unroll") for (int n = 0; n < 2; ++n) _Pragma("unroll") for (int k = 0; k < 2; ++k) \
;         acc[ai][bj][m][n] = __builtin_amdgcn_mfma_f32_16x16x32_bf16(Bt[n][k], At[m][k], acc[ai][bj][m][n], 0, 0, 0); __builtin_amdgcn_s_setprio(0); } while (0)
; #define PG8_WAIT_V(n) asm volatile("s_waitcnt vmcnt(" #n ")" ::: "memory")
; #define PG8_WAIT_L(n) asm volatile("s_waitcnt lgkmcnt(" #n ")" ::: "memory")
; template <class Epi, class Sched, bool ALIGN_EPI, bool LAST_FUSED = false, bool PERM = false, bool CARRY = false>
; __device__ __forceinline__ void gemm_phase(LAS unsigned char* lds, const int tid, const int K, const int lda, const int ldb, const Sched& S, const Epi& E) {
;     ...
;         for (int t = 0; t < nt; t += 2) {
;             const bool last = (t == nt - 2);
;             const char* a1 = cA + (size_t)(t + 1) * kstep;
;             const char* a2 = last ? nA : cA + (size_t)(t + 2) * kstep; const char* b2 = last ? nB : cB + (size_t)(t + 2) * kstep;
;             const char* a3 = a2 + kstep; const char* b3 = b2 + kstep;
;             PG8_LDB(B0, 0, 0); PG8_LDB(B1, 0, 1); PG8_SCHED; PG8_LDA(At, 0, 0); PG8_STAGE(PG8_SA(1, 1), a1 + hstepA, voffA);
;             PG8_WAIT_V(8); PG8_WAIT_L(0); PG8_BAR; PG8_MMA(0, 0, At, B0); PG8_MMA(0, 1, At, B1); PG8_BAR; PG8_SCHED;
;             PG8_LDA(At, 0, 1); PG8_STAGE(PG8_SB(0, 0), b2, voffB); PG8_STAGE(PG8_SB(0, 1), b2 + hstepB, voffB); PG8_STAGE(PG8_SA(0, 0), a2, voffA);
;             PG8_WAIT_V(8); PG8_WAIT_L(0); PG8_BAR; PG8_MMA(1, 0, At, B0); PG8_MMA(1, 1, At, B1); PG8_BAR; PG8_SCHED;
.LBB0_512:
	s_add_u32 s28, s4, 0xfff80080
	s_addc_u32 s29, s5, -1
	s_add_i32 s31, 0, 0x10000
	s_cmp_eq_u32 s24, 28
	s_cselect_b32 s41, s87, s29
	s_cselect_b32 s40, s86, s28
	v_add_u32_e32 v148, s31, v160
	s_cselect_b32 s37, s39, s23
	s_cselect_b32 s36, s38, s22
	s_add_i32 s35, 0, 0x14000
	ds_read_b128 v[140:143], v148
	ds_read_b128 v[144:147], v148 offset:1024
	ds_read_b128 v[162:165], v148 offset:2048
	ds_read_b128 v[166:169], v148 offset:3072
	v_add_u32_e32 v148, s35, v160
	ds_read_b128 v[170:173], v148
	ds_read_b128 v[174:177], v148 offset:1024
	ds_read_b128 v[178:181], v148 offset:2048
	ds_read_b128 v[182:185], v148 offset:3072
	v_lshl_add_u64 v[148:149], s[4:5], 0, v[136:137]
	s_add_i32 m0, s54, 0xc000
	ds_read_b128 v[186:189], v161
	ds_read_b128 v[190:193], v161 offset:1024
	ds_read_b128 v[194:197], v161 offset:2048
	ds_read_b128 v[198:201], v161 offset:3072
	ds_read_b128 v[202:205], v161 offset:4096
	ds_read_b128 v[206:209], v161 offset:5120
	ds_read_b128 v[210:213], v161 offset:6144
	ds_read_b128 v[214:217], v161 offset:7168
	global_load_lds_dwordx4 v[148:149], off
	v_lshl_add_u64 v[148:149], s[4:5], 0, v[138:139]
	s_add_i32 m0, s54, 0xe000
	s_nop 0
	global_load_lds_dwordx4 v[148:149], off
	s_waitcnt vmcnt(8)
	s_waitcnt lgkmcnt(0)
	s_barrier
	s_setprio 1
	s_waitcnt lgkmcnt(0)
	v_mfma_f32_16x16x32_bf16 v[126:129], v[140:143], v[186:189], v[126:129]
	v_mfma_f32_16x16x32_bf16 v[122:125], v[162:165], v[186:189], v[122:125]
	v_mfma_f32_16x16x32_bf16 v[110:113], v[140:143], v[194:197], v[110:113]
	v_mfma_f32_16x16x32_bf16 v[106:109], v[162:165], v[194:197], v[106:109]
	v_mfma_f32_16x16x32_bf16 v[94:97], v[140:143], v[202:205], v[94:97]
	v_mfma_f32_16x16x32_bf16 v[90:93], v[162:165], v[202:205], v[90:93]
	v_mfma_f32_16x16x32_bf16 v[78:81], v[140:143], v[210:213], v[78:81]
	v_mfma_f32_16x16x32_bf16 v[74:77], v[162:165], v[210:213], v[74:77]
	v_mfma_f32_16x16x32_bf16 v[126:129], v[144:147], v[190:193], v[126:129]
	v_mfma_f32_16x16x32_bf16 v[122:125], v[166:169], v[190:193], v[122:125]
	v_mfma_f32_16x16x32_bf16 v[110:113], v[144:147], v[198:201], v[110:113]
	v_mfma_f32_16x16x32_bf16 v[106:109], v[166:169], v[198:201], v[106:109]
	v_mfma_f32_16x16x32_bf16 v[94:97], v[144:147], v[206:209], v[94:97]
	v_mfma_f32_16x16x32_bf16 v[90:93], v[166:169], v[206:209], v[90:93]
	v_mfma_f32_16x16x32_bf16 v[78:81], v[144:147], v[214:217], v[78:81]
	v_mfma_f32_16x16x32_bf16 v[74:77], v[166:169], v[214:217], v[74:77]
	s_setprio 0
	s_setprio 1
	v_mfma_f32_16x16x32_bf16 v[118:121], v[170:173], v[186:189], v[118:121]
	v_mfma_f32_16x16x32_bf16 v[114:117], v[178:181], v[186:189], v[114:117]
	v_mfma_f32_16x16x32_bf16 v[102:105], v[170:173], v[194:197], v[102:105]
	v_mfma_f32_16x16x32_bf16 v[98:101], v[178:181], v[194:197], v[98:101]
	v_mfma_f32_16x16x32_bf16 v[86:89], v[170:173], v[202:205], v[86:89]
	v_mfma_f32_16x16x32_bf16 v[82:85], v[178:181], v[202:205], v[82:85]
	v_mfma_f32_16x16x32_bf16 v[70:73], v[170:173], v[210:213], v[70:73]
	v_mfma_f32_16x16x32_bf16 v[66:69], v[178:181], v[210:213], v[66:69]
	v_mfma_f32_16x16x32_bf16 v[118:121], v[174:177], v[190:193], v[118:121]
	v_mfma_f32_16x16x32_bf16 v[114:117], v[182:185], v[190:193], v[114:117]
	v_mfma_f32_16x16x32_bf16 v[102:105], v[174:177], v[198:201], v[102:105]
	v_mfma_f32_16x16x32_bf16 v[98:101], v[182:185], v[198:201], v[98:101]
	v_mfma_f32_16x16x32_bf16 v[86:89], v[174:177], v[206:209], v[86:89]
	v_mfma_f32_16x16x32_bf16 v[82:85], v[182:185], v[206:209], v[82:85]
	v_mfma_f32_16x16x32_bf16 v[70:73], v[174:177], v[214:217], v[70:73]
	v_mfma_f32_16x16x32_bf16 v[66:69], v[182:185], v[214:217], v[66:69]
	s_setprio 0
	s_barrier
	s_add_i32 s28, s31, s52
	v_lshl_add_u64 v[148:149], s[36:37], 0, v[0:1]
	s_mov_b32 m0, s28
	ds_read_b128 v[186:189], v161 offset:16384
	ds_read_b128 v[190:193], v161 offset:17408
	ds_read_b128 v[194:197], v161 offset:18432
	ds_read_b128 v[198:201], v161 offset:19456
	ds_read_b128 v[202:205], v161 offset:20480
	ds_read_b128 v[206:209], v161 offset:21504
	ds_read_b128 v[210:213], v161 offset:22528
	ds_read_b128 v[214:217], v161 offset:23552
	global_load_lds_dwordx4 v[148:149], off
	s_add_i32 m0, s28, 0x2000
	s_add_u32 s28, s36, 0x80000
	v_lshl_add_u64 v[152:153], s[36:37], 0, v[130:131]
	s_addc_u32 s29, s37, 0
	s_add_i32 s31, s35, s52
	global_load_lds_dwordx4 v[152:153], off
	v_lshl_add_u64 v[156:157], s[28:29], 0, v[0:1]
	s_mov_b32 m0, s31
	v_lshl_add_u64 v[218:219], s[40:41], 0, v[132:133]
	global_load_lds_dwordx4 v[156:157], off
	v_lshl_add_u64 v[156:157], s[28:29], 0, v[130:131]
	s_add_i32 m0, s31, 0x2000
	s_nop 0
	global_load_lds_dwordx4 v[156:157], off
	v_lshl_add_u64 v[156:157], s[40:41], 0, v[134:135]
	s_mov_b32 m0, s54
	s_nop 0
	global_load_lds_dwordx4 v[156:157], off
	s_mov_b32 m0, s55
	s_nop 0
	global_load_lds_dwordx4 v[218:219], off
	s_waitcnt vmcnt(8)
	s_waitcnt lgkmcnt(0)
	s_barrier
; #define PG8_STAGE(bufoff, gbase, voff) do { _Pragma("unroll") for (int _i = 0; _i < 2; ++_i) \
;         __builtin_amdgcn_global_load_lds((const unsigned*)((const char*)(gbase) + (voff)[_i]), (LAS unsigned*)(lds + (bufoff) + ldsw + _i * 8192), 16, 0, 0); } while (0)
; #define PG8_LDA(dst, b, h) do { _Pragma("unroll") for (int m = 0; m < 4; ++m) _Pragma("unroll") for (int k = 0; k < 2; ++k) dst[m][k] = *(const LAS bf16x8*)(lds + PG8_SA(b, h) + aoff + m * 2048 + k * 1024); } while (0)
; #define PG8_LDB(dst, b, h) do { _Pragma("unroll") for (int n = 0; n < 2; ++n) _Pragma("unroll") for (int k = 0; k < 2; ++k) dst[n][k] = *(const LAS bf16x8*)(lds + PG8_SB(b, h) + boff + n * 2048 + k * 1024); } while (0)
; #define PG8_MMA(ai, bj, At, Bt) do { __builtin_amdgcn_s_setprio(1); _Pragma("unroll") for (int m = 0; m < 4; ++m) _Pragma("unroll") for (int n = 0; n < 2; ++n) _Pragma("unroll") for (int k = 0; k < 2; ++k) \
;         acc[ai][bj][m][n] = __builtin_amdgcn_mfma_f32_16x16x32_bf16(Bt[n][k], At[m][k], acc[ai][bj][m][n], 0, 0, 0); __builtin_amdgcn_s_setprio(0); } while (0)
; #define PG8_WAIT_V(n) asm volatile("s_waitcnt vmcnt(" #n ")" ::: "memory")
; #define PG8_WAIT_L(n) asm volatile("s_waitcnt lgkmcnt(" #n ")" ::: "memory")
; #define PG8_BAR __builtin_amdgcn_s_barrier()
; #define PG8_SCHED __builtin_amdgcn_sched_barrier(0)
; template <class Epi, class Sched, bool ALIGN_EPI, bool LAST_FUSED = false, bool PERM = false, bool CARRY = false>
; __device__ __forceinline__ void gemm_phase(LAS unsigned char* lds, const int tid, const int K, const int lda, const int ldb, const Sched& S, const Epi& E) {
;     ...
;             PG8_WAIT_V(8); PG8_WAIT_L(0); PG8_BAR; PG8_MMA(1, 0, At, B0); PG8_MMA(1, 1, At, B1); PG8_BAR; PG8_SCHED;
;             PG8_LDB(B0, 1, 0); PG8_LDB(B1, 1, 1); PG8_SCHED; PG8_LDA(At, 1, 0); PG8_STAGE(PG8_SA(0, 1), a2 + hstepA, voffA);
;             PG8_WAIT_V(8); PG8_WAIT_L(0); PG8_BAR; PG8_MMA(0, 0, At, B0); PG8_MMA(0, 1, At, B1); PG8_BAR; PG8_SCHED;
	s_setprio 1
	s_waitcnt lgkmcnt(0)
	v_mfma_f32_16x16x32_bf16 v[62:65], v[140:143], v[186:189], v[62:65]
	v_mfma_f32_16x16x32_bf16 v[58:61], v[162:165], v[186:189], v[58:61]
	v_mfma_f32_16x16x32_bf16 v[46:49], v[140:143], v[194:197], v[46:49]
	v_mfma_f32_16x16x32_bf16 v[42:45], v[162:165], v[194:197], v[42:45]
	v_mfma_f32_16x16x32_bf16 v[30:33], v[140:143], v[202:205], v[30:33]
	v_mfma_f32_16x16x32_bf16 v[26:29], v[162:165], v[202:205], v[26:29]
	v_mfma_f32_16x16x32_bf16 v[14:17], v[140:143], v[210:213], v[14:17]
	v_mfma_f32_16x16x32_bf16 v[10:13], v[162:165], v[210:213], v[10:13]
	v_mfma_f32_16x16x32_bf16 v[62:65], v[144:147], v[190:193], v[62:65]
	v_mfma_f32_16x16x32_bf16 v[58:61], v[166:169], v[190:193], v[58:61]
	v_mfma_f32_16x16x32_bf16 v[46:49], v[144:147], v[198:201], v[46:49]
	v_mfma_f32_16x16x32_bf16 v[42:45], v[166:169], v[198:201], v[42:45]
	v_mfma_f32_16x16x32_bf16 v[30:33], v[144:147], v[206:209], v[30:33]
	v_mfma_f32_16x16x32_bf16 v[26:29], v[166:169], v[206:209], v[26:29]
	v_mfma_f32_16x16x32_bf16 v[14:17], v[144:147], v[214:217], v[14:17]
	v_mfma_f32_16x16x32_bf16 v[10:13], v[166:169], v[214:217], v[10:13]
	s_setprio 0
	s_setprio 1
	v_mfma_f32_16x16x32_bf16 v[54:57], v[170:173], v[186:189], v[54:57]
	v_mfma_f32_16x16x32_bf16 v[50:53], v[178:181], v[186:189], v[50:53]
	v_mfma_f32_16x16x32_bf16 v[38:41], v[170:173], v[194:197], v[38:41]
	v_mfma_f32_16x16x32_bf16 v[34:37], v[178:181], v[194:197], v[34:37]
	v_mfma_f32_16x16x32_bf16 v[22:25], v[170:173], v[202:205], v[22:25]
	v_mfma_f32_16x16x32_bf16 v[18:21], v[178:181], v[202:205], v[18:21]
	v_mfma_f32_16x16x32_bf16 v[6:9], v[170:173], v[210:213], v[6:9]
	v_mfma_f32_16x16x32_bf16 v[2:5], v[178:181], v[210:213], v[2:5]
	v_mfma_f32_16x16x32_bf16 v[54:57], v[174:177], v[190:193], v[54:57]
	v_mfma_f32_16x16x32_bf16 v[50:53], v[182:185], v[190:193], v[50:53]
	v_mfma_f32_16x16x32_bf16 v[38:41], v[174:177], v[198:201], v[38:41]
	v_mfma_f32_16x16x32_bf16 v[34:37], v[182:185], v[198:201], v[34:37]
	v_mfma_f32_16x16x32_bf16 v[22:25], v[174:177], v[206:209], v[22:25]
	v_mfma_f32_16x16x32_bf16 v[18:21], v[182:185], v[206:209], v[18:21]
	v_mfma_f32_16x16x32_bf16 v[6:9], v[174:177], v[214:217], v[6:9]
	v_mfma_f32_16x16x32_bf16 v[2:5], v[182:185], v[214:217], v[2:5]
	s_setprio 0
	s_barrier
	s_add_i32 s31, 0, 0x18000
	v_add_u32_e32 v150, s31, v160
	s_add_i32 s35, 0, 0x1c000
	ds_read_b128 v[140:143], v150
	ds_read_b128 v[144:147], v150 offset:1024
	ds_read_b128 v[162:165], v150 offset:2048
	ds_read_b128 v[166:169], v150 offset:3072
	v_add_u32_e32 v150, s35, v160
	ds_read_b128 v[170:173], v150
	ds_read_b128 v[174:177], v150 offset:1024
	ds_read_b128 v[178:181], v150 offset:2048
	ds_read_b128 v[182:185], v150 offset:3072
	s_add_u32 s28, s40, 0x80000
	s_addc_u32 s29, s41, 0
	s_mov_b32 m0, s56
	v_lshl_add_u64 v[220:221], s[28:29], 0, v[134:135]
	ds_read_b128 v[186:189], v161 offset:32768
	ds_read_b128 v[190:193], v161 offset:33792
	ds_read_b128 v[194:197], v161 offset:34816
	ds_read_b128 v[198:201], v161 offset:35840
	ds_read_b128 v[202:205], v161 offset:36864
	ds_read_b128 v[206:209], v161 offset:37888
	ds_read_b128 v[210:213], v161 offset:38912
	ds_read_b128 v[214:217], v161 offset:39936
	global_load_lds_dwordx4 v[220:221], off
	v_lshl_add_u64 v[220:221], s[28:29], 0, v[132:133]
	s_mov_b32 m0, s57
	s_nop 0
	global_load_lds_dwordx4 v[220:221], off
	s_waitcnt vmcnt(8)
	s_waitcnt lgkmcnt(0)
	s_barrier
	s_setprio 1
	s_waitcnt lgkmcnt(0)
	v_mfma_f32_16x16x32_bf16 v[126:129], v[140:143], v[186:189], v[126:129]
	v_mfma_f32_16x16x32_bf16 v[122:125], v[162:165], v[186:189], v[122:125]
	v_mfma_f32_16x16x32_bf16 v[110:113], v[140:143], v[194:197], v[110:113]
	v_mfma_f32_16x16x32_bf16 v[106:109], v[162:165], v[194:197], v[106:109]
	v_mfma_f32_16x16x32_bf16 v[94:97], v[140:143], v[202:205], v[94:97]
	v_mfma_f32_16x16x32_bf16 v[90:93], v[162:165], v[202:205], v[90:93]
	v_mfma_f32_16x16x32_bf16 v[78:81], v[140:143], v[210:213], v[78:81]
	v_mfma_f32_16x16x32_bf16 v[74:77], v[162:165], v[210:213], v[74:77]
	v_mfma_f32_16x16x32_bf16 v[126:129], v[144:147], v[190:193], v[126:129]
	v_mfma_f32_16x16x32_bf16 v[122:125], v[166:169], v[190:193], v[122:125]
	v_mfma_f32_16x16x32_bf16 v[110:113], v[144:147], v[198:201], v[110:113]
	v_mfma_f32_16x16x32_bf16 v[106:109], v[166:169], v[198:201], v[106:109]
	v_mfma_f32_16x16x32_bf16 v[94:97], v[144:147], v[206:209], v[94:97]
	v_mfma_f32_16x16x32_bf16 v[90:93], v[166:169], v[206:209], v[90:93]
	v_mfma_f32_16x16x32_bf16 v[78:81], v[144:147], v[214:217], v[78:81]
	v_mfma_f32_16x16x32_bf16 v[74:77], v[166:169], v[214:217], v[74:77]
	s_setprio 0
	s_setprio 1
	v_mfma_f32_16x16x32_bf16 v[118:121], v[170:173], v[186:189], v[118:121]
	v_mfma_f32_16x16x32_bf16 v[114:117], v[178:181], v[186:189], v[114:117]
	v_mfma_f32_16x16x32_bf16 v[102:105], v[170:173], v[194:197], v[102:105]
	v_mfma_f32_16x16x32_bf16 v[98:101], v[178:181], v[194:197], v[98:101]
	v_mfma_f32_16x16x32_bf16 v[86:89], v[170:173], v[202:205], v[86:89]
	v_mfma_f32_16x16x32_bf16 v[82:85], v[178:181], v[202:205], v[82:85]
	v_mfma_f32_16x16x32_bf16 v[70:73], v[170:173], v[210:213], v[70:73]
	v_mfma_f32_16x16x32_bf16 v[66:69], v[178:181], v[210:213], v[66:69]
	v_mfma_f32_16x16x32_bf16 v[118:121], v[174:177], v[190:193], v[118:121]
	v_mfma_f32_16x16x32_bf16 v[114:117], v[182:185], v[190:193], v[114:117]
	v_mfma_f32_16x16x32_bf16 v[102:105], v[174:177], v[198:201], v[102:105]
	v_mfma_f32_16x16x32_bf16 v[98:101], v[182:185], v[198:201], v[98:101]
	v_mfma_f32_16x16x32_bf16 v[86:89], v[174:177], v[206:209], v[86:89]
	v_mfma_f32_16x16x32_bf16 v[82:85], v[182:185], v[206:209], v[82:85]
	v_mfma_f32_16x16x32_bf16 v[70:73], v[174:177], v[214:217], v[70:73]
	v_mfma_f32_16x16x32_bf16 v[66:69], v[182:185], v[214:217], v[66:69]
	s_setprio 0
	s_barrier
; #define PG8_STAGE(bufoff, gbase, voff) do { _Pragma("unroll") for (int _i = 0; _i < 2; ++_i) \
;         __builtin_amdgcn_global_load_lds((const unsigned*)((const char*)(gbase) + (voff)[_i]), (LAS unsigned*)(lds + (bufoff) + ldsw + _i * 8192), 16, 0, 0); } while (0)
; #define PG8_LDA(dst, b, h) do { _Pragma("unroll") for (int m = 0; m < 4; ++m) _Pragma("unroll") for (int k = 0; k < 2; ++k) dst[m][k] = *(const LAS bf16x8*)(lds + PG8_SA(b, h) + aoff + m * 2048 + k * 1024); } while (0)
; #define PG8_MMA(ai, bj, At, Bt) do { __builtin_amdgcn_s_setprio(1); _Pragma("unroll") for (int m = 0; m < 4; ++m) _Pragma("unroll") for (int n = 0; n < 2; ++n) _Pragma("unroll") for (int k = 0; k < 2; ++k) \
;         acc[ai][bj][m][n] = __builtin_amdgcn_mfma_f32_16x16x32_bf16(Bt[n][k], At[m][k], acc[ai][bj][m][n], 0, 0, 0); __builtin_amdgcn_s_setprio(0); } while (0)
; #define PG8_WAIT_V(n) asm volatile("s_waitcnt vmcnt(" #n ")" ::: "memory")
; #define PG8_WAIT_L(n) asm volatile("s_waitcnt lgkmcnt(" #n ")" ::: "memory")
; #define PG8_BAR __builtin_amdgcn_s_barrier()
; #define PG8_SCHED __builtin_amdgcn_sched_barrier(0)
; template <class Epi, class Sched, bool ALIGN_EPI, bool LAST_FUSED = false, bool PERM = false, bool CARRY = false>
; __device__ __forceinline__ void gemm_phase(LAS unsigned char* lds, const int tid, const int K, const int lda, const int ldb, const Sched& S, const Epi& E) {
;     ...
;             PG8_LDA(At, 1, 1); PG8_STAGE(PG8_SB(1, 0), b3, voffB); PG8_STAGE(PG8_SB(1, 1), b3 + hstepB, voffB); PG8_STAGE(PG8_SA(1, 0), a3, voffA);
;             PG8_WAIT_V(8); PG8_WAIT_L(0); PG8_BAR; PG8_MMA(1, 0, At, B0); PG8_MMA(1, 1, At, B1); PG8_BAR; PG8_SCHED;
;         }
	s_add_i32 s28, s31, s52
	v_lshl_add_u64 v[148:149], v[148:149], 0, s[68:69]
	s_mov_b32 m0, s28
	ds_read_b128 v[186:189], v161 offset:49152
	ds_read_b128 v[190:193], v161 offset:50176
	ds_read_b128 v[194:197], v161 offset:51200
	ds_read_b128 v[198:201], v161 offset:52224
	ds_read_b128 v[202:205], v161 offset:53248
	ds_read_b128 v[206:209], v161 offset:54272
	ds_read_b128 v[210:213], v161 offset:55296
	ds_read_b128 v[214:217], v161 offset:56320
	global_load_lds_dwordx4 v[148:149], off
	s_add_i32 m0, s28, 0x2000
	s_add_u32 s28, s36, 0x80080
	v_lshl_add_u64 v[148:149], v[152:153], 0, s[68:69]
	s_addc_u32 s29, s37, 0
	s_add_i32 s31, s35, s52
	global_load_lds_dwordx4 v[148:149], off
	v_lshl_add_u64 v[148:149], s[28:29], 0, v[0:1]
	s_mov_b32 m0, s31
	s_nop 0
	global_load_lds_dwordx4 v[148:149], off
	v_lshl_add_u64 v[148:149], s[28:29], 0, v[130:131]
	s_add_i32 m0, s31, 0x2000
	s_nop 0
	global_load_lds_dwordx4 v[148:149], off
	v_lshl_add_u64 v[148:149], v[156:157], 0, s[68:69]
	s_mov_b32 m0, s59
	s_nop 0
	global_load_lds_dwordx4 v[148:149], off
	v_lshl_add_u64 v[148:149], v[218:219], 0, s[68:69]
	s_mov_b32 m0, s60
	s_nop 0
	global_load_lds_dwordx4 v[148:149], off
	s_waitcnt vmcnt(8)
	s_waitcnt lgkmcnt(0)
	s_barrier
	s_setprio 1
	s_waitcnt lgkmcnt(0)
	v_mfma_f32_16x16x32_bf16 v[62:65], v[140:143], v[186:189], v[62:65]
	v_mfma_f32_16x16x32_bf16 v[58:61], v[162:165], v[186:189], v[58:61]
	v_mfma_f32_16x16x32_bf16 v[46:49], v[140:143], v[194:197], v[46:49]
	v_mfma_f32_16x16x32_bf16 v[42:45], v[162:165], v[194:197], v[42:45]
	v_mfma_f32_16x16x32_bf16 v[30:33], v[140:143], v[202:205], v[30:33]
	v_mfma_f32_16x16x32_bf16 v[26:29], v[162:165], v[202:205], v[26:29]
	v_mfma_f32_16x16x32_bf16 v[14:17], v[140:143], v[210:213], v[14:17]
	v_mfma_f32_16x16x32_bf16 v[10:13], v[162:165], v[210:213], v[10:13]
	v_mfma_f32_16x16x32_bf16 v[62:65], v[144:147], v[190:193], v[62:65]
	v_mfma_f32_16x16x32_bf16 v[58:61], v[166:169], v[190:193], v[58:61]
	v_mfma_f32_16x16x32_bf16 v[46:49], v[144:147], v[198:201], v[46:49]
	v_mfma_f32_16x16x32_bf16 v[42:45], v[166:169], v[198:201], v[42:45]
	v_mfma_f32_16x16x32_bf16 v[30:33], v[144:147], v[206:209], v[30:33]
	v_mfma_f32_16x16x32_bf16 v[26:29], v[166:169], v[206:209], v[26:29]
	v_mfma_f32_16x16x32_bf16 v[14:17], v[144:147], v[214:217], v[14:17]
	v_mfma_f32_16x16x32_bf16 v[10:13], v[166:169], v[214:217], v[10:13]
	s_setprio 0
	s_setprio 1
	v_mfma_f32_16x16x32_bf16 v[54:57], v[170:173], v[186:189], v[54:57]
	v_mfma_f32_16x16x32_bf16 v[50:53], v[178:181], v[186:189], v[50:53]
	v_mfma_f32_16x16x32_bf16 v[38:41], v[170:173], v[194:197], v[38:41]
	v_mfma_f32_16x16x32_bf16 v[34:37], v[178:181], v[194:197], v[34:37]
	v_mfma_f32_16x16x32_bf16 v[22:25], v[170:173], v[202:205], v[22:25]
	v_mfma_f32_16x16x32_bf16 v[18:21], v[178:181], v[202:205], v[18:21]
	v_mfma_f32_16x16x32_bf16 v[6:9], v[170:173], v[210:213], v[6:9]
	v_mfma_f32_16x16x32_bf16 v[2:5], v[178:181], v[210:213], v[2:5]
	v_mfma_f32_16x16x32_bf16 v[54:57], v[174:177], v[190:193], v[54:57]
	v_mfma_f32_16x16x32_bf16 v[50:53], v[182:185], v[190:193], v[50:53]
	v_mfma_f32_16x16x32_bf16 v[38:41], v[174:177], v[198:201], v[38:41]
	v_mfma_f32_16x16x32_bf16 v[34:37], v[182:185], v[198:201], v[34:37]
	v_mfma_f32_16x16x32_bf16 v[22:25], v[174:177], v[206:209], v[22:25]
	v_mfma_f32_16x16x32_bf16 v[18:21], v[182:185], v[206:209], v[18:21]
	v_mfma_f32_16x16x32_bf16 v[6:9], v[174:177], v[214:217], v[6:9]
	v_mfma_f32_16x16x32_bf16 v[2:5], v[182:185], v[214:217], v[2:5]
	s_add_i32 s24, s24, 2
	s_add_u32 s4, s4, 0x100
	s_addc_u32 s5, s5, 0
	s_add_u32 s22, s22, 0x100
	s_addc_u32 s23, s23, 0
	s_cmp_gt_u32 s24, 29
	s_setprio 0
	s_barrier
	s_cbranch_scc0 .LBB0_512
	s_and_b64 vcc, exec, s[78:79]
	s_cbranch_vccz .LBB0_515
	s_barrier

; #define PG8_STAGE(bufoff, gbase, voff) do { _Pragma("unroll") for (int _i = 0; _i < 2; ++_i) \
;         __builtin_amdgcn_global_load_lds((const unsigned*)((const char*)(gbase) + (voff)[_i]), (LAS unsigned*)(lds + (bufoff) + ldsw + _i * 8192), 16, 0, 0); } while (0)
; #define PG8_LDA(dst, b, h) do { _Pragma("unroll") for (int m = 0; m < 4; ++m) _Pragma("unroll") for (int k = 0; k < 2; ++k) dst[m][k] = *(const LAS bf16x8*)(lds + PG8_SA(b, h) + aoff + m * 2048 + k * 1024); } while (0)
; #define PG8_LDB(dst, b, h) do { _Pragma("unroll") for (int n = 0; n < 2; ++n) _Pragma("unroll") for (int k = 0; k < 2; ++k) dst[n][k] = *(const LAS bf16x8*)(lds + PG8_SB(b, h) + boff + n * 2048 + k * 1024); } while (0)
; #define PG8_MMA(ai, bj, At, Bt) do { __builtin_amdgcn_s_setprio(1); _Pragma("unroll") for (int m = 0; m < 4; ++m) _Pragma("unroll") for (int n = 0; n < 2; ++n) _Pragma("unroll") for (int k = 0; k < 2; ++k) \
;         acc[ai][bj][m][n] = __builtin_amdgcn_mfma_f32_16x16x32_bf16(Bt[n][k], At[m][k], acc[ai][bj][m][n], 0, 0, 0); __builtin_amdgcn_s_setprio(0); } while (0)
; #define PG8_WAIT_V(n) asm volatile("s_waitcnt vmcnt(" #n ")" ::: "memory")
; #define PG8_WAIT_L(n) asm volatile("s_waitcnt lgkmcnt(" #n ")" ::: "memory")
; template <class Epi, class Sched, bool ALIGN_EPI, bool LAST_FUSED = false, bool PERM = false, bool CARRY = false>
; __device__ __forceinline__ void gemm_phase(LAS unsigned char* lds, const int tid, const int K, const int lda, const int ldb, const Sched& S, const Epi& E) {
;     ...
;         for (int t = 0; t < nt; t += 2) {
;             const bool last = (t == nt - 2);
;             const char* a1 = cA + (size_t)(t + 1) * kstep;
;             const char* a2 = last ? nA : cA + (size_t)(t + 2) * kstep; const char* b2 = last ? nB : cB + (size_t)(t + 2) * kstep;
;             const char* a3 = a2 + kstep; const char* b3 = b2 + kstep;
;             PG8_LDB(B0, 0, 0); PG8_LDB(B1, 0, 1); PG8_SCHED; PG8_LDA(At, 0, 0); PG8_STAGE(PG8_SA(1, 1), a1 + hstepA, voffA);
;             PG8_WAIT_V(8); PG8_WAIT_L(0); PG8_BAR; PG8_MMA(0, 0, At, B0); PG8_MMA(0, 1, At, B1); PG8_BAR; PG8_SCHED;
;             PG8_LDA(At, 0, 1); PG8_STAGE(PG8_SB(0, 0), b2, voffB); PG8_STAGE(PG8_SB(0, 1), b2 + hstepB, voffB); PG8_STAGE(PG8_SA(0, 0), a2, voffA);
;             PG8_WAIT_V(8); PG8_WAIT_L(0); PG8_BAR; PG8_MMA(1, 0, At, B0); PG8_MMA(1, 1, At, B1); PG8_BAR; PG8_SCHED;
.LBB0_705:
	s_add_u32 s30, s26, 0x100
	s_addc_u32 s31, s27, 0
	s_add_i32 s54, 0, 0x10000
	s_cmp_eq_u32 s53, 8
	s_cselect_b32 s39, s15, s31
	s_cselect_b32 s38, s14, s30
	v_add_u32_e32 v140, s54, v144
	s_cselect_b32 s37, s17, s52
	s_cselect_b32 s36, s16, s13
	s_add_i32 s55, 0, 0x14000
	ds_read_b128 v[146:149], v140
	ds_read_b128 v[150:153], v140 offset:1024
	ds_read_b128 v[154:157], v140 offset:2048
	ds_read_b128 v[158:161], v140 offset:3072
	v_add_u32_e32 v140, s55, v144
	ds_read_b128 v[162:165], v140
	ds_read_b128 v[166:169], v140 offset:1024
	ds_read_b128 v[170:173], v140 offset:2048
	ds_read_b128 v[174:177], v140 offset:3072
	v_lshl_add_u64 v[140:141], s[26:27], 0, v[136:137]
	s_add_i32 m0, s19, 0xc000
	ds_read_b128 v[178:181], v145
	ds_read_b128 v[182:185], v145 offset:1024
	ds_read_b128 v[186:189], v145 offset:2048
	ds_read_b128 v[190:193], v145 offset:3072
	ds_read_b128 v[194:197], v145 offset:4096
	ds_read_b128 v[198:201], v145 offset:5120
	ds_read_b128 v[202:205], v145 offset:6144
	ds_read_b128 v[206:209], v145 offset:7168
	global_load_lds_dwordx4 v[140:141], off
	v_lshl_add_u64 v[140:141], s[26:27], 0, v[138:139]
	s_add_i32 m0, s19, 0xe000
	s_nop 0
	global_load_lds_dwordx4 v[140:141], off
	s_waitcnt vmcnt(8)
	s_waitcnt lgkmcnt(0)
	s_barrier
	s_setprio 1
	s_waitcnt lgkmcnt(0)
	v_mfma_f32_16x16x32_bf16 v[126:129], v[146:149], v[178:181], v[126:129]
	v_mfma_f32_16x16x32_bf16 v[122:125], v[154:157], v[178:181], v[122:125]
	v_mfma_f32_16x16x32_bf16 v[118:121], v[146:149], v[186:189], v[118:121]
	v_mfma_f32_16x16x32_bf16 v[110:113], v[154:157], v[186:189], v[110:113]
	v_mfma_f32_16x16x32_bf16 v[102:105], v[146:149], v[194:197], v[102:105]
	v_mfma_f32_16x16x32_bf16 v[94:97], v[154:157], v[194:197], v[94:97]
	v_mfma_f32_16x16x32_bf16 v[86:89], v[146:149], v[202:205], v[86:89]
	v_mfma_f32_16x16x32_bf16 v[78:81], v[154:157], v[202:205], v[78:81]
	v_mfma_f32_16x16x32_bf16 v[126:129], v[150:153], v[182:185], v[126:129]
	v_mfma_f32_16x16x32_bf16 v[122:125], v[158:161], v[182:185], v[122:125]
	v_mfma_f32_16x16x32_bf16 v[118:121], v[150:153], v[190:193], v[118:121]
	v_mfma_f32_16x16x32_bf16 v[110:113], v[158:161], v[190:193], v[110:113]
	v_mfma_f32_16x16x32_bf16 v[102:105], v[150:153], v[198:201], v[102:105]
	v_mfma_f32_16x16x32_bf16 v[94:97], v[158:161], v[198:201], v[94:97]
	v_mfma_f32_16x16x32_bf16 v[86:89], v[150:153], v[206:209], v[86:89]
	v_mfma_f32_16x16x32_bf16 v[78:81], v[158:161], v[206:209], v[78:81]
	s_setprio 0
	s_setprio 1
	v_mfma_f32_16x16x32_bf16 v[114:117], v[162:165], v[178:181], v[114:117]
	v_mfma_f32_16x16x32_bf16 v[106:109], v[170:173], v[178:181], v[106:109]
	v_mfma_f32_16x16x32_bf16 v[98:101], v[162:165], v[186:189], v[98:101]
	v_mfma_f32_16x16x32_bf16 v[90:93], v[170:173], v[186:189], v[90:93]
	v_mfma_f32_16x16x32_bf16 v[82:85], v[162:165], v[194:197], v[82:85]
	v_mfma_f32_16x16x32_bf16 v[74:77], v[170:173], v[194:197], v[74:77]
	v_mfma_f32_16x16x32_bf16 v[70:73], v[162:165], v[202:205], v[70:73]
	v_mfma_f32_16x16x32_bf16 v[66:69], v[170:173], v[202:205], v[66:69]
	v_mfma_f32_16x16x32_bf16 v[114:117], v[166:169], v[182:185], v[114:117]
	v_mfma_f32_16x16x32_bf16 v[106:109], v[174:177], v[182:185], v[106:109]
	v_mfma_f32_16x16x32_bf16 v[98:101], v[166:169], v[190:193], v[98:101]
	v_mfma_f32_16x16x32_bf16 v[90:93], v[174:177], v[190:193], v[90:93]
	v_mfma_f32_16x16x32_bf16 v[82:85], v[166:169], v[198:201], v[82:85]
	v_mfma_f32_16x16x32_bf16 v[74:77], v[174:177], v[198:201], v[74:77]
	v_mfma_f32_16x16x32_bf16 v[70:73], v[166:169], v[206:209], v[70:73]
	v_mfma_f32_16x16x32_bf16 v[66:69], v[174:177], v[206:209], v[66:69]
	s_setprio 0
	s_barrier
	s_add_i32 s26, s54, s40
	v_lshl_add_u64 v[140:141], s[36:37], 0, v[0:1]
	s_mov_b32 m0, s26
	ds_read_b128 v[178:181], v145 offset:16384
	ds_read_b128 v[182:185], v145 offset:17408
	ds_read_b128 v[186:189], v145 offset:18432
	ds_read_b128 v[190:193], v145 offset:19456
	ds_read_b128 v[194:197], v145 offset:20480
	ds_read_b128 v[198:201], v145 offset:21504
	ds_read_b128 v[202:205], v145 offset:22528
	ds_read_b128 v[206:209], v145 offset:23552
	global_load_lds_dwordx4 v[140:141], off
	s_add_i32 m0, s26, 0x2000
	s_add_u32 s26, s36, 0x30000
	v_lshl_add_u64 v[210:211], s[36:37], 0, v[130:131]
	s_addc_u32 s27, s37, 0
	s_add_i32 s54, s55, s40
	global_load_lds_dwordx4 v[210:211], off
	v_lshl_add_u64 v[212:213], s[26:27], 0, v[0:1]
	s_mov_b32 m0, s54
	v_lshl_add_u64 v[214:215], s[38:39], 0, v[132:133]
	global_load_lds_dwordx4 v[212:213], off
	v_lshl_add_u64 v[212:213], s[26:27], 0, v[130:131]
	s_add_i32 m0, s54, 0x2000
	s_nop 0
	global_load_lds_dwordx4 v[212:213], off
	v_lshl_add_u64 v[212:213], s[38:39], 0, v[134:135]
	s_mov_b32 m0, s19
	s_nop 0
	global_load_lds_dwordx4 v[212:213], off
	s_mov_b32 m0, s42
	s_nop 0
	global_load_lds_dwordx4 v[214:215], off
	s_waitcnt vmcnt(8)
	s_waitcnt lgkmcnt(0)
	s_barrier
; #define PG8_STAGE(bufoff, gbase, voff) do { _Pragma("unroll") for (int _i = 0; _i < 2; ++_i) \
;         __builtin_amdgcn_global_load_lds((const unsigned*)((const char*)(gbase) + (voff)[_i]), (LAS unsigned*)(lds + (bufoff) + ldsw + _i * 8192), 16, 0, 0); } while (0)
; #define PG8_LDA(dst, b, h) do { _Pragma("unroll") for (int m = 0; m < 4; ++m) _Pragma("unroll") for (int k = 0; k < 2; ++k) dst[m][k] = *(const LAS bf16x8*)(lds + PG8_SA(b, h) + aoff + m * 2048 + k * 1024); } while (0)
; #define PG8_LDB(dst, b, h) do { _Pragma("unroll") for (int n = 0; n < 2; ++n) _Pragma("unroll") for (int k = 0; k < 2; ++k) dst[n][k] = *(const LAS bf16x8*)(lds + PG8_SB(b, h) + boff + n * 2048 + k * 1024); } while (0)
; #define PG8_MMA(ai, bj, At, Bt) do { __builtin_amdgcn_s_setprio(1); _Pragma("unroll") for (int m = 0; m < 4; ++m) _Pragma("unroll") for (int n = 0; n < 2; ++n) _Pragma("unroll") for (int k = 0; k < 2; ++k) \
;         acc[ai][bj][m][n] = __builtin_amdgcn_mfma_f32_16x16x32_bf16(Bt[n][k], At[m][k], acc[ai][bj][m][n], 0, 0, 0); __builtin_amdgcn_s_setprio(0); } while (0)
; #define PG8_WAIT_V(n) asm volatile("s_waitcnt vmcnt(" #n ")" ::: "memory")
; #define PG8_WAIT_L(n) asm volatile("s_waitcnt lgkmcnt(" #n ")" ::: "memory")
; #define PG8_BAR __builtin_amdgcn_s_barrier()
; #define PG8_SCHED __builtin_amdgcn_sched_barrier(0)
; template <class Epi, class Sched, bool ALIGN_EPI, bool LAST_FUSED = false, bool PERM = false, bool CARRY = false>
; __device__ __forceinline__ void gemm_phase(LAS unsigned char* lds, const int tid, const int K, const int lda, const int ldb, const Sched& S, const Epi& E) {
;     ...
;             PG8_WAIT_V(8); PG8_WAIT_L(0); PG8_BAR; PG8_MMA(1, 0, At, B0); PG8_MMA(1, 1, At, B1); PG8_BAR; PG8_SCHED;
;             PG8_LDB(B0, 1, 0); PG8_LDB(B1, 1, 1); PG8_SCHED; PG8_LDA(At, 1, 0); PG8_STAGE(PG8_SA(0, 1), a2 + hstepA, voffA);
;             PG8_WAIT_V(8); PG8_WAIT_L(0); PG8_BAR; PG8_MMA(0, 0, At, B0); PG8_MMA(0, 1, At, B1); PG8_BAR; PG8_SCHED;
	s_setprio 1
	s_waitcnt lgkmcnt(0)
	v_mfma_f32_16x16x32_bf16 v[62:65], v[146:149], v[178:181], v[62:65]
	v_mfma_f32_16x16x32_bf16 v[58:61], v[154:157], v[178:181], v[58:61]
	v_mfma_f32_16x16x32_bf16 v[54:57], v[146:149], v[186:189], v[54:57]
	v_mfma_f32_16x16x32_bf16 v[46:49], v[154:157], v[186:189], v[46:49]
	v_mfma_f32_16x16x32_bf16 v[38:41], v[146:149], v[194:197], v[38:41]
	v_mfma_f32_16x16x32_bf16 v[30:33], v[154:157], v[194:197], v[30:33]
	v_mfma_f32_16x16x32_bf16 v[22:25], v[146:149], v[202:205], v[22:25]
	v_mfma_f32_16x16x32_bf16 v[14:17], v[154:157], v[202:205], v[14:17]
	v_mfma_f32_16x16x32_bf16 v[62:65], v[150:153], v[182:185], v[62:65]
	v_mfma_f32_16x16x32_bf16 v[58:61], v[158:161], v[182:185], v[58:61]
	v_mfma_f32_16x16x32_bf16 v[54:57], v[150:153], v[190:193], v[54:57]
	v_mfma_f32_16x16x32_bf16 v[46:49], v[158:161], v[190:193], v[46:49]
	v_mfma_f32_16x16x32_bf16 v[38:41], v[150:153], v[198:201], v[38:41]
	v_mfma_f32_16x16x32_bf16 v[30:33], v[158:161], v[198:201], v[30:33]
	v_mfma_f32_16x16x32_bf16 v[22:25], v[150:153], v[206:209], v[22:25]
	v_mfma_f32_16x16x32_bf16 v[14:17], v[158:161], v[206:209], v[14:17]
	s_setprio 0
	s_setprio 1
	v_mfma_f32_16x16x32_bf16 v[50:53], v[162:165], v[178:181], v[50:53]
	v_mfma_f32_16x16x32_bf16 v[42:45], v[170:173], v[178:181], v[42:45]
	v_mfma_f32_16x16x32_bf16 v[34:37], v[162:165], v[186:189], v[34:37]
	v_mfma_f32_16x16x32_bf16 v[26:29], v[170:173], v[186:189], v[26:29]
	v_mfma_f32_16x16x32_bf16 v[18:21], v[162:165], v[194:197], v[18:21]
	v_mfma_f32_16x16x32_bf16 v[10:13], v[170:173], v[194:197], v[10:13]
	v_mfma_f32_16x16x32_bf16 v[6:9], v[162:165], v[202:205], v[6:9]
	v_mfma_f32_16x16x32_bf16 v[2:5], v[170:173], v[202:205], v[2:5]
	v_mfma_f32_16x16x32_bf16 v[50:53], v[166:169], v[182:185], v[50:53]
	v_mfma_f32_16x16x32_bf16 v[42:45], v[174:177], v[182:185], v[42:45]
	v_mfma_f32_16x16x32_bf16 v[34:37], v[166:169], v[190:193], v[34:37]
	v_mfma_f32_16x16x32_bf16 v[26:29], v[174:177], v[190:193], v[26:29]
	v_mfma_f32_16x16x32_bf16 v[18:21], v[166:169], v[198:201], v[18:21]
	v_mfma_f32_16x16x32_bf16 v[10:13], v[174:177], v[198:201], v[10:13]
	v_mfma_f32_16x16x32_bf16 v[6:9], v[166:169], v[206:209], v[6:9]
	v_mfma_f32_16x16x32_bf16 v[2:5], v[174:177], v[206:209], v[2:5]
	s_setprio 0
	s_barrier
	s_add_i32 s54, 0, 0x18000
	s_add_i32 s55, 0, 0x1c000
	v_add_u32_e32 v158, s54, v144
	v_add_u32_e32 v174, s55, v144
	ds_read_b128 v[146:149], v158
	ds_read_b128 v[150:153], v158 offset:1024
	ds_read_b128 v[154:157], v158 offset:2048
	ds_read_b128 v[158:161], v158 offset:3072
	ds_read_b128 v[162:165], v174
	ds_read_b128 v[166:169], v174 offset:1024
	ds_read_b128 v[170:173], v174 offset:2048
	ds_read_b128 v[174:177], v174 offset:3072
	s_add_u32 s26, s38, 0x180000
	s_addc_u32 s27, s39, 0
	s_mov_b32 m0, s43
	v_lshl_add_u64 v[216:217], s[26:27], 0, v[134:135]
	ds_read_b128 v[178:181], v145 offset:32768
	ds_read_b128 v[182:185], v145 offset:33792
	ds_read_b128 v[186:189], v145 offset:34816
	ds_read_b128 v[190:193], v145 offset:35840
	ds_read_b128 v[194:197], v145 offset:36864
	ds_read_b128 v[198:201], v145 offset:37888
	ds_read_b128 v[202:205], v145 offset:38912
	ds_read_b128 v[206:209], v145 offset:39936
	global_load_lds_dwordx4 v[216:217], off
	v_lshl_add_u64 v[216:217], s[26:27], 0, v[132:133]
	s_mov_b32 m0, s44
	s_nop 0
	global_load_lds_dwordx4 v[216:217], off
	s_waitcnt vmcnt(8)
	s_waitcnt lgkmcnt(0)
	s_barrier
	s_setprio 1
	s_waitcnt lgkmcnt(0)
	v_mfma_f32_16x16x32_bf16 v[126:129], v[146:149], v[178:181], v[126:129]
	v_mfma_f32_16x16x32_bf16 v[122:125], v[154:157], v[178:181], v[122:125]
	v_mfma_f32_16x16x32_bf16 v[118:121], v[146:149], v[186:189], v[118:121]
	v_mfma_f32_16x16x32_bf16 v[110:113], v[154:157], v[186:189], v[110:113]
	v_mfma_f32_16x16x32_bf16 v[102:105], v[146:149], v[194:197], v[102:105]
	v_mfma_f32_16x16x32_bf16 v[94:97], v[154:157], v[194:197], v[94:97]
	v_mfma_f32_16x16x32_bf16 v[86:89], v[146:149], v[202:205], v[86:89]
	v_mfma_f32_16x16x32_bf16 v[78:81], v[154:157], v[202:205], v[78:81]
	v_mfma_f32_16x16x32_bf16 v[126:129], v[150:153], v[182:185], v[126:129]
	v_mfma_f32_16x16x32_bf16 v[122:125], v[158:161], v[182:185], v[122:125]
	v_mfma_f32_16x16x32_bf16 v[118:121], v[150:153], v[190:193], v[118:121]
	v_mfma_f32_16x16x32_bf16 v[110:113], v[158:161], v[190:193], v[110:113]
	v_mfma_f32_16x16x32_bf16 v[102:105], v[150:153], v[198:201], v[102:105]
	v_mfma_f32_16x16x32_bf16 v[94:97], v[158:161], v[198:201], v[94:97]
	v_mfma_f32_16x16x32_bf16 v[86:89], v[150:153], v[206:209], v[86:89]
	v_mfma_f32_16x16x32_bf16 v[78:81], v[158:161], v[206:209], v[78:81]
	s_setprio 0
	s_setprio 1
	v_mfma_f32_16x16x32_bf16 v[114:117], v[162:165], v[178:181], v[114:117]
	v_mfma_f32_16x16x32_bf16 v[106:109], v[170:173], v[178:181], v[106:109]
	v_mfma_f32_16x16x32_bf16 v[98:101], v[162:165], v[186:189], v[98:101]
	v_mfma_f32_16x16x32_bf16 v[90:93], v[170:173], v[186:189], v[90:93]
	v_mfma_f32_16x16x32_bf16 v[82:85], v[162:165], v[194:197], v[82:85]
	v_mfma_f32_16x16x32_bf16 v[74:77], v[170:173], v[194:197], v[74:77]
	v_mfma_f32_16x16x32_bf16 v[70:73], v[162:165], v[202:205], v[70:73]
	v_mfma_f32_16x16x32_bf16 v[66:69], v[170:173], v[202:205], v[66:69]
	v_mfma_f32_16x16x32_bf16 v[114:117], v[166:169], v[182:185], v[114:117]
	v_mfma_f32_16x16x32_bf16 v[106:109], v[174:177], v[182:185], v[106:109]
	v_mfma_f32_16x16x32_bf16 v[98:101], v[166:169], v[190:193], v[98:101]
	v_mfma_f32_16x16x32_bf16 v[90:93], v[174:177], v[190:193], v[90:93]
	v_mfma_f32_16x16x32_bf16 v[82:85], v[166:169], v[198:201], v[82:85]
	v_mfma_f32_16x16x32_bf16 v[74:77], v[174:177], v[198:201], v[74:77]
	v_mfma_f32_16x16x32_bf16 v[70:73], v[166:169], v[206:209], v[70:73]
	v_mfma_f32_16x16x32_bf16 v[66:69], v[174:177], v[206:209], v[66:69]
	s_setprio 0
	s_barrier
; #define PG8_STAGE(bufoff, gbase, voff) do { _Pragma("unroll") for (int _i = 0; _i < 2; ++_i) \
;         __builtin_amdgcn_global_load_lds((const unsigned*)((const char*)(gbase) + (voff)[_i]), (LAS unsigned*)(lds + (bufoff) + ldsw + _i * 8192), 16, 0, 0); } while (0)
; #define PG8_LDA(dst, b, h) do { _Pragma("unroll") for (int m = 0; m < 4; ++m) _Pragma("unroll") for (int k = 0; k < 2; ++k) dst[m][k] = *(const LAS bf16x8*)(lds + PG8_SA(b, h) + aoff + m * 2048 + k * 1024); } while (0)
; #define PG8_MMA(ai, bj, At, Bt) do { __builtin_amdgcn_s_setprio(1); _Pragma("unroll") for (int m = 0; m < 4; ++m) _Pragma("unroll") for (int n = 0; n < 2; ++n) _Pragma("unroll") for (int k = 0; k < 2; ++k) \
;         acc[ai][bj][m][n] = __builtin_amdgcn_mfma_f32_16x16x32_bf16(Bt[n][k], At[m][k], acc[ai][bj][m][n], 0, 0, 0); __builtin_amdgcn_s_setprio(0); } while (0)
; #define PG8_WAIT_V(n) asm volatile("s_waitcnt vmcnt(" #n ")" ::: "memory")
; #define PG8_WAIT_L(n) asm volatile("s_waitcnt lgkmcnt(" #n ")" ::: "memory")
; #define PG8_BAR __builtin_amdgcn_s_barrier()
; #define PG8_SCHED __builtin_amdgcn_sched_barrier(0)
; template <class Epi, class Sched, bool ALIGN_EPI, bool LAST_FUSED = false, bool PERM = false, bool CARRY = false>
; __device__ __forceinline__ void gemm_phase(LAS unsigned char* lds, const int tid, const int K, const int lda, const int ldb, const Sched& S, const Epi& E) {
;     ...
;             PG8_LDA(At, 1, 1); PG8_STAGE(PG8_SB(1, 0), b3, voffB); PG8_STAGE(PG8_SB(1, 1), b3 + hstepB, voffB); PG8_STAGE(PG8_SA(1, 0), a3, voffA);
;             PG8_WAIT_V(8); PG8_WAIT_L(0); PG8_BAR; PG8_MMA(1, 0, At, B0); PG8_MMA(1, 1, At, B1); PG8_BAR; PG8_SCHED;
;         }
	s_add_i32 s26, s54, s40
	v_lshl_add_u64 v[140:141], v[140:141], 0, s[68:69]
	s_mov_b32 m0, s26
	ds_read_b128 v[178:181], v145 offset:49152
	ds_read_b128 v[182:185], v145 offset:50176
	ds_read_b128 v[186:189], v145 offset:51200
	ds_read_b128 v[190:193], v145 offset:52224
	ds_read_b128 v[194:197], v145 offset:53248
	ds_read_b128 v[198:201], v145 offset:54272
	ds_read_b128 v[202:205], v145 offset:55296
	ds_read_b128 v[206:209], v145 offset:56320
	global_load_lds_dwordx4 v[140:141], off
	s_add_i32 m0, s26, 0x2000
	s_add_u32 s26, s36, 0x30080
	v_lshl_add_u64 v[140:141], v[210:211], 0, s[68:69]
	s_addc_u32 s27, s37, 0
	s_add_i32 s36, s55, s40
	global_load_lds_dwordx4 v[140:141], off
	v_lshl_add_u64 v[140:141], s[26:27], 0, v[0:1]
	s_mov_b32 m0, s36
	s_nop 0
	global_load_lds_dwordx4 v[140:141], off
	v_lshl_add_u64 v[140:141], s[26:27], 0, v[130:131]
	s_add_i32 m0, s36, 0x2000
	s_nop 0
	global_load_lds_dwordx4 v[140:141], off
	v_lshl_add_u64 v[140:141], v[212:213], 0, s[68:69]
	s_mov_b32 m0, s46
	s_nop 0
	global_load_lds_dwordx4 v[140:141], off
	v_lshl_add_u64 v[140:141], v[214:215], 0, s[68:69]
	s_mov_b32 m0, s47
	s_nop 0
	global_load_lds_dwordx4 v[140:141], off
	s_waitcnt vmcnt(8)
	s_waitcnt lgkmcnt(0)
	s_barrier
	s_setprio 1
	s_waitcnt lgkmcnt(0)
	v_mfma_f32_16x16x32_bf16 v[62:65], v[146:149], v[178:181], v[62:65]
	v_mfma_f32_16x16x32_bf16 v[58:61], v[154:157], v[178:181], v[58:61]
	v_mfma_f32_16x16x32_bf16 v[54:57], v[146:149], v[186:189], v[54:57]
	v_mfma_f32_16x16x32_bf16 v[46:49], v[154:157], v[186:189], v[46:49]
	v_mfma_f32_16x16x32_bf16 v[38:41], v[146:149], v[194:197], v[38:41]
	v_mfma_f32_16x16x32_bf16 v[30:33], v[154:157], v[194:197], v[30:33]
	v_mfma_f32_16x16x32_bf16 v[22:25], v[146:149], v[202:205], v[22:25]
	v_mfma_f32_16x16x32_bf16 v[14:17], v[154:157], v[202:205], v[14:17]
	v_mfma_f32_16x16x32_bf16 v[62:65], v[150:153], v[182:185], v[62:65]
	v_mfma_f32_16x16x32_bf16 v[58:61], v[158:161], v[182:185], v[58:61]
	v_mfma_f32_16x16x32_bf16 v[54:57], v[150:153], v[190:193], v[54:57]
	v_mfma_f32_16x16x32_bf16 v[46:49], v[158:161], v[190:193], v[46:49]
	v_mfma_f32_16x16x32_bf16 v[38:41], v[150:153], v[198:201], v[38:41]
	v_mfma_f32_16x16x32_bf16 v[30:33], v[158:161], v[198:201], v[30:33]
	v_mfma_f32_16x16x32_bf16 v[22:25], v[150:153], v[206:209], v[22:25]
	v_mfma_f32_16x16x32_bf16 v[14:17], v[158:161], v[206:209], v[14:17]
	s_setprio 0
	s_setprio 1
	v_mfma_f32_16x16x32_bf16 v[50:53], v[162:165], v[178:181], v[50:53]
	v_mfma_f32_16x16x32_bf16 v[42:45], v[170:173], v[178:181], v[42:45]
	v_mfma_f32_16x16x32_bf16 v[34:37], v[162:165], v[186:189], v[34:37]
	v_mfma_f32_16x16x32_bf16 v[26:29], v[170:173], v[186:189], v[26:29]
	v_mfma_f32_16x16x32_bf16 v[18:21], v[162:165], v[194:197], v[18:21]
	v_mfma_f32_16x16x32_bf16 v[10:13], v[170:173], v[194:197], v[10:13]
	v_mfma_f32_16x16x32_bf16 v[6:9], v[162:165], v[202:205], v[6:9]
	v_mfma_f32_16x16x32_bf16 v[2:5], v[170:173], v[202:205], v[2:5]
	v_mfma_f32_16x16x32_bf16 v[50:53], v[166:169], v[182:185], v[50:53]
	v_mfma_f32_16x16x32_bf16 v[42:45], v[174:177], v[182:185], v[42:45]
	v_mfma_f32_16x16x32_bf16 v[34:37], v[166:169], v[190:193], v[34:37]
	v_mfma_f32_16x16x32_bf16 v[26:29], v[174:177], v[190:193], v[26:29]
	v_mfma_f32_16x16x32_bf16 v[18:21], v[166:169], v[198:201], v[18:21]
	v_mfma_f32_16x16x32_bf16 v[10:13], v[174:177], v[198:201], v[10:13]
	v_mfma_f32_16x16x32_bf16 v[6:9], v[166:169], v[206:209], v[6:9]
	v_mfma_f32_16x16x32_bf16 v[2:5], v[174:177], v[206:209], v[2:5]
	s_add_i32 s53, s53, 2
	s_add_u32 s13, s13, 0x100
	s_addc_u32 s52, s52, 0
	s_cmp_gt_u32 s53, 9
	s_mov_b64 s[26:27], s[30:31]
	s_setprio 0
	s_barrier
	s_cbranch_scc0 .LBB0_705
	s_and_b64 vcc, exec, s[10:11]
	s_cbranch_vccz .LBB0_708
	s_barrier

; #define PG8_STAGE(bufoff, gbase, voff) do { _Pragma("unroll") for (int _i = 0; _i < 2; ++_i) \
;         __builtin_amdgcn_global_load_lds((const unsigned*)((const char*)(gbase) + (voff)[_i]), (LAS unsigned*)(lds + (bufoff) + ldsw + _i * 8192), 16, 0, 0); } while (0)
; #define PG8_LDA(dst, b, h) do { _Pragma("unroll") for (int m = 0; m < 4; ++m) _Pragma("unroll") for (int k = 0; k < 2; ++k) dst[m][k] = *(const LAS bf16x8*)(lds + PG8_SA(b, h) + aoff + m * 2048 + k * 1024); } while (0)
; #define PG8_LDB(dst, b, h) do { _Pragma("unroll") for (int n = 0; n < 2; ++n) _Pragma("unroll") for (int k = 0; k < 2; ++k) dst[n][k] = *(const LAS bf16x8*)(lds + PG8_SB(b, h) + boff + n * 2048 + k * 1024); } while (0)
; #define PG8_MMA(ai, bj, At, Bt) do { __builtin_amdgcn_s_setprio(1); _Pragma("unroll") for (int m = 0; m < 4; ++m) _Pragma("unroll") for (int n = 0; n < 2; ++n) _Pragma("unroll") for (int k = 0; k < 2; ++k) \
;         acc[ai][bj][m][n] = __builtin_amdgcn_mfma_f32_16x16x32_bf16(Bt[n][k], At[m][k], acc[ai][bj][m][n], 0, 0, 0); __builtin_amdgcn_s_setprio(0); } while (0)
; #define PG8_WAIT_V(n) asm volatile("s_waitcnt vmcnt(" #n ")" ::: "memory")
; #define PG8_WAIT_L(n) asm volatile("s_waitcnt lgkmcnt(" #n ")" ::: "memory")
; template <class Epi, class Sched, bool ALIGN_EPI, bool LAST_FUSED = false, bool PERM = false, bool CARRY = false>
; __device__ __forceinline__ void gemm_phase(LAS unsigned char* lds, const int tid, const int K, const int lda, const int ldb, const Sched& S, const Epi& E) {
;     ...
;         for (int t = 0; t < nt; t += 2) {
;             const bool last = (t == nt - 2);
;             const char* a1 = cA + (size_t)(t + 1) * kstep;
;             const char* a2 = last ? nA : cA + (size_t)(t + 2) * kstep; const char* b2 = last ? nB : cB + (size_t)(t + 2) * kstep;
;             const char* a3 = a2 + kstep; const char* b3 = b2 + kstep;
;             PG8_LDB(B0, 0, 0); PG8_LDB(B1, 0, 1); PG8_SCHED; PG8_LDA(At, 0, 0); PG8_STAGE(PG8_SA(1, 1), a1 + hstepA, voffA);
;             PG8_WAIT_V(8); PG8_WAIT_L(0); PG8_BAR; PG8_MMA(0, 0, At, B0); PG8_MMA(0, 1, At, B1); PG8_BAR; PG8_SCHED;
;             PG8_LDA(At, 0, 1); PG8_STAGE(PG8_SB(0, 0), b2, voffB); PG8_STAGE(PG8_SB(0, 1), b2 + hstepB, voffB); PG8_STAGE(PG8_SA(0, 0), a2, voffA);
;             PG8_WAIT_V(8); PG8_WAIT_L(0); PG8_BAR; PG8_MMA(1, 0, At, B0); PG8_MMA(1, 1, At, B1); PG8_BAR; PG8_SCHED;
.LBB0_838:
	s_add_u32 s6, s4, 0xfff80080
	s_addc_u32 s7, s5, -1
	s_add_i32 s29, 0, 0x10000
	s_cmp_eq_u32 s28, 28
	s_cselect_b32 s37, s43, s7
	s_cselect_b32 s36, s42, s6
	v_add_u32_e32 v140, s29, v146
	s_cselect_b32 s7, s71, s23
	s_cselect_b32 s6, s70, s22
	s_add_i32 s31, 0, 0x14000
	ds_read_b128 v[136:139], v140
	ds_read_b128 v[148:151], v140 offset:1024
	ds_read_b128 v[152:155], v140 offset:2048
	ds_read_b128 v[156:159], v140 offset:3072
	v_add_u32_e32 v140, s31, v146
	ds_read_b128 v[160:163], v140
	ds_read_b128 v[164:167], v140 offset:1024
	ds_read_b128 v[168:171], v140 offset:2048
	ds_read_b128 v[172:175], v140 offset:3072
	v_lshl_add_u64 v[140:141], s[4:5], 0, v[132:133]
	s_add_i32 m0, s50, 0xc000
	ds_read_b128 v[176:179], v147
	ds_read_b128 v[180:183], v147 offset:1024
	ds_read_b128 v[184:187], v147 offset:2048
	ds_read_b128 v[188:191], v147 offset:3072
	ds_read_b128 v[192:195], v147 offset:4096
	ds_read_b128 v[196:199], v147 offset:5120
	ds_read_b128 v[200:203], v147 offset:6144
	ds_read_b128 v[204:207], v147 offset:7168
	global_load_lds_dwordx4 v[140:141], off
	v_lshl_add_u64 v[140:141], s[4:5], 0, v[134:135]
	s_add_i32 m0, s50, 0xe000
	s_nop 0
	global_load_lds_dwordx4 v[140:141], off
	s_waitcnt vmcnt(8)
	s_waitcnt lgkmcnt(0)
	s_barrier
	s_setprio 1
	s_waitcnt lgkmcnt(0)
	v_mfma_f32_16x16x32_bf16 v[126:129], v[136:139], v[176:179], v[126:129]
	v_mfma_f32_16x16x32_bf16 v[122:125], v[152:155], v[176:179], v[122:125]
	v_mfma_f32_16x16x32_bf16 v[110:113], v[136:139], v[184:187], v[110:113]
	v_mfma_f32_16x16x32_bf16 v[106:109], v[152:155], v[184:187], v[106:109]
	v_mfma_f32_16x16x32_bf16 v[94:97], v[136:139], v[192:195], v[94:97]
	v_mfma_f32_16x16x32_bf16 v[90:93], v[152:155], v[192:195], v[90:93]
	v_mfma_f32_16x16x32_bf16 v[78:81], v[136:139], v[200:203], v[78:81]
	v_mfma_f32_16x16x32_bf16 v[74:77], v[152:155], v[200:203], v[74:77]
	v_mfma_f32_16x16x32_bf16 v[126:129], v[148:151], v[180:183], v[126:129]
	v_mfma_f32_16x16x32_bf16 v[122:125], v[156:159], v[180:183], v[122:125]
	v_mfma_f32_16x16x32_bf16 v[110:113], v[148:151], v[188:191], v[110:113]
	v_mfma_f32_16x16x32_bf16 v[106:109], v[156:159], v[188:191], v[106:109]
	v_mfma_f32_16x16x32_bf16 v[94:97], v[148:151], v[196:199], v[94:97]
	v_mfma_f32_16x16x32_bf16 v[90:93], v[156:159], v[196:199], v[90:93]
	v_mfma_f32_16x16x32_bf16 v[78:81], v[148:151], v[204:207], v[78:81]
	v_mfma_f32_16x16x32_bf16 v[74:77], v[156:159], v[204:207], v[74:77]
	s_setprio 0
	s_setprio 1
	v_mfma_f32_16x16x32_bf16 v[118:121], v[160:163], v[176:179], v[118:121]
	v_mfma_f32_16x16x32_bf16 v[114:117], v[168:171], v[176:179], v[114:117]
	v_mfma_f32_16x16x32_bf16 v[102:105], v[160:163], v[184:187], v[102:105]
	v_mfma_f32_16x16x32_bf16 v[98:101], v[168:171], v[184:187], v[98:101]
	v_mfma_f32_16x16x32_bf16 v[86:89], v[160:163], v[192:195], v[86:89]
	v_mfma_f32_16x16x32_bf16 v[82:85], v[168:171], v[192:195], v[82:85]
	v_mfma_f32_16x16x32_bf16 v[70:73], v[160:163], v[200:203], v[70:73]
	v_mfma_f32_16x16x32_bf16 v[66:69], v[168:171], v[200:203], v[66:69]
	v_mfma_f32_16x16x32_bf16 v[118:121], v[164:167], v[180:183], v[118:121]
	v_mfma_f32_16x16x32_bf16 v[114:117], v[172:175], v[180:183], v[114:117]
	v_mfma_f32_16x16x32_bf16 v[102:105], v[164:167], v[188:191], v[102:105]
	v_mfma_f32_16x16x32_bf16 v[98:101], v[172:175], v[188:191], v[98:101]
	v_mfma_f32_16x16x32_bf16 v[86:89], v[164:167], v[196:199], v[86:89]
	v_mfma_f32_16x16x32_bf16 v[82:85], v[172:175], v[196:199], v[82:85]
	v_mfma_f32_16x16x32_bf16 v[70:73], v[164:167], v[204:207], v[70:73]
	v_mfma_f32_16x16x32_bf16 v[66:69], v[172:175], v[204:207], v[66:69]
	s_setprio 0
	s_barrier
	s_add_i32 s29, s29, s49
	v_lshl_add_u64 v[140:141], s[6:7], 0, v[0:1]
	s_mov_b32 m0, s29
	ds_read_b128 v[176:179], v147 offset:16384
	ds_read_b128 v[180:183], v147 offset:17408
	ds_read_b128 v[184:187], v147 offset:18432
	ds_read_b128 v[188:191], v147 offset:19456
	ds_read_b128 v[192:195], v147 offset:20480
	ds_read_b128 v[196:199], v147 offset:21504
	ds_read_b128 v[200:203], v147 offset:22528
	ds_read_b128 v[204:207], v147 offset:23552
	global_load_lds_dwordx4 v[140:141], off
	s_add_i32 m0, s29, 0x2000
	s_add_u32 s44, s6, 0x80000
	v_lshl_add_u64 v[208:209], s[6:7], 0, v[130:131]
	s_addc_u32 s45, s7, 0
	s_add_i32 s29, s31, s49
	global_load_lds_dwordx4 v[208:209], off
	v_lshl_add_u64 v[210:211], s[44:45], 0, v[0:1]
	s_mov_b32 m0, s29
	v_lshl_add_u64 v[212:213], s[36:37], 0, v[130:131]
	global_load_lds_dwordx4 v[210:211], off
	v_lshl_add_u64 v[210:211], s[44:45], 0, v[130:131]
	s_add_i32 m0, s29, 0x2000
	s_nop 0
	global_load_lds_dwordx4 v[210:211], off
	v_lshl_add_u64 v[210:211], s[36:37], 0, v[0:1]
	s_mov_b32 m0, s50
	s_nop 0
	global_load_lds_dwordx4 v[210:211], off
	s_mov_b32 m0, s51
	s_nop 0
	global_load_lds_dwordx4 v[212:213], off
	s_waitcnt vmcnt(8)
	s_waitcnt lgkmcnt(0)
	s_barrier
; #define PG8_STAGE(bufoff, gbase, voff) do { _Pragma("unroll") for (int _i = 0; _i < 2; ++_i) \
;         __builtin_amdgcn_global_load_lds((const unsigned*)((const char*)(gbase) + (voff)[_i]), (LAS unsigned*)(lds + (bufoff) + ldsw + _i * 8192), 16, 0, 0); } while (0)
; #define PG8_LDA(dst, b, h) do { _Pragma("unroll") for (int m = 0; m < 4; ++m) _Pragma("unroll") for (int k = 0; k < 2; ++k) dst[m][k] = *(const LAS bf16x8*)(lds + PG8_SA(b, h) + aoff + m * 2048 + k * 1024); } while (0)
; #define PG8_LDB(dst, b, h) do { _Pragma("unroll") for (int n = 0; n < 2; ++n) _Pragma("unroll") for (int k = 0; k < 2; ++k) dst[n][k] = *(const LAS bf16x8*)(lds + PG8_SB(b, h) + boff + n * 2048 + k * 1024); } while (0)
; #define PG8_MMA(ai, bj, At, Bt) do { __builtin_amdgcn_s_setprio(1); _Pragma("unroll") for (int m = 0; m < 4; ++m) _Pragma("unroll") for (int n = 0; n < 2; ++n) _Pragma("unroll") for (int k = 0; k < 2; ++k) \
;         acc[ai][bj][m][n] = __builtin_amdgcn_mfma_f32_16x16x32_bf16(Bt[n][k], At[m][k], acc[ai][bj][m][n], 0, 0, 0); __builtin_amdgcn_s_setprio(0); } while (0)
; #define PG8_WAIT_V(n) asm volatile("s_waitcnt vmcnt(" #n ")" ::: "memory")
; #define PG8_WAIT_L(n) asm volatile("s_waitcnt lgkmcnt(" #n ")" ::: "memory")
; #define PG8_BAR __builtin_amdgcn_s_barrier()
; #define PG8_SCHED __builtin_amdgcn_sched_barrier(0)
; template <class Epi, class Sched, bool ALIGN_EPI, bool LAST_FUSED = false, bool PERM = false, bool CARRY = false>
; __device__ __forceinline__ void gemm_phase(LAS unsigned char* lds, const int tid, const int K, const int lda, const int ldb, const Sched& S, const Epi& E) {
;     ...
;             PG8_WAIT_V(8); PG8_WAIT_L(0); PG8_BAR; PG8_MMA(1, 0, At, B0); PG8_MMA(1, 1, At, B1); PG8_BAR; PG8_SCHED;
;             PG8_LDB(B0, 1, 0); PG8_LDB(B1, 1, 1); PG8_SCHED; PG8_LDA(At, 1, 0); PG8_STAGE(PG8_SA(0, 1), a2 + hstepA, voffA);
;             PG8_WAIT_V(8); PG8_WAIT_L(0); PG8_BAR; PG8_MMA(0, 0, At, B0); PG8_MMA(0, 1, At, B1); PG8_BAR; PG8_SCHED;
	s_setprio 1
	s_waitcnt lgkmcnt(0)
	v_mfma_f32_16x16x32_bf16 v[62:65], v[136:139], v[176:179], v[62:65]
	v_mfma_f32_16x16x32_bf16 v[58:61], v[152:155], v[176:179], v[58:61]
	v_mfma_f32_16x16x32_bf16 v[46:49], v[136:139], v[184:187], v[46:49]
	v_mfma_f32_16x16x32_bf16 v[42:45], v[152:155], v[184:187], v[42:45]
	v_mfma_f32_16x16x32_bf16 v[30:33], v[136:139], v[192:195], v[30:33]
	v_mfma_f32_16x16x32_bf16 v[26:29], v[152:155], v[192:195], v[26:29]
	v_mfma_f32_16x16x32_bf16 v[14:17], v[136:139], v[200:203], v[14:17]
	v_mfma_f32_16x16x32_bf16 v[10:13], v[152:155], v[200:203], v[10:13]
	v_mfma_f32_16x16x32_bf16 v[62:65], v[148:151], v[180:183], v[62:65]
	v_mfma_f32_16x16x32_bf16 v[58:61], v[156:159], v[180:183], v[58:61]
	v_mfma_f32_16x16x32_bf16 v[46:49], v[148:151], v[188:191], v[46:49]
	v_mfma_f32_16x16x32_bf16 v[42:45], v[156:159], v[188:191], v[42:45]
	v_mfma_f32_16x16x32_bf16 v[30:33], v[148:151], v[196:199], v[30:33]
	v_mfma_f32_16x16x32_bf16 v[26:29], v[156:159], v[196:199], v[26:29]
	v_mfma_f32_16x16x32_bf16 v[14:17], v[148:151], v[204:207], v[14:17]
	v_mfma_f32_16x16x32_bf16 v[10:13], v[156:159], v[204:207], v[10:13]
	s_setprio 0
	s_setprio 1
	v_mfma_f32_16x16x32_bf16 v[54:57], v[160:163], v[176:179], v[54:57]
	v_mfma_f32_16x16x32_bf16 v[50:53], v[168:171], v[176:179], v[50:53]
	v_mfma_f32_16x16x32_bf16 v[38:41], v[160:163], v[184:187], v[38:41]
	v_mfma_f32_16x16x32_bf16 v[34:37], v[168:171], v[184:187], v[34:37]
	v_mfma_f32_16x16x32_bf16 v[22:25], v[160:163], v[192:195], v[22:25]
	v_mfma_f32_16x16x32_bf16 v[18:21], v[168:171], v[192:195], v[18:21]
	v_mfma_f32_16x16x32_bf16 v[6:9], v[160:163], v[200:203], v[6:9]
	v_mfma_f32_16x16x32_bf16 v[2:5], v[168:171], v[200:203], v[2:5]
	v_mfma_f32_16x16x32_bf16 v[54:57], v[164:167], v[180:183], v[54:57]
	v_mfma_f32_16x16x32_bf16 v[50:53], v[172:175], v[180:183], v[50:53]
	v_mfma_f32_16x16x32_bf16 v[38:41], v[164:167], v[188:191], v[38:41]
	v_mfma_f32_16x16x32_bf16 v[34:37], v[172:175], v[188:191], v[34:37]
	v_mfma_f32_16x16x32_bf16 v[22:25], v[164:167], v[196:199], v[22:25]
	v_mfma_f32_16x16x32_bf16 v[18:21], v[172:175], v[196:199], v[18:21]
	v_mfma_f32_16x16x32_bf16 v[6:9], v[164:167], v[204:207], v[6:9]
	v_mfma_f32_16x16x32_bf16 v[2:5], v[172:175], v[204:207], v[2:5]
	s_setprio 0
	s_barrier
	s_add_i32 s29, 0, 0x18000
	s_add_i32 s31, 0, 0x1c000
	v_add_u32_e32 v156, s29, v146
	v_add_u32_e32 v172, s31, v146
	ds_read_b128 v[136:139], v156
	ds_read_b128 v[148:151], v156 offset:1024
	ds_read_b128 v[152:155], v156 offset:2048
	ds_read_b128 v[156:159], v156 offset:3072
	ds_read_b128 v[160:163], v172
	ds_read_b128 v[164:167], v172 offset:1024
	ds_read_b128 v[168:171], v172 offset:2048
	ds_read_b128 v[172:175], v172 offset:3072
	s_add_u32 s36, s36, 0x80000
	s_addc_u32 s37, s37, 0
	s_mov_b32 m0, s52
	v_lshl_add_u64 v[214:215], s[36:37], 0, v[0:1]
	ds_read_b128 v[176:179], v147 offset:32768
	ds_read_b128 v[180:183], v147 offset:33792
	ds_read_b128 v[184:187], v147 offset:34816
	ds_read_b128 v[188:191], v147 offset:35840
	ds_read_b128 v[192:195], v147 offset:36864
	ds_read_b128 v[196:199], v147 offset:37888
	ds_read_b128 v[200:203], v147 offset:38912
	ds_read_b128 v[204:207], v147 offset:39936
	global_load_lds_dwordx4 v[214:215], off
	v_lshl_add_u64 v[214:215], s[36:37], 0, v[130:131]
	s_mov_b32 m0, s53
	s_nop 0
	global_load_lds_dwordx4 v[214:215], off
	s_waitcnt vmcnt(8)
	s_waitcnt lgkmcnt(0)
	s_barrier
	s_setprio 1
	s_waitcnt lgkmcnt(0)
	v_mfma_f32_16x16x32_bf16 v[126:129], v[136:139], v[176:179], v[126:129]
	v_mfma_f32_16x16x32_bf16 v[122:125], v[152:155], v[176:179], v[122:125]
	v_mfma_f32_16x16x32_bf16 v[110:113], v[136:139], v[184:187], v[110:113]
	v_mfma_f32_16x16x32_bf16 v[106:109], v[152:155], v[184:187], v[106:109]
	v_mfma_f32_16x16x32_bf16 v[94:97], v[136:139], v[192:195], v[94:97]
	v_mfma_f32_16x16x32_bf16 v[90:93], v[152:155], v[192:195], v[90:93]
	v_mfma_f32_16x16x32_bf16 v[78:81], v[136:139], v[200:203], v[78:81]
	v_mfma_f32_16x16x32_bf16 v[74:77], v[152:155], v[200:203], v[74:77]
	v_mfma_f32_16x16x32_bf16 v[126:129], v[148:151], v[180:183], v[126:129]
	v_mfma_f32_16x16x32_bf16 v[122:125], v[156:159], v[180:183], v[122:125]
	v_mfma_f32_16x16x32_bf16 v[110:113], v[148:151], v[188:191], v[110:113]
	v_mfma_f32_16x16x32_bf16 v[106:109], v[156:159], v[188:191], v[106:109]
	v_mfma_f32_16x16x32_bf16 v[94:97], v[148:151], v[196:199], v[94:97]
	v_mfma_f32_16x16x32_bf16 v[90:93], v[156:159], v[196:199], v[90:93]
	v_mfma_f32_16x16x32_bf16 v[78:81], v[148:151], v[204:207], v[78:81]
	v_mfma_f32_16x16x32_bf16 v[74:77], v[156:159], v[204:207], v[74:77]
	s_setprio 0
	s_setprio 1
	v_mfma_f32_16x16x32_bf16 v[118:121], v[160:163], v[176:179], v[118:121]
	v_mfma_f32_16x16x32_bf16 v[114:117], v[168:171], v[176:179], v[114:117]
	v_mfma_f32_16x16x32_bf16 v[102:105], v[160:163], v[184:187], v[102:105]
	v_mfma_f32_16x16x32_bf16 v[98:101], v[168:171], v[184:187], v[98:101]
	v_mfma_f32_16x16x32_bf16 v[86:89], v[160:163], v[192:195], v[86:89]
	v_mfma_f32_16x16x32_bf16 v[82:85], v[168:171], v[192:195], v[82:85]
	v_mfma_f32_16x16x32_bf16 v[70:73], v[160:163], v[200:203], v[70:73]
	v_mfma_f32_16x16x32_bf16 v[66:69], v[168:171], v[200:203], v[66:69]
	v_mfma_f32_16x16x32_bf16 v[118:121], v[164:167], v[180:183], v[118:121]
	v_mfma_f32_16x16x32_bf16 v[114:117], v[172:175], v[180:183], v[114:117]
	v_mfma_f32_16x16x32_bf16 v[102:105], v[164:167], v[188:191], v[102:105]
	v_mfma_f32_16x16x32_bf16 v[98:101], v[172:175], v[188:191], v[98:101]
	v_mfma_f32_16x16x32_bf16 v[86:89], v[164:167], v[196:199], v[86:89]
	v_mfma_f32_16x16x32_bf16 v[82:85], v[172:175], v[196:199], v[82:85]
	v_mfma_f32_16x16x32_bf16 v[70:73], v[164:167], v[204:207], v[70:73]
	v_mfma_f32_16x16x32_bf16 v[66:69], v[172:175], v[204:207], v[66:69]
	s_setprio 0
	s_barrier
; #define PG8_STAGE(bufoff, gbase, voff) do { _Pragma("unroll") for (int _i = 0; _i < 2; ++_i) \
;         __builtin_amdgcn_global_load_lds((const unsigned*)((const char*)(gbase) + (voff)[_i]), (LAS unsigned*)(lds + (bufoff) + ldsw + _i * 8192), 16, 0, 0); } while (0)
; #define PG8_LDA(dst, b, h) do { _Pragma("unroll") for (int m = 0; m < 4; ++m) _Pragma("unroll") for (int k = 0; k < 2; ++k) dst[m][k] = *(const LAS bf16x8*)(lds + PG8_SA(b, h) + aoff + m * 2048 + k * 1024); } while (0)
; #define PG8_MMA(ai, bj, At, Bt) do { __builtin_amdgcn_s_setprio(1); _Pragma("unroll") for (int m = 0; m < 4; ++m) _Pragma("unroll") for (int n = 0; n < 2; ++n) _Pragma("unroll") for (int k = 0; k < 2; ++k) \
;         acc[ai][bj][m][n] = __builtin_amdgcn_mfma_f32_16x16x32_bf16(Bt[n][k], At[m][k], acc[ai][bj][m][n], 0, 0, 0); __builtin_amdgcn_s_setprio(0); } while (0)
; #define PG8_WAIT_V(n) asm volatile("s_waitcnt vmcnt(" #n ")" ::: "memory")
; #define PG8_WAIT_L(n) asm volatile("s_waitcnt lgkmcnt(" #n ")" ::: "memory")
; #define PG8_BAR __builtin_amdgcn_s_barrier()
; #define PG8_SCHED __builtin_amdgcn_sched_barrier(0)
; template <class Epi, class Sched, bool ALIGN_EPI, bool LAST_FUSED = false, bool PERM = false, bool CARRY = false>
; __device__ __forceinline__ void gemm_phase(LAS unsigned char* lds, const int tid, const int K, const int lda, const int ldb, const Sched& S, const Epi& E) {
;     ...
;             PG8_LDA(At, 1, 1); PG8_STAGE(PG8_SB(1, 0), b3, voffB); PG8_STAGE(PG8_SB(1, 1), b3 + hstepB, voffB); PG8_STAGE(PG8_SA(1, 0), a3, voffA);
;             PG8_WAIT_V(8); PG8_WAIT_L(0); PG8_BAR; PG8_MMA(1, 0, At, B0); PG8_MMA(1, 1, At, B1); PG8_BAR; PG8_SCHED;
;         }
	s_add_i32 s29, s29, s49
	v_lshl_add_u64 v[140:141], v[140:141], 0, s[68:69]
	s_mov_b32 m0, s29
	ds_read_b128 v[176:179], v147 offset:49152
	ds_read_b128 v[180:183], v147 offset:50176
	ds_read_b128 v[184:187], v147 offset:51200
	ds_read_b128 v[188:191], v147 offset:52224
	ds_read_b128 v[192:195], v147 offset:53248
	ds_read_b128 v[196:199], v147 offset:54272
	ds_read_b128 v[200:203], v147 offset:55296
	ds_read_b128 v[204:207], v147 offset:56320
	global_load_lds_dwordx4 v[140:141], off
	s_add_i32 m0, s29, 0x2000
	s_add_u32 s6, s6, 0x80080
	v_lshl_add_u64 v[140:141], v[208:209], 0, s[68:69]
	s_addc_u32 s7, s7, 0
	s_add_i32 s29, s31, s49
	global_load_lds_dwordx4 v[140:141], off
	v_lshl_add_u64 v[140:141], s[6:7], 0, v[0:1]
	s_mov_b32 m0, s29
	s_nop 0
	global_load_lds_dwordx4 v[140:141], off
	v_lshl_add_u64 v[140:141], s[6:7], 0, v[130:131]
	s_add_i32 m0, s29, 0x2000
	s_nop 0
	global_load_lds_dwordx4 v[140:141], off
	v_lshl_add_u64 v[140:141], v[210:211], 0, s[68:69]
	s_mov_b32 m0, s55
	s_nop 0
	global_load_lds_dwordx4 v[140:141], off
	v_lshl_add_u64 v[140:141], v[212:213], 0, s[68:69]
	s_mov_b32 m0, s56
	s_nop 0
	global_load_lds_dwordx4 v[140:141], off
	s_waitcnt vmcnt(8)
	s_waitcnt lgkmcnt(0)
	s_barrier
	s_setprio 1
	s_waitcnt lgkmcnt(0)
	v_mfma_f32_16x16x32_bf16 v[62:65], v[136:139], v[176:179], v[62:65]
	v_mfma_f32_16x16x32_bf16 v[58:61], v[152:155], v[176:179], v[58:61]
	v_mfma_f32_16x16x32_bf16 v[46:49], v[136:139], v[184:187], v[46:49]
	v_mfma_f32_16x16x32_bf16 v[42:45], v[152:155], v[184:187], v[42:45]
	v_mfma_f32_16x16x32_bf16 v[30:33], v[136:139], v[192:195], v[30:33]
	v_mfma_f32_16x16x32_bf16 v[26:29], v[152:155], v[192:195], v[26:29]
	v_mfma_f32_16x16x32_bf16 v[14:17], v[136:139], v[200:203], v[14:17]
	v_mfma_f32_16x16x32_bf16 v[10:13], v[152:155], v[200:203], v[10:13]
	v_mfma_f32_16x16x32_bf16 v[62:65], v[148:151], v[180:183], v[62:65]
	v_mfma_f32_16x16x32_bf16 v[58:61], v[156:159], v[180:183], v[58:61]
	v_mfma_f32_16x16x32_bf16 v[46:49], v[148:151], v[188:191], v[46:49]
	v_mfma_f32_16x16x32_bf16 v[42:45], v[156:159], v[188:191], v[42:45]
	v_mfma_f32_16x16x32_bf16 v[30:33], v[148:151], v[196:199], v[30:33]
	v_mfma_f32_16x16x32_bf16 v[26:29], v[156:159], v[196:199], v[26:29]
	v_mfma_f32_16x16x32_bf16 v[14:17], v[148:151], v[204:207], v[14:17]
	v_mfma_f32_16x16x32_bf16 v[10:13], v[156:159], v[204:207], v[10:13]
	s_setprio 0
	s_setprio 1
	v_mfma_f32_16x16x32_bf16 v[54:57], v[160:163], v[176:179], v[54:57]
	v_mfma_f32_16x16x32_bf16 v[50:53], v[168:171], v[176:179], v[50:53]
	v_mfma_f32_16x16x32_bf16 v[38:41], v[160:163], v[184:187], v[38:41]
	v_mfma_f32_16x16x32_bf16 v[34:37], v[168:171], v[184:187], v[34:37]
	v_mfma_f32_16x16x32_bf16 v[22:25], v[160:163], v[192:195], v[22:25]
	v_mfma_f32_16x16x32_bf16 v[18:21], v[168:171], v[192:195], v[18:21]
	v_mfma_f32_16x16x32_bf16 v[6:9], v[160:163], v[200:203], v[6:9]
	v_mfma_f32_16x16x32_bf16 v[2:5], v[168:171], v[200:203], v[2:5]
	v_mfma_f32_16x16x32_bf16 v[54:57], v[164:167], v[180:183], v[54:57]
	v_mfma_f32_16x16x32_bf16 v[50:53], v[172:175], v[180:183], v[50:53]
	v_mfma_f32_16x16x32_bf16 v[38:41], v[164:167], v[188:191], v[38:41]
	v_mfma_f32_16x16x32_bf16 v[34:37], v[172:175], v[188:191], v[34:37]
	v_mfma_f32_16x16x32_bf16 v[22:25], v[164:167], v[196:199], v[22:25]
	v_mfma_f32_16x16x32_bf16 v[18:21], v[172:175], v[196:199], v[18:21]
	v_mfma_f32_16x16x32_bf16 v[6:9], v[164:167], v[204:207], v[6:9]
	v_mfma_f32_16x16x32_bf16 v[2:5], v[172:175], v[204:207], v[2:5]
	s_add_i32 s28, s28, 2
	s_add_u32 s4, s4, 0x100
	s_addc_u32 s5, s5, 0
	s_add_u32 s22, s22, 0x100
	s_addc_u32 s23, s23, 0
	s_cmp_gt_u32 s28, 29
	s_setprio 0
	s_barrier
	s_cbranch_scc0 .LBB0_838
	s_and_b64 vcc, exec, s[26:27]
	s_cbranch_vccz .LBB0_841
	s_barrier

; #define PG8_STAGE(bufoff, gbase, voff) do { _Pragma("unroll") for (int _i = 0; _i < 2; ++_i) \
;         __builtin_amdgcn_global_load_lds((const unsigned*)((const char*)(gbase) + (voff)[_i]), (LAS unsigned*)(lds + (bufoff) + ldsw + _i * 8192), 16, 0, 0); } while (0)
; #define PG8_LDA(dst, b, h) do { _Pragma("unroll") for (int m = 0; m < 4; ++m) _Pragma("unroll") for (int k = 0; k < 2; ++k) dst[m][k] = *(const LAS bf16x8*)(lds + PG8_SA(b, h) + aoff + m * 2048 + k * 1024); } while (0)
; #define PG8_LDB(dst, b, h) do { _Pragma("unroll") for (int n = 0; n < 2; ++n) _Pragma("unroll") for (int k = 0; k < 2; ++k) dst[n][k] = *(const LAS bf16x8*)(lds + PG8_SB(b, h) + boff + n * 2048 + k * 1024); } while (0)
; #define PG8_MMA(ai, bj, At, Bt) do { __builtin_amdgcn_s_setprio(1); _Pragma("unroll") for (int m = 0; m < 4; ++m) _Pragma("unroll") for (int n = 0; n < 2; ++n) _Pragma("unroll") for (int k = 0; k < 2; ++k) \
;         acc[ai][bj][m][n] = __builtin_amdgcn_mfma_f32_16x16x32_bf16(Bt[n][k], At[m][k], acc[ai][bj][m][n], 0, 0, 0); __builtin_amdgcn_s_setprio(0); } while (0)
; #define PG8_WAIT_V(n) asm volatile("s_waitcnt vmcnt(" #n ")" ::: "memory")
; #define PG8_WAIT_L(n) asm volatile("s_waitcnt lgkmcnt(" #n ")" ::: "memory")
; template <class Epi, class Sched, bool ALIGN_EPI, bool LAST_FUSED = false, bool PERM = false, bool CARRY = false>
; __device__ __forceinline__ void gemm_phase(LAS unsigned char* lds, const int tid, const int K, const int lda, const int ldb, const Sched& S, const Epi& E) {
;     ...
;         for (int t = 0; t < nt; t += 2) {
;             const bool last = (t == nt - 2);
;             const char* a1 = cA + (size_t)(t + 1) * kstep;
;             const char* a2 = last ? nA : cA + (size_t)(t + 2) * kstep; const char* b2 = last ? nB : cB + (size_t)(t + 2) * kstep;
;             const char* a3 = a2 + kstep; const char* b3 = b2 + kstep;
;             PG8_LDB(B0, 0, 0); PG8_LDB(B1, 0, 1); PG8_SCHED; PG8_LDA(At, 0, 0); PG8_STAGE(PG8_SA(1, 1), a1 + hstepA, voffA);
;             PG8_WAIT_V(8); PG8_WAIT_L(0); PG8_BAR; PG8_MMA(0, 0, At, B0); PG8_MMA(0, 1, At, B1); PG8_BAR; PG8_SCHED;
;             PG8_LDA(At, 0, 1); PG8_STAGE(PG8_SB(0, 0), b2, voffB); PG8_STAGE(PG8_SB(0, 1), b2 + hstepB, voffB); PG8_STAGE(PG8_SA(0, 0), a2, voffA);
;             PG8_WAIT_V(8); PG8_WAIT_L(0); PG8_BAR; PG8_MMA(1, 0, At, B0); PG8_MMA(1, 1, At, B1); PG8_BAR; PG8_SCHED;
.LBB0_1077:
	s_add_u32 s23, s26, 0xfff80080
	s_addc_u32 s28, s27, -1
	s_add_i32 s29, 0, 0x10000
	s_cmp_eq_u32 s15, 28
	s_cselect_b32 s37, s17, s28
	s_cselect_b32 s36, s16, s23
	s_cselect_b32 s31, s19, s13
	s_cselect_b32 s30, s18, s5
	s_add_i32 s23, 0, 0x14000
	v_add_u32_e32 v152, s29, v142
	v_add_u32_e32 v168, s23, v142
	ds_read_b128 v[136:139], v152
	ds_read_b128 v[144:147], v152 offset:1024
	ds_read_b128 v[148:151], v152 offset:2048
	ds_read_b128 v[152:155], v152 offset:3072
	ds_read_b128 v[156:159], v168
	ds_read_b128 v[160:163], v168 offset:1024
	ds_read_b128 v[164:167], v168 offset:2048
	ds_read_b128 v[168:171], v168 offset:3072
	v_lshl_add_u64 v[204:205], s[26:27], 0, v[132:133]
	s_add_i32 m0, s46, 0xc000
	ds_read_b128 v[172:175], v143
	ds_read_b128 v[176:179], v143 offset:1024
	ds_read_b128 v[180:183], v143 offset:2048
	ds_read_b128 v[184:187], v143 offset:3072
	ds_read_b128 v[188:191], v143 offset:4096
	ds_read_b128 v[192:195], v143 offset:5120
	ds_read_b128 v[196:199], v143 offset:6144
	ds_read_b128 v[200:203], v143 offset:7168
	global_load_lds_dwordx4 v[204:205], off
	v_lshl_add_u64 v[204:205], s[26:27], 0, v[134:135]
	s_add_i32 m0, s46, 0xe000
	s_nop 0
	global_load_lds_dwordx4 v[204:205], off
	s_waitcnt vmcnt(8)
	s_waitcnt lgkmcnt(0)
	s_barrier
	s_setprio 1
	s_waitcnt lgkmcnt(0)
	v_mfma_f32_16x16x32_bf16 v[126:129], v[136:139], v[172:175], v[126:129]
	v_mfma_f32_16x16x32_bf16 v[122:125], v[148:151], v[172:175], v[122:125]
	v_mfma_f32_16x16x32_bf16 v[110:113], v[136:139], v[180:183], v[110:113]
	v_mfma_f32_16x16x32_bf16 v[106:109], v[148:151], v[180:183], v[106:109]
	v_mfma_f32_16x16x32_bf16 v[94:97], v[136:139], v[188:191], v[94:97]
	v_mfma_f32_16x16x32_bf16 v[90:93], v[148:151], v[188:191], v[90:93]
	v_mfma_f32_16x16x32_bf16 v[78:81], v[136:139], v[196:199], v[78:81]
	v_mfma_f32_16x16x32_bf16 v[74:77], v[148:151], v[196:199], v[74:77]
	v_mfma_f32_16x16x32_bf16 v[126:129], v[144:147], v[176:179], v[126:129]
	v_mfma_f32_16x16x32_bf16 v[122:125], v[152:155], v[176:179], v[122:125]
	v_mfma_f32_16x16x32_bf16 v[110:113], v[144:147], v[184:187], v[110:113]
	v_mfma_f32_16x16x32_bf16 v[106:109], v[152:155], v[184:187], v[106:109]
	v_mfma_f32_16x16x32_bf16 v[94:97], v[144:147], v[192:195], v[94:97]
	v_mfma_f32_16x16x32_bf16 v[90:93], v[152:155], v[192:195], v[90:93]
	v_mfma_f32_16x16x32_bf16 v[78:81], v[144:147], v[200:203], v[78:81]
	v_mfma_f32_16x16x32_bf16 v[74:77], v[152:155], v[200:203], v[74:77]
	s_setprio 0
	s_setprio 1
	v_mfma_f32_16x16x32_bf16 v[118:121], v[156:159], v[172:175], v[118:121]
	v_mfma_f32_16x16x32_bf16 v[114:117], v[164:167], v[172:175], v[114:117]
	v_mfma_f32_16x16x32_bf16 v[102:105], v[156:159], v[180:183], v[102:105]
	v_mfma_f32_16x16x32_bf16 v[98:101], v[164:167], v[180:183], v[98:101]
	v_mfma_f32_16x16x32_bf16 v[86:89], v[156:159], v[188:191], v[86:89]
	v_mfma_f32_16x16x32_bf16 v[82:85], v[164:167], v[188:191], v[82:85]
	v_mfma_f32_16x16x32_bf16 v[70:73], v[156:159], v[196:199], v[70:73]
	v_mfma_f32_16x16x32_bf16 v[66:69], v[164:167], v[196:199], v[66:69]
	v_mfma_f32_16x16x32_bf16 v[118:121], v[160:163], v[176:179], v[118:121]
	v_mfma_f32_16x16x32_bf16 v[114:117], v[168:171], v[176:179], v[114:117]
	v_mfma_f32_16x16x32_bf16 v[102:105], v[160:163], v[184:187], v[102:105]
	v_mfma_f32_16x16x32_bf16 v[98:101], v[168:171], v[184:187], v[98:101]
	v_mfma_f32_16x16x32_bf16 v[86:89], v[160:163], v[192:195], v[86:89]
	v_mfma_f32_16x16x32_bf16 v[82:85], v[168:171], v[192:195], v[82:85]
	v_mfma_f32_16x16x32_bf16 v[70:73], v[160:163], v[200:203], v[70:73]
	v_mfma_f32_16x16x32_bf16 v[66:69], v[168:171], v[200:203], v[66:69]
	s_setprio 0
	s_barrier
	s_add_i32 s28, s29, s43
	v_lshl_add_u64 v[204:205], s[30:31], 0, v[0:1]
	s_mov_b32 m0, s28
	ds_read_b128 v[172:175], v143 offset:16384
	ds_read_b128 v[176:179], v143 offset:17408
	ds_read_b128 v[180:183], v143 offset:18432
	ds_read_b128 v[184:187], v143 offset:19456
	ds_read_b128 v[188:191], v143 offset:20480
	ds_read_b128 v[192:195], v143 offset:21504
	ds_read_b128 v[196:199], v143 offset:22528
	ds_read_b128 v[200:203], v143 offset:23552
	global_load_lds_dwordx4 v[204:205], off
	s_add_i32 m0, s28, 0x2000
	s_add_u32 s28, s30, 0x80000
	v_lshl_add_u64 v[206:207], s[30:31], 0, v[130:131]
	s_addc_u32 s29, s31, 0
	s_add_i32 s23, s23, s43
	global_load_lds_dwordx4 v[206:207], off
	v_lshl_add_u64 v[208:209], s[28:29], 0, v[0:1]
	s_mov_b32 m0, s23
	v_lshl_add_u64 v[210:211], s[36:37], 0, v[130:131]
	global_load_lds_dwordx4 v[208:209], off
	v_lshl_add_u64 v[208:209], s[28:29], 0, v[130:131]
	s_add_i32 m0, s23, 0x2000
	s_nop 0
	global_load_lds_dwordx4 v[208:209], off
	v_lshl_add_u64 v[208:209], s[36:37], 0, v[0:1]
	s_mov_b32 m0, s46
	s_nop 0
	global_load_lds_dwordx4 v[208:209], off
	s_mov_b32 m0, s47
	s_nop 0
	global_load_lds_dwordx4 v[210:211], off
	s_waitcnt vmcnt(8)
	s_waitcnt lgkmcnt(0)
	s_barrier
; #define PG8_STAGE(bufoff, gbase, voff) do { _Pragma("unroll") for (int _i = 0; _i < 2; ++_i) \
;         __builtin_amdgcn_global_load_lds((const unsigned*)((const char*)(gbase) + (voff)[_i]), (LAS unsigned*)(lds + (bufoff) + ldsw + _i * 8192), 16, 0, 0); } while (0)
; #define PG8_LDA(dst, b, h) do { _Pragma("unroll") for (int m = 0; m < 4; ++m) _Pragma("unroll") for (int k = 0; k < 2; ++k) dst[m][k] = *(const LAS bf16x8*)(lds + PG8_SA(b, h) + aoff + m * 2048 + k * 1024); } while (0)
; #define PG8_LDB(dst, b, h) do { _Pragma("unroll") for (int n = 0; n < 2; ++n) _Pragma("unroll") for (int k = 0; k < 2; ++k) dst[n][k] = *(const LAS bf16x8*)(lds + PG8_SB(b, h) + boff + n * 2048 + k * 1024); } while (0)
; #define PG8_MMA(ai, bj, At, Bt) do { __builtin_amdgcn_s_setprio(1); _Pragma("unroll") for (int m = 0; m < 4; ++m) _Pragma("unroll") for (int n = 0; n < 2; ++n) _Pragma("unroll") for (int k = 0; k < 2; ++k) \
;         acc[ai][bj][m][n] = __builtin_amdgcn_mfma_f32_16x16x32_bf16(Bt[n][k], At[m][k], acc[ai][bj][m][n], 0, 0, 0); __builtin_amdgcn_s_setprio(0); } while (0)
; #define PG8_WAIT_V(n) asm volatile("s_waitcnt vmcnt(" #n ")" ::: "memory")
; #define PG8_WAIT_L(n) asm volatile("s_waitcnt lgkmcnt(" #n ")" ::: "memory")
; #define PG8_BAR __builtin_amdgcn_s_barrier()
; #define PG8_SCHED __builtin_amdgcn_sched_barrier(0)
; template <class Epi, class Sched, bool ALIGN_EPI, bool LAST_FUSED = false, bool PERM = false, bool CARRY = false>
; __device__ __forceinline__ void gemm_phase(LAS unsigned char* lds, const int tid, const int K, const int lda, const int ldb, const Sched& S, const Epi& E) {
;     ...
;             PG8_WAIT_V(8); PG8_WAIT_L(0); PG8_BAR; PG8_MMA(1, 0, At, B0); PG8_MMA(1, 1, At, B1); PG8_BAR; PG8_SCHED;
;             PG8_LDB(B0, 1, 0); PG8_LDB(B1, 1, 1); PG8_SCHED; PG8_LDA(At, 1, 0); PG8_STAGE(PG8_SA(0, 1), a2 + hstepA, voffA);
;             PG8_WAIT_V(8); PG8_WAIT_L(0); PG8_BAR; PG8_MMA(0, 0, At, B0); PG8_MMA(0, 1, At, B1); PG8_BAR; PG8_SCHED;
	s_setprio 1
	s_waitcnt lgkmcnt(0)
	v_mfma_f32_16x16x32_bf16 v[62:65], v[136:139], v[172:175], v[62:65]
	v_mfma_f32_16x16x32_bf16 v[58:61], v[148:151], v[172:175], v[58:61]
	v_mfma_f32_16x16x32_bf16 v[46:49], v[136:139], v[180:183], v[46:49]
	v_mfma_f32_16x16x32_bf16 v[42:45], v[148:151], v[180:183], v[42:45]
	v_mfma_f32_16x16x32_bf16 v[30:33], v[136:139], v[188:191], v[30:33]
	v_mfma_f32_16x16x32_bf16 v[26:29], v[148:151], v[188:191], v[26:29]
	v_mfma_f32_16x16x32_bf16 v[14:17], v[136:139], v[196:199], v[14:17]
	v_mfma_f32_16x16x32_bf16 v[10:13], v[148:151], v[196:199], v[10:13]
	v_mfma_f32_16x16x32_bf16 v[62:65], v[144:147], v[176:179], v[62:65]
	v_mfma_f32_16x16x32_bf16 v[58:61], v[152:155], v[176:179], v[58:61]
	v_mfma_f32_16x16x32_bf16 v[46:49], v[144:147], v[184:187], v[46:49]
	v_mfma_f32_16x16x32_bf16 v[42:45], v[152:155], v[184:187], v[42:45]
	v_mfma_f32_16x16x32_bf16 v[30:33], v[144:147], v[192:195], v[30:33]
	v_mfma_f32_16x16x32_bf16 v[26:29], v[152:155], v[192:195], v[26:29]
	v_mfma_f32_16x16x32_bf16 v[14:17], v[144:147], v[200:203], v[14:17]
	v_mfma_f32_16x16x32_bf16 v[10:13], v[152:155], v[200:203], v[10:13]
	s_setprio 0
	s_setprio 1
	v_mfma_f32_16x16x32_bf16 v[54:57], v[156:159], v[172:175], v[54:57]
	v_mfma_f32_16x16x32_bf16 v[50:53], v[164:167], v[172:175], v[50:53]
	v_mfma_f32_16x16x32_bf16 v[38:41], v[156:159], v[180:183], v[38:41]
	v_mfma_f32_16x16x32_bf16 v[34:37], v[164:167], v[180:183], v[34:37]
	v_mfma_f32_16x16x32_bf16 v[22:25], v[156:159], v[188:191], v[22:25]
	v_mfma_f32_16x16x32_bf16 v[18:21], v[164:167], v[188:191], v[18:21]
	v_mfma_f32_16x16x32_bf16 v[6:9], v[156:159], v[196:199], v[6:9]
	v_mfma_f32_16x16x32_bf16 v[2:5], v[164:167], v[196:199], v[2:5]
	v_mfma_f32_16x16x32_bf16 v[54:57], v[160:163], v[176:179], v[54:57]
	v_mfma_f32_16x16x32_bf16 v[50:53], v[168:171], v[176:179], v[50:53]
	v_mfma_f32_16x16x32_bf16 v[38:41], v[160:163], v[184:187], v[38:41]
	v_mfma_f32_16x16x32_bf16 v[34:37], v[168:171], v[184:187], v[34:37]
	v_mfma_f32_16x16x32_bf16 v[22:25], v[160:163], v[192:195], v[22:25]
	v_mfma_f32_16x16x32_bf16 v[18:21], v[168:171], v[192:195], v[18:21]
	v_mfma_f32_16x16x32_bf16 v[6:9], v[160:163], v[200:203], v[6:9]
	v_mfma_f32_16x16x32_bf16 v[2:5], v[168:171], v[200:203], v[2:5]
	s_setprio 0
	s_barrier
	s_add_i32 s23, 0, 0x18000
	s_add_i32 s35, 0, 0x1c000
	v_add_u32_e32 v152, s23, v142
	v_add_u32_e32 v168, s35, v142
	ds_read_b128 v[136:139], v152
	ds_read_b128 v[144:147], v152 offset:1024
	ds_read_b128 v[148:151], v152 offset:2048
	ds_read_b128 v[152:155], v152 offset:3072
	ds_read_b128 v[156:159], v168
	ds_read_b128 v[160:163], v168 offset:1024
	ds_read_b128 v[164:167], v168 offset:2048
	ds_read_b128 v[168:171], v168 offset:3072
	s_add_u32 s28, s36, 0x80000
	s_addc_u32 s29, s37, 0
	s_mov_b32 m0, s48
	v_lshl_add_u64 v[212:213], s[28:29], 0, v[0:1]
	ds_read_b128 v[172:175], v143 offset:32768
	ds_read_b128 v[176:179], v143 offset:33792
	ds_read_b128 v[180:183], v143 offset:34816
	ds_read_b128 v[184:187], v143 offset:35840
	ds_read_b128 v[188:191], v143 offset:36864
	ds_read_b128 v[192:195], v143 offset:37888
	ds_read_b128 v[196:199], v143 offset:38912
	ds_read_b128 v[200:203], v143 offset:39936
	global_load_lds_dwordx4 v[212:213], off
	v_lshl_add_u64 v[212:213], s[28:29], 0, v[130:131]
	s_mov_b32 m0, s49
	s_nop 0
	global_load_lds_dwordx4 v[212:213], off
	s_waitcnt vmcnt(8)
	s_waitcnt lgkmcnt(0)
	s_barrier
	s_setprio 1
	s_waitcnt lgkmcnt(0)
	v_mfma_f32_16x16x32_bf16 v[126:129], v[136:139], v[172:175], v[126:129]
	v_mfma_f32_16x16x32_bf16 v[122:125], v[148:151], v[172:175], v[122:125]
	v_mfma_f32_16x16x32_bf16 v[110:113], v[136:139], v[180:183], v[110:113]
	v_mfma_f32_16x16x32_bf16 v[106:109], v[148:151], v[180:183], v[106:109]
	v_mfma_f32_16x16x32_bf16 v[94:97], v[136:139], v[188:191], v[94:97]
	v_mfma_f32_16x16x32_bf16 v[90:93], v[148:151], v[188:191], v[90:93]
	v_mfma_f32_16x16x32_bf16 v[78:81], v[136:139], v[196:199], v[78:81]
	v_mfma_f32_16x16x32_bf16 v[74:77], v[148:151], v[196:199], v[74:77]
	v_mfma_f32_16x16x32_bf16 v[126:129], v[144:147], v[176:179], v[126:129]
	v_mfma_f32_16x16x32_bf16 v[122:125], v[152:155], v[176:179], v[122:125]
	v_mfma_f32_16x16x32_bf16 v[110:113], v[144:147], v[184:187], v[110:113]
	v_mfma_f32_16x16x32_bf16 v[106:109], v[152:155], v[184:187], v[106:109]
	v_mfma_f32_16x16x32_bf16 v[94:97], v[144:147], v[192:195], v[94:97]
	v_mfma_f32_16x16x32_bf16 v[90:93], v[152:155], v[192:195], v[90:93]
	v_mfma_f32_16x16x32_bf16 v[78:81], v[144:147], v[200:203], v[78:81]
	v_mfma_f32_16x16x32_bf16 v[74:77], v[152:155], v[200:203], v[74:77]
	s_setprio 0
	s_setprio 1
	v_mfma_f32_16x16x32_bf16 v[118:121], v[156:159], v[172:175], v[118:121]
	v_mfma_f32_16x16x32_bf16 v[114:117], v[164:167], v[172:175], v[114:117]
	v_mfma_f32_16x16x32_bf16 v[102:105], v[156:159], v[180:183], v[102:105]
	v_mfma_f32_16x16x32_bf16 v[98:101], v[164:167], v[180:183], v[98:101]
	v_mfma_f32_16x16x32_bf16 v[86:89], v[156:159], v[188:191], v[86:89]
	v_mfma_f32_16x16x32_bf16 v[82:85], v[164:167], v[188:191], v[82:85]
	v_mfma_f32_16x16x32_bf16 v[70:73], v[156:159], v[196:199], v[70:73]
	v_mfma_f32_16x16x32_bf16 v[66:69], v[164:167], v[196:199], v[66:69]
	v_mfma_f32_16x16x32_bf16 v[118:121], v[160:163], v[176:179], v[118:121]
	v_mfma_f32_16x16x32_bf16 v[114:117], v[168:171], v[176:179], v[114:117]
	v_mfma_f32_16x16x32_bf16 v[102:105], v[160:163], v[184:187], v[102:105]
	v_mfma_f32_16x16x32_bf16 v[98:101], v[168:171], v[184:187], v[98:101]
	v_mfma_f32_16x16x32_bf16 v[86:89], v[160:163], v[192:195], v[86:89]
	v_mfma_f32_16x16x32_bf16 v[82:85], v[168:171], v[192:195], v[82:85]
	v_mfma_f32_16x16x32_bf16 v[70:73], v[160:163], v[200:203], v[70:73]
	v_mfma_f32_16x16x32_bf16 v[66:69], v[168:171], v[200:203], v[66:69]
	s_setprio 0
	s_barrier
; #define PG8_STAGE(bufoff, gbase, voff) do { _Pragma("unroll") for (int _i = 0; _i < 2; ++_i) \
;         __builtin_amdgcn_global_load_lds((const unsigned*)((const char*)(gbase) + (voff)[_i]), (LAS unsigned*)(lds + (bufoff) + ldsw + _i * 8192), 16, 0, 0); } while (0)
; #define PG8_LDA(dst, b, h) do { _Pragma("unroll") for (int m = 0; m < 4; ++m) _Pragma("unroll") for (int k = 0; k < 2; ++k) dst[m][k] = *(const LAS bf16x8*)(lds + PG8_SA(b, h) + aoff + m * 2048 + k * 1024); } while (0)
; #define PG8_LDB(dst, b, h) do { _Pragma("unroll") for (int n = 0; n < 2; ++n) _Pragma("unroll") for (int k = 0; k < 2; ++k) dst[n][k] = *(const LAS bf16x8*)(lds + PG8_SB(b, h) + boff + n * 2048 + k * 1024); } while (0)
; template <class Epi, class Sched, bool ALIGN_EPI, bool LAST_FUSED = false, bool PERM = false, bool CARRY = false>
; __device__ __forceinline__ void gemm_phase(LAS unsigned char* lds, const int tid, const int K, const int lda, const int ldb, const Sched& S, const Epi& E) {
;     ...
;         for (int t = 0; t < nt; t += 2) {
;             const bool last = (t == nt - 2);
;             const char* a1 = cA + (size_t)(t + 1) * kstep;
;             const char* a2 = last ? nA : cA + (size_t)(t + 2) * kstep; const char* b2 = last ? nB : cB + (size_t)(t + 2) * kstep;
;             const char* a3 = a2 + kstep; const char* b3 = b2 + kstep;
;             PG8_LDB(B0, 0, 0); PG8_LDB(B1, 0, 1); PG8_SCHED; PG8_LDA(At, 0, 0); PG8_STAGE(PG8_SA(1, 1), a1 + hstepA, voffA);
;             PG8_WAIT_V(8); PG8_WAIT_L(0); PG8_BAR; PG8_MMA(0, 0, At, B0); PG8_MMA(0, 1, At, B1); PG8_BAR; PG8_SCHED;
;             PG8_LDA(At, 0, 1); PG8_STAGE(PG8_SB(0, 0), b2, voffB); PG8_STAGE(PG8_SB(0, 1), b2 + hstepB, voffB); PG8_STAGE(PG8_SA(0, 0), a2, voffA);
;             PG8_WAIT_V(8); PG8_WAIT_L(0); PG8_BAR; PG8_MMA(1, 0, At, B0); PG8_MMA(1, 1, At, B1); PG8_BAR; PG8_SCHED;
;             PG8_LDB(B0, 1, 0); PG8_LDB(B1, 1, 1); PG8_SCHED; PG8_LDA(At, 1, 0); PG8_STAGE(PG8_SA(0, 1), a2 + hstepA, voffA);
;             PG8_WAIT_V(8); PG8_WAIT_L(0); PG8_BAR; PG8_MMA(0, 0, At, B0); PG8_MMA(0, 1, At, B1); PG8_BAR; PG8_SCHED;
;             PG8_LDA(At, 1, 1); PG8_STAGE(PG8_SB(1, 0), b3, voffB); PG8_STAGE(PG8_SB(1, 1), b3 + hstepB, voffB); PG8_STAGE(PG8_SA(1, 0), a3, voffA);
;             PG8_WAIT_V(8); PG8_WAIT_L(0); PG8_BAR; PG8_MMA(1, 0, At, B0); PG8_MMA(1, 1, At, B1); PG8_BAR; PG8_SCHED;
	s_add_i32 s23, s23, s43
	v_lshl_add_u64 v[204:205], v[204:205], 0, s[68:69]
	s_mov_b32 m0, s23
	ds_read_b128 v[172:175], v143 offset:49152
	ds_read_b128 v[176:179], v143 offset:50176
	ds_read_b128 v[180:183], v143 offset:51200
	ds_read_b128 v[184:187], v143 offset:52224
	ds_read_b128 v[188:191], v143 offset:53248
	ds_read_b128 v[192:195], v143 offset:54272
	ds_read_b128 v[196:199], v143 offset:55296
	ds_read_b128 v[200:203], v143 offset:56320
	global_load_lds_dwordx4 v[204:205], off
	s_add_i32 m0, s23, 0x2000
	s_add_u32 s28, s30, 0x80080
	v_lshl_add_u64 v[204:205], v[206:207], 0, s[68:69]
	s_addc_u32 s29, s31, 0
	s_add_i32 s23, s35, s43
	global_load_lds_dwordx4 v[204:205], off
	v_lshl_add_u64 v[204:205], s[28:29], 0, v[0:1]
	s_mov_b32 m0, s23
	s_nop 0
	global_load_lds_dwordx4 v[204:205], off
	v_lshl_add_u64 v[204:205], s[28:29], 0, v[130:131]
	s_add_i32 m0, s23, 0x2000
	s_nop 0
	global_load_lds_dwordx4 v[204:205], off
	v_lshl_add_u64 v[204:205], v[208:209], 0, s[68:69]
	s_mov_b32 m0, s51
	s_nop 0
	global_load_lds_dwordx4 v[204:205], off
	v_lshl_add_u64 v[204:205], v[210:211], 0, s[68:69]
	s_mov_b32 m0, s52
	s_nop 0
	global_load_lds_dwordx4 v[204:205], off
	s_waitcnt vmcnt(8)
	s_waitcnt lgkmcnt(0)
	s_barrier
	s_setprio 1
	s_waitcnt lgkmcnt(0)
	v_mfma_f32_16x16x32_bf16 v[62:65], v[136:139], v[172:175], v[62:65]
	v_mfma_f32_16x16x32_bf16 v[58:61], v[148:151], v[172:175], v[58:61]
	v_mfma_f32_16x16x32_bf16 v[46:49], v[136:139], v[180:183], v[46:49]
	v_mfma_f32_16x16x32_bf16 v[42:45], v[148:151], v[180:183], v[42:45]
	v_mfma_f32_16x16x32_bf16 v[30:33], v[136:139], v[188:191], v[30:33]
	v_mfma_f32_16x16x32_bf16 v[26:29], v[148:151], v[188:191], v[26:29]
	v_mfma_f32_16x16x32_bf16 v[14:17], v[136:139], v[196:199], v[14:17]
	v_mfma_f32_16x16x32_bf16 v[10:13], v[148:151], v[196:199], v[10:13]
	v_mfma_f32_16x16x32_bf16 v[62:65], v[144:147], v[176:179], v[62:65]
	v_mfma_f32_16x16x32_bf16 v[58:61], v[152:155], v[176:179], v[58:61]
	v_mfma_f32_16x16x32_bf16 v[46:49], v[144:147], v[184:187], v[46:49]
	v_mfma_f32_16x16x32_bf16 v[42:45], v[152:155], v[184:187], v[42:45]
	v_mfma_f32_16x16x32_bf16 v[30:33], v[144:147], v[192:195], v[30:33]
	v_mfma_f32_16x16x32_bf16 v[26:29], v[152:155], v[192:195], v[26:29]
	v_mfma_f32_16x16x32_bf16 v[14:17], v[144:147], v[200:203], v[14:17]
	v_mfma_f32_16x16x32_bf16 v[10:13], v[152:155], v[200:203], v[10:13]
	s_setprio 0
	s_setprio 1
	v_mfma_f32_16x16x32_bf16 v[54:57], v[156:159], v[172:175], v[54:57]
	v_mfma_f32_16x16x32_bf16 v[50:53], v[164:167], v[172:175], v[50:53]
	v_mfma_f32_16x16x32_bf16 v[38:41], v[156:159], v[180:183], v[38:41]
	v_mfma_f32_16x16x32_bf16 v[34:37], v[164:167], v[180:183], v[34:37]
	v_mfma_f32_16x16x32_bf16 v[22:25], v[156:159], v[188:191], v[22:25]
	v_mfma_f32_16x16x32_bf16 v[18:21], v[164:167], v[188:191], v[18:21]
	v_mfma_f32_16x16x32_bf16 v[6:9], v[156:159], v[196:199], v[6:9]
	v_mfma_f32_16x16x32_bf16 v[2:5], v[164:167], v[196:199], v[2:5]
	v_mfma_f32_16x16x32_bf16 v[54:57], v[160:163], v[176:179], v[54:57]
	v_mfma_f32_16x16x32_bf16 v[50:53], v[168:171], v[176:179], v[50:53]
	v_mfma_f32_16x16x32_bf16 v[38:41], v[160:163], v[184:187], v[38:41]
	v_mfma_f32_16x16x32_bf16 v[34:37], v[168:171], v[184:187], v[34:37]
	v_mfma_f32_16x16x32_bf16 v[22:25], v[160:163], v[192:195], v[22:25]
	v_mfma_f32_16x16x32_bf16 v[18:21], v[168:171], v[192:195], v[18:21]
	v_mfma_f32_16x16x32_bf16 v[6:9], v[160:163], v[200:203], v[6:9]
	v_mfma_f32_16x16x32_bf16 v[2:5], v[168:171], v[200:203], v[2:5]
	s_add_i32 s15, s15, 2
	s_add_u32 s26, s26, 0x100
	s_addc_u32 s27, s27, 0
	s_add_u32 s5, s5, 0x100
	s_addc_u32 s13, s13, 0
	s_cmp_gt_u32 s15, 29
	s_setprio 0
	s_barrier
	s_cbranch_scc0 .LBB0_1077
	s_and_b64 vcc, exec, s[10:11]
	s_cbranch_vccz .LBB0_1080
	s_barrier

; #define PG8_STAGE(bufoff, gbase, voff) do { _Pragma("unroll") for (int _i = 0; _i < 2; ++_i) \
;         __builtin_amdgcn_global_load_lds((const unsigned*)((const char*)(gbase) + (voff)[_i]), (LAS unsigned*)(lds + (bufoff) + ldsw + _i * 8192), 16, 0, 0); } while (0)
; #define PG8_LDA(dst, b, h) do { _Pragma("unroll") for (int m = 0; m < 4; ++m) _Pragma("unroll") for (int k = 0; k < 2; ++k) dst[m][k] = *(const LAS bf16x8*)(lds + PG8_SA(b, h) + aoff + m * 2048 + k * 1024); } while (0)
; #define PG8_LDB(dst, b, h) do { _Pragma("unroll") for (int n = 0; n < 2; ++n) _Pragma("unroll") for (int k = 0; k < 2; ++k) dst[n][k] = *(const LAS bf16x8*)(lds + PG8_SB(b, h) + boff + n * 2048 + k * 1024); } while (0)
; #define PG8_MMA(ai, bj, At, Bt) do { __builtin_amdgcn_s_setprio(1); _Pragma("unroll") for (int m = 0; m < 4; ++m) _Pragma("unroll") for (int n = 0; n < 2; ++n) _Pragma("unroll") for (int k = 0; k < 2; ++k) \
;         acc[ai][bj][m][n] = __builtin_amdgcn_mfma_f32_16x16x32_bf16(Bt[n][k], At[m][k], acc[ai][bj][m][n], 0, 0, 0); __builtin_amdgcn_s_setprio(0); } while (0)
; #define PG8_WAIT_V(n) asm volatile("s_waitcnt vmcnt(" #n ")" ::: "memory")
; #define PG8_WAIT_L(n) asm volatile("s_waitcnt lgkmcnt(" #n ")" ::: "memory")
; template <class Epi, class Sched, bool ALIGN_EPI, bool LAST_FUSED = false, bool PERM = false, bool CARRY = false>
; __device__ __forceinline__ void gemm_phase(LAS unsigned char* lds, const int tid, const int K, const int lda, const int ldb, const Sched& S, const Epi& E) {
;     ...
;         for (int t = 0; t < nt; t += 2) {
;             const bool last = (t == nt - 2);
;             const char* a1 = cA + (size_t)(t + 1) * kstep;
;             const char* a2 = last ? nA : cA + (size_t)(t + 2) * kstep; const char* b2 = last ? nB : cB + (size_t)(t + 2) * kstep;
;             const char* a3 = a2 + kstep; const char* b3 = b2 + kstep;
;             PG8_LDB(B0, 0, 0); PG8_LDB(B1, 0, 1); PG8_SCHED; PG8_LDA(At, 0, 0); PG8_STAGE(PG8_SA(1, 1), a1 + hstepA, voffA);
;             PG8_WAIT_V(8); PG8_WAIT_L(0); PG8_BAR; PG8_MMA(0, 0, At, B0); PG8_MMA(0, 1, At, B1); PG8_BAR; PG8_SCHED;
;             PG8_LDA(At, 0, 1); PG8_STAGE(PG8_SB(0, 0), b2, voffB); PG8_STAGE(PG8_SB(0, 1), b2 + hstepB, voffB); PG8_STAGE(PG8_SA(0, 0), a2, voffA);
;             PG8_WAIT_V(8); PG8_WAIT_L(0); PG8_BAR; PG8_MMA(1, 0, At, B0); PG8_MMA(1, 1, At, B1); PG8_BAR; PG8_SCHED;
.LBB0_1585:
	s_add_u32 s52, s42, s48
	s_addc_u32 s53, s43, s49
	s_add_u32 s76, s40, s48
	s_addc_u32 s77, s41, s49
	s_add_i32 s96, 0, 0x10000
	s_cmp_eq_u32 s3, s95
	s_cselect_b32 s53, s24, s53
	s_cselect_b32 s52, s55, s52
	s_cselect_b32 s77, s93, s77
	s_cselect_b32 s76, s94, s76
	s_add_i32 vcc_lo, 0, 0x14000
	v_add_u32_e32 v156, s96, v140
	v_add_u32_e32 v172, vcc_lo, v140
	ds_read_b128 v[142:145], v156
	ds_read_b128 v[146:149], v156 offset:1024
	ds_read_b128 v[150:153], v156 offset:2048
	ds_read_b128 v[156:159], v156 offset:3072
	ds_read_b128 v[160:163], v172
	ds_read_b128 v[164:167], v172 offset:1024
	ds_read_b128 v[168:171], v172 offset:2048
	ds_read_b128 v[172:175], v172 offset:3072
	v_lshl_add_u64 v[208:209], s[42:43], 0, v[138:139]
	s_add_i32 m0, s35, 0xc000
	ds_read_b128 v[176:179], v141
	ds_read_b128 v[180:183], v141 offset:1024
	ds_read_b128 v[184:187], v141 offset:2048
	ds_read_b128 v[188:191], v141 offset:3072
	ds_read_b128 v[192:195], v141 offset:4096
	ds_read_b128 v[196:199], v141 offset:5120
	ds_read_b128 v[200:203], v141 offset:6144
	ds_read_b128 v[204:207], v141 offset:7168
	global_load_lds_dwordx4 v[208:209], off
	v_lshl_add_u64 v[208:209], s[42:43], 0, v[128:129]
	s_add_i32 m0, s35, 0xe000
	s_nop 0
	global_load_lds_dwordx4 v[208:209], off
	s_waitcnt vmcnt(8)
	s_waitcnt lgkmcnt(0)
	s_barrier
	s_setprio 1
	s_waitcnt lgkmcnt(0)
	v_mfma_f32_16x16x32_bf16 v[62:65], v[142:145], v[176:179], v[62:65]
	v_mfma_f32_16x16x32_bf16 v[42:45], v[150:153], v[176:179], v[42:45]
	v_mfma_f32_16x16x32_bf16 v[18:21], v[142:145], v[184:187], v[18:21]
	v_mfma_f32_16x16x32_bf16 v[14:17], v[150:153], v[184:187], v[14:17]
	v_mfma_f32_16x16x32_bf16 v[38:41], v[142:145], v[192:195], v[38:41]
	v_mfma_f32_16x16x32_bf16 v[30:33], v[150:153], v[192:195], v[30:33]
	v_mfma_f32_16x16x32_bf16 v[58:61], v[142:145], v[200:203], v[58:61]
	v_mfma_f32_16x16x32_bf16 v[54:57], v[150:153], v[200:203], v[54:57]
	v_mfma_f32_16x16x32_bf16 v[62:65], v[146:149], v[180:183], v[62:65]
	v_mfma_f32_16x16x32_bf16 v[42:45], v[156:159], v[180:183], v[42:45]
	v_mfma_f32_16x16x32_bf16 v[18:21], v[146:149], v[188:191], v[18:21]
	v_mfma_f32_16x16x32_bf16 v[14:17], v[156:159], v[188:191], v[14:17]
	v_mfma_f32_16x16x32_bf16 v[38:41], v[146:149], v[196:199], v[38:41]
	v_mfma_f32_16x16x32_bf16 v[30:33], v[156:159], v[196:199], v[30:33]
	v_mfma_f32_16x16x32_bf16 v[58:61], v[146:149], v[204:207], v[58:61]
	v_mfma_f32_16x16x32_bf16 v[54:57], v[156:159], v[204:207], v[54:57]
	s_setprio 0
	s_setprio 1
	v_mfma_f32_16x16x32_bf16 v[34:37], v[160:163], v[176:179], v[34:37]
	v_mfma_f32_16x16x32_bf16 v[2:5], v[168:171], v[176:179], v[2:5]
	v_mfma_f32_16x16x32_bf16 v[10:13], v[160:163], v[184:187], v[10:13]
	v_mfma_f32_16x16x32_bf16 v[6:9], v[168:171], v[184:187], v[6:9]
	v_mfma_f32_16x16x32_bf16 v[26:29], v[160:163], v[192:195], v[26:29]
	v_mfma_f32_16x16x32_bf16 v[22:25], v[168:171], v[192:195], v[22:25]
	v_mfma_f32_16x16x32_bf16 v[50:53], v[160:163], v[200:203], v[50:53]
	v_mfma_f32_16x16x32_bf16 v[46:49], v[168:171], v[200:203], v[46:49]
	v_mfma_f32_16x16x32_bf16 v[34:37], v[164:167], v[180:183], v[34:37]
	v_mfma_f32_16x16x32_bf16 v[2:5], v[172:175], v[180:183], v[2:5]
	v_mfma_f32_16x16x32_bf16 v[10:13], v[164:167], v[188:191], v[10:13]
	v_mfma_f32_16x16x32_bf16 v[6:9], v[172:175], v[188:191], v[6:9]
	v_mfma_f32_16x16x32_bf16 v[26:29], v[164:167], v[196:199], v[26:29]
	v_mfma_f32_16x16x32_bf16 v[22:25], v[172:175], v[196:199], v[22:25]
	v_mfma_f32_16x16x32_bf16 v[50:53], v[164:167], v[204:207], v[50:53]
	v_mfma_f32_16x16x32_bf16 v[46:49], v[172:175], v[204:207], v[46:49]
	s_setprio 0
	s_barrier
	s_add_i32 s96, s96, s87
	v_lshl_add_u64 v[208:209], s[76:77], 0, v[0:1]
	s_mov_b32 m0, s96
	ds_read_b128 v[176:179], v141 offset:16384
	ds_read_b128 v[180:183], v141 offset:17408
	ds_read_b128 v[184:187], v141 offset:18432
	ds_read_b128 v[188:191], v141 offset:19456
	ds_read_b128 v[192:195], v141 offset:20480
	ds_read_b128 v[196:199], v141 offset:21504
	ds_read_b128 v[200:203], v141 offset:22528
	ds_read_b128 v[204:207], v141 offset:23552
	global_load_lds_dwordx4 v[208:209], off
	s_add_i32 m0, s96, 0x2000
	s_add_u32 s96, s76, 0x80000
	v_lshl_add_u64 v[210:211], s[76:77], 0, v[122:123]
	s_addc_u32 s97, s77, 0
	s_add_i32 vcc_lo, vcc_lo, s87
	global_load_lds_dwordx4 v[210:211], off
	v_lshl_add_u64 v[212:213], s[96:97], 0, v[0:1]
	s_mov_b32 m0, vcc_lo
	v_lshl_add_u64 v[214:215], s[52:53], 0, v[122:123]
	global_load_lds_dwordx4 v[212:213], off
	v_lshl_add_u64 v[212:213], s[96:97], 0, v[122:123]
	s_add_i32 m0, vcc_lo, 0x2000
	s_nop 0
	global_load_lds_dwordx4 v[212:213], off
	v_lshl_add_u64 v[212:213], s[52:53], 0, v[0:1]
	s_mov_b32 m0, s35
	s_nop 0
	global_load_lds_dwordx4 v[212:213], off
	s_mov_b32 m0, s28
	s_nop 0
	global_load_lds_dwordx4 v[214:215], off
	s_waitcnt vmcnt(8)
	s_waitcnt lgkmcnt(0)
	s_barrier
; #define PG8_STAGE(bufoff, gbase, voff) do { _Pragma("unroll") for (int _i = 0; _i < 2; ++_i) \
;         __builtin_amdgcn_global_load_lds((const unsigned*)((const char*)(gbase) + (voff)[_i]), (LAS unsigned*)(lds + (bufoff) + ldsw + _i * 8192), 16, 0, 0); } while (0)
; #define PG8_LDA(dst, b, h) do { _Pragma("unroll") for (int m = 0; m < 4; ++m) _Pragma("unroll") for (int k = 0; k < 2; ++k) dst[m][k] = *(const LAS bf16x8*)(lds + PG8_SA(b, h) + aoff + m * 2048 + k * 1024); } while (0)
; #define PG8_LDB(dst, b, h) do { _Pragma("unroll") for (int n = 0; n < 2; ++n) _Pragma("unroll") for (int k = 0; k < 2; ++k) dst[n][k] = *(const LAS bf16x8*)(lds + PG8_SB(b, h) + boff + n * 2048 + k * 1024); } while (0)
; #define PG8_MMA(ai, bj, At, Bt) do { __builtin_amdgcn_s_setprio(1); _Pragma("unroll") for (int m = 0; m < 4; ++m) _Pragma("unroll") for (int n = 0; n < 2; ++n) _Pragma("unroll") for (int k = 0; k < 2; ++k) \
;         acc[ai][bj][m][n] = __builtin_amdgcn_mfma_f32_16x16x32_bf16(Bt[n][k], At[m][k], acc[ai][bj][m][n], 0, 0, 0); __builtin_amdgcn_s_setprio(0); } while (0)
; #define PG8_WAIT_V(n) asm volatile("s_waitcnt vmcnt(" #n ")" ::: "memory")
; #define PG8_WAIT_L(n) asm volatile("s_waitcnt lgkmcnt(" #n ")" ::: "memory")
; #define PG8_BAR __builtin_amdgcn_s_barrier()
; #define PG8_SCHED __builtin_amdgcn_sched_barrier(0)
; template <class Epi, class Sched, bool ALIGN_EPI, bool LAST_FUSED = false, bool PERM = false, bool CARRY = false>
; __device__ __forceinline__ void gemm_phase(LAS unsigned char* lds, const int tid, const int K, const int lda, const int ldb, const Sched& S, const Epi& E) {
;     ...
;             PG8_WAIT_V(8); PG8_WAIT_L(0); PG8_BAR; PG8_MMA(1, 0, At, B0); PG8_MMA(1, 1, At, B1); PG8_BAR; PG8_SCHED;
;             PG8_LDB(B0, 1, 0); PG8_LDB(B1, 1, 1); PG8_SCHED; PG8_LDA(At, 1, 0); PG8_STAGE(PG8_SA(0, 1), a2 + hstepA, voffA);
;             PG8_WAIT_V(8); PG8_WAIT_L(0); PG8_BAR; PG8_MMA(0, 0, At, B0); PG8_MMA(0, 1, At, B1); PG8_BAR; PG8_SCHED;
	s_setprio 1
	s_waitcnt lgkmcnt(0)
	v_mfma_f32_16x16x32_bf16 v[78:81], v[142:145], v[176:179], v[78:81]
	v_mfma_f32_16x16x32_bf16 v[74:77], v[150:153], v[176:179], v[74:77]
	v_mfma_f32_16x16x32_bf16 v[98:101], v[142:145], v[184:187], v[98:101]
	v_mfma_f32_16x16x32_bf16 v[94:97], v[150:153], v[184:187], v[94:97]
	v_mfma_f32_16x16x32_bf16 v[118:121], v[142:145], v[192:195], v[118:121]
	v_mfma_f32_16x16x32_bf16 v[114:117], v[150:153], v[192:195], v[114:117]
	v_mfma_f32_16x16x32_bf16 v[134:137], v[142:145], v[200:203], v[134:137]
	v_mfma_f32_16x16x32_bf16 v[130:133], v[150:153], v[200:203], v[130:133]
	v_mfma_f32_16x16x32_bf16 v[78:81], v[146:149], v[180:183], v[78:81]
	v_mfma_f32_16x16x32_bf16 v[74:77], v[156:159], v[180:183], v[74:77]
	v_mfma_f32_16x16x32_bf16 v[98:101], v[146:149], v[188:191], v[98:101]
	v_mfma_f32_16x16x32_bf16 v[94:97], v[156:159], v[188:191], v[94:97]
	v_mfma_f32_16x16x32_bf16 v[118:121], v[146:149], v[196:199], v[118:121]
	v_mfma_f32_16x16x32_bf16 v[114:117], v[156:159], v[196:199], v[114:117]
	v_mfma_f32_16x16x32_bf16 v[134:137], v[146:149], v[204:207], v[134:137]
	v_mfma_f32_16x16x32_bf16 v[130:133], v[156:159], v[204:207], v[130:133]
	s_setprio 0
	s_setprio 1
	v_mfma_f32_16x16x32_bf16 v[70:73], v[160:163], v[176:179], v[70:73]
	v_mfma_f32_16x16x32_bf16 v[66:69], v[168:171], v[176:179], v[66:69]
	v_mfma_f32_16x16x32_bf16 v[90:93], v[160:163], v[184:187], v[90:93]
	v_mfma_f32_16x16x32_bf16 v[86:89], v[168:171], v[184:187], v[86:89]
	v_mfma_f32_16x16x32_bf16 v[110:113], v[160:163], v[192:195], v[110:113]
	v_mfma_f32_16x16x32_bf16 v[106:109], v[168:171], v[192:195], v[106:109]
	v_mfma_f32_16x16x32_bf16 v[102:105], v[160:163], v[200:203], v[102:105]
	v_mfma_f32_16x16x32_bf16 v[82:85], v[168:171], v[200:203], v[82:85]
	v_mfma_f32_16x16x32_bf16 v[70:73], v[164:167], v[180:183], v[70:73]
	v_mfma_f32_16x16x32_bf16 v[66:69], v[172:175], v[180:183], v[66:69]
	v_mfma_f32_16x16x32_bf16 v[90:93], v[164:167], v[188:191], v[90:93]
	v_mfma_f32_16x16x32_bf16 v[86:89], v[172:175], v[188:191], v[86:89]
	v_mfma_f32_16x16x32_bf16 v[110:113], v[164:167], v[196:199], v[110:113]
	v_mfma_f32_16x16x32_bf16 v[106:109], v[172:175], v[196:199], v[106:109]
	v_mfma_f32_16x16x32_bf16 v[102:105], v[164:167], v[204:207], v[102:105]
	v_mfma_f32_16x16x32_bf16 v[82:85], v[172:175], v[204:207], v[82:85]
	s_setprio 0
	s_barrier
	s_add_i32 s96, 0, 0x18000
	s_add_i32 s97, 0, 0x1c000
	v_add_u32_e32 v156, s96, v140
	v_add_u32_e32 v172, s97, v140
	ds_read_b128 v[142:145], v156
	ds_read_b128 v[146:149], v156 offset:1024
	ds_read_b128 v[150:153], v156 offset:2048
	ds_read_b128 v[156:159], v156 offset:3072
	ds_read_b128 v[160:163], v172
	ds_read_b128 v[164:167], v172 offset:1024
	ds_read_b128 v[168:171], v172 offset:2048
	ds_read_b128 v[172:175], v172 offset:3072
	s_add_u32 s52, s52, 0x80000
	s_addc_u32 s53, s53, 0
	s_mov_b32 m0, s29
	v_lshl_add_u64 v[216:217], s[52:53], 0, v[0:1]
	ds_read_b128 v[176:179], v141 offset:32768
	ds_read_b128 v[180:183], v141 offset:33792
	ds_read_b128 v[184:187], v141 offset:34816
	ds_read_b128 v[188:191], v141 offset:35840
	ds_read_b128 v[192:195], v141 offset:36864
	ds_read_b128 v[196:199], v141 offset:37888
	ds_read_b128 v[200:203], v141 offset:38912
	ds_read_b128 v[204:207], v141 offset:39936
	global_load_lds_dwordx4 v[216:217], off
	v_lshl_add_u64 v[216:217], s[52:53], 0, v[122:123]
	s_mov_b32 m0, s14
	s_nop 0
	global_load_lds_dwordx4 v[216:217], off
	s_waitcnt vmcnt(8)
	s_waitcnt lgkmcnt(0)
	s_barrier
	s_setprio 1
	s_waitcnt lgkmcnt(0)
	v_mfma_f32_16x16x32_bf16 v[62:65], v[142:145], v[176:179], v[62:65]
	v_mfma_f32_16x16x32_bf16 v[42:45], v[150:153], v[176:179], v[42:45]
	v_mfma_f32_16x16x32_bf16 v[18:21], v[142:145], v[184:187], v[18:21]
	v_mfma_f32_16x16x32_bf16 v[14:17], v[150:153], v[184:187], v[14:17]
	v_mfma_f32_16x16x32_bf16 v[38:41], v[142:145], v[192:195], v[38:41]
	v_mfma_f32_16x16x32_bf16 v[30:33], v[150:153], v[192:195], v[30:33]
	v_mfma_f32_16x16x32_bf16 v[58:61], v[142:145], v[200:203], v[58:61]
	v_mfma_f32_16x16x32_bf16 v[54:57], v[150:153], v[200:203], v[54:57]
	v_mfma_f32_16x16x32_bf16 v[62:65], v[146:149], v[180:183], v[62:65]
	v_mfma_f32_16x16x32_bf16 v[42:45], v[156:159], v[180:183], v[42:45]
	v_mfma_f32_16x16x32_bf16 v[18:21], v[146:149], v[188:191], v[18:21]
	v_mfma_f32_16x16x32_bf16 v[14:17], v[156:159], v[188:191], v[14:17]
	v_mfma_f32_16x16x32_bf16 v[38:41], v[146:149], v[196:199], v[38:41]
	v_mfma_f32_16x16x32_bf16 v[30:33], v[156:159], v[196:199], v[30:33]
	v_mfma_f32_16x16x32_bf16 v[58:61], v[146:149], v[204:207], v[58:61]
	v_mfma_f32_16x16x32_bf16 v[54:57], v[156:159], v[204:207], v[54:57]
	s_setprio 0
	s_setprio 1
	v_mfma_f32_16x16x32_bf16 v[34:37], v[160:163], v[176:179], v[34:37]
	v_mfma_f32_16x16x32_bf16 v[2:5], v[168:171], v[176:179], v[2:5]
	v_mfma_f32_16x16x32_bf16 v[10:13], v[160:163], v[184:187], v[10:13]
	v_mfma_f32_16x16x32_bf16 v[6:9], v[168:171], v[184:187], v[6:9]
	v_mfma_f32_16x16x32_bf16 v[26:29], v[160:163], v[192:195], v[26:29]
	v_mfma_f32_16x16x32_bf16 v[22:25], v[168:171], v[192:195], v[22:25]
	v_mfma_f32_16x16x32_bf16 v[50:53], v[160:163], v[200:203], v[50:53]
	v_mfma_f32_16x16x32_bf16 v[46:49], v[168:171], v[200:203], v[46:49]
	v_mfma_f32_16x16x32_bf16 v[34:37], v[164:167], v[180:183], v[34:37]
	v_mfma_f32_16x16x32_bf16 v[2:5], v[172:175], v[180:183], v[2:5]
	v_mfma_f32_16x16x32_bf16 v[10:13], v[164:167], v[188:191], v[10:13]
	v_mfma_f32_16x16x32_bf16 v[6:9], v[172:175], v[188:191], v[6:9]
	v_mfma_f32_16x16x32_bf16 v[26:29], v[164:167], v[196:199], v[26:29]
	v_mfma_f32_16x16x32_bf16 v[22:25], v[172:175], v[196:199], v[22:25]
	v_mfma_f32_16x16x32_bf16 v[50:53], v[164:167], v[204:207], v[50:53]
	v_mfma_f32_16x16x32_bf16 v[46:49], v[172:175], v[204:207], v[46:49]
	s_setprio 0
	s_barrier
; #define PG8_STAGE(bufoff, gbase, voff) do { _Pragma("unroll") for (int _i = 0; _i < 2; ++_i) \
;         __builtin_amdgcn_global_load_lds((const unsigned*)((const char*)(gbase) + (voff)[_i]), (LAS unsigned*)(lds + (bufoff) + ldsw + _i * 8192), 16, 0, 0); } while (0)
; #define PG8_LDA(dst, b, h) do { _Pragma("unroll") for (int m = 0; m < 4; ++m) _Pragma("unroll") for (int k = 0; k < 2; ++k) dst[m][k] = *(const LAS bf16x8*)(lds + PG8_SA(b, h) + aoff + m * 2048 + k * 1024); } while (0)
; #define PG8_LDB(dst, b, h) do { _Pragma("unroll") for (int n = 0; n < 2; ++n) _Pragma("unroll") for (int k = 0; k < 2; ++k) dst[n][k] = *(const LAS bf16x8*)(lds + PG8_SB(b, h) + boff + n * 2048 + k * 1024); } while (0)
; template <class Epi, class Sched, bool ALIGN_EPI, bool LAST_FUSED = false, bool PERM = false, bool CARRY = false>
; __device__ __forceinline__ void gemm_phase(LAS unsigned char* lds, const int tid, const int K, const int lda, const int ldb, const Sched& S, const Epi& E) {
;     ...
;         for (int t = 0; t < nt; t += 2) {
;             const bool last = (t == nt - 2);
;             const char* a1 = cA + (size_t)(t + 1) * kstep;
;             const char* a2 = last ? nA : cA + (size_t)(t + 2) * kstep; const char* b2 = last ? nB : cB + (size_t)(t + 2) * kstep;
;             const char* a3 = a2 + kstep; const char* b3 = b2 + kstep;
;             PG8_LDB(B0, 0, 0); PG8_LDB(B1, 0, 1); PG8_SCHED; PG8_LDA(At, 0, 0); PG8_STAGE(PG8_SA(1, 1), a1 + hstepA, voffA);
;             PG8_WAIT_V(8); PG8_WAIT_L(0); PG8_BAR; PG8_MMA(0, 0, At, B0); PG8_MMA(0, 1, At, B1); PG8_BAR; PG8_SCHED;
;             PG8_LDA(At, 0, 1); PG8_STAGE(PG8_SB(0, 0), b2, voffB); PG8_STAGE(PG8_SB(0, 1), b2 + hstepB, voffB); PG8_STAGE(PG8_SA(0, 0), a2, voffA);
;             PG8_WAIT_V(8); PG8_WAIT_L(0); PG8_BAR; PG8_MMA(1, 0, At, B0); PG8_MMA(1, 1, At, B1); PG8_BAR; PG8_SCHED;
;             PG8_LDB(B0, 1, 0); PG8_LDB(B1, 1, 1); PG8_SCHED; PG8_LDA(At, 1, 0); PG8_STAGE(PG8_SA(0, 1), a2 + hstepA, voffA);
;             PG8_WAIT_V(8); PG8_WAIT_L(0); PG8_BAR; PG8_MMA(0, 0, At, B0); PG8_MMA(0, 1, At, B1); PG8_BAR; PG8_SCHED;
;             PG8_LDA(At, 1, 1); PG8_STAGE(PG8_SB(1, 0), b3, voffB); PG8_STAGE(PG8_SB(1, 1), b3 + hstepB, voffB); PG8_STAGE(PG8_SA(1, 0), a3, voffA);
;             PG8_WAIT_V(8); PG8_WAIT_L(0); PG8_BAR; PG8_MMA(1, 0, At, B0); PG8_MMA(1, 1, At, B1); PG8_BAR; PG8_SCHED;
	s_add_i32 s52, s96, s87
	v_lshl_add_u64 v[208:209], v[208:209], 0, s[68:69]
	s_mov_b32 m0, s52
	ds_read_b128 v[176:179], v141 offset:49152
	ds_read_b128 v[180:183], v141 offset:50176
	ds_read_b128 v[184:187], v141 offset:51200
	ds_read_b128 v[188:191], v141 offset:52224
	ds_read_b128 v[192:195], v141 offset:53248
	ds_read_b128 v[196:199], v141 offset:54272
	ds_read_b128 v[200:203], v141 offset:55296
	ds_read_b128 v[204:207], v141 offset:56320
	global_load_lds_dwordx4 v[208:209], off
	s_add_i32 m0, s52, 0x2000
	s_add_u32 s52, s76, 0x80080
	v_lshl_add_u64 v[208:209], v[210:211], 0, s[68:69]
	s_addc_u32 s53, s77, 0
	s_add_i32 s76, s97, s87
	global_load_lds_dwordx4 v[208:209], off
	v_lshl_add_u64 v[208:209], s[52:53], 0, v[0:1]
	s_mov_b32 m0, s76
	s_nop 0
	global_load_lds_dwordx4 v[208:209], off
	v_lshl_add_u64 v[208:209], s[52:53], 0, v[122:123]
	s_add_i32 m0, s76, 0x2000
	s_nop 0
	global_load_lds_dwordx4 v[208:209], off
	v_lshl_add_u64 v[208:209], v[212:213], 0, s[68:69]
	s_mov_b32 m0, s85
	s_nop 0
	global_load_lds_dwordx4 v[208:209], off
	v_lshl_add_u64 v[208:209], v[214:215], 0, s[68:69]
	s_mov_b32 m0, s89
	s_nop 0
	global_load_lds_dwordx4 v[208:209], off
	s_waitcnt vmcnt(8)
	s_waitcnt lgkmcnt(0)
	s_barrier
	s_setprio 1
	s_waitcnt lgkmcnt(0)
	v_mfma_f32_16x16x32_bf16 v[78:81], v[142:145], v[176:179], v[78:81]
	v_mfma_f32_16x16x32_bf16 v[74:77], v[150:153], v[176:179], v[74:77]
	v_mfma_f32_16x16x32_bf16 v[98:101], v[142:145], v[184:187], v[98:101]
	v_mfma_f32_16x16x32_bf16 v[94:97], v[150:153], v[184:187], v[94:97]
	v_mfma_f32_16x16x32_bf16 v[118:121], v[142:145], v[192:195], v[118:121]
	v_mfma_f32_16x16x32_bf16 v[114:117], v[150:153], v[192:195], v[114:117]
	v_mfma_f32_16x16x32_bf16 v[134:137], v[142:145], v[200:203], v[134:137]
	v_mfma_f32_16x16x32_bf16 v[130:133], v[150:153], v[200:203], v[130:133]
	v_mfma_f32_16x16x32_bf16 v[78:81], v[146:149], v[180:183], v[78:81]
	v_mfma_f32_16x16x32_bf16 v[74:77], v[156:159], v[180:183], v[74:77]
	v_mfma_f32_16x16x32_bf16 v[98:101], v[146:149], v[188:191], v[98:101]
	v_mfma_f32_16x16x32_bf16 v[94:97], v[156:159], v[188:191], v[94:97]
	v_mfma_f32_16x16x32_bf16 v[118:121], v[146:149], v[196:199], v[118:121]
	v_mfma_f32_16x16x32_bf16 v[114:117], v[156:159], v[196:199], v[114:117]
	v_mfma_f32_16x16x32_bf16 v[134:137], v[146:149], v[204:207], v[134:137]
	v_mfma_f32_16x16x32_bf16 v[130:133], v[156:159], v[204:207], v[130:133]
	s_setprio 0
	s_setprio 1
	v_mfma_f32_16x16x32_bf16 v[70:73], v[160:163], v[176:179], v[70:73]
	v_mfma_f32_16x16x32_bf16 v[66:69], v[168:171], v[176:179], v[66:69]
	v_mfma_f32_16x16x32_bf16 v[90:93], v[160:163], v[184:187], v[90:93]
	v_mfma_f32_16x16x32_bf16 v[86:89], v[168:171], v[184:187], v[86:89]
	v_mfma_f32_16x16x32_bf16 v[110:113], v[160:163], v[192:195], v[110:113]
	v_mfma_f32_16x16x32_bf16 v[106:109], v[168:171], v[192:195], v[106:109]
	v_mfma_f32_16x16x32_bf16 v[102:105], v[160:163], v[200:203], v[102:105]
	v_mfma_f32_16x16x32_bf16 v[82:85], v[168:171], v[200:203], v[82:85]
	v_mfma_f32_16x16x32_bf16 v[70:73], v[164:167], v[180:183], v[70:73]
	v_mfma_f32_16x16x32_bf16 v[66:69], v[172:175], v[180:183], v[66:69]
	v_mfma_f32_16x16x32_bf16 v[90:93], v[164:167], v[188:191], v[90:93]
	v_mfma_f32_16x16x32_bf16 v[86:89], v[172:175], v[188:191], v[86:89]
	v_mfma_f32_16x16x32_bf16 v[110:113], v[164:167], v[196:199], v[110:113]
	v_mfma_f32_16x16x32_bf16 v[106:109], v[172:175], v[196:199], v[106:109]
	v_mfma_f32_16x16x32_bf16 v[102:105], v[164:167], v[204:207], v[102:105]
	v_mfma_f32_16x16x32_bf16 v[82:85], v[172:175], v[204:207], v[82:85]
	s_add_i32 s52, s95, 2
	s_add_u32 s48, s48, 0x100
	s_addc_u32 s49, s49, 0
	v_lshl_add_u64 v[138:139], v[138:139], 0, s[72:73]
	v_lshl_add_u64 v[128:129], v[128:129], 0, s[72:73]
	s_cmp_ge_i32 s95, s3
	s_mov_b32 s95, s52
	s_setprio 0
	s_barrier
	s_cbranch_scc0 .LBB0_1585
	s_and_b64 vcc, exec, s[36:37]
	s_cbranch_vccz .LBB0_1588
	s_barrier

; #define PG8_STAGE(bufoff, gbase, voff) do { _Pragma("unroll") for (int _i = 0; _i < 2; ++_i) \
;         __builtin_amdgcn_global_load_lds((const unsigned*)((const char*)(gbase) + (voff)[_i]), (LAS unsigned*)(lds + (bufoff) + ldsw + _i * 8192), 16, 0, 0); } while (0)
; #define PG8_LDA(dst, b, h) do { _Pragma("unroll") for (int m = 0; m < 4; ++m) _Pragma("unroll") for (int k = 0; k < 2; ++k) dst[m][k] = *(const LAS bf16x8*)(lds + PG8_SA(b, h) + aoff + m * 2048 + k * 1024); } while (0)
; #define PG8_LDB(dst, b, h) do { _Pragma("unroll") for (int n = 0; n < 2; ++n) _Pragma("unroll") for (int k = 0; k < 2; ++k) dst[n][k] = *(const LAS bf16x8*)(lds + PG8_SB(b, h) + boff + n * 2048 + k * 1024); } while (0)
; #define PG8_MMA(ai, bj, At, Bt) do { __builtin_amdgcn_s_setprio(1); _Pragma("unroll") for (int m = 0; m < 4; ++m) _Pragma("unroll") for (int n = 0; n < 2; ++n) _Pragma("unroll") for (int k = 0; k < 2; ++k) \
;         acc[ai][bj][m][n] = __builtin_amdgcn_mfma_f32_16x16x32_bf16(Bt[n][k], At[m][k], acc[ai][bj][m][n], 0, 0, 0); __builtin_amdgcn_s_setprio(0); } while (0)
; #define PG8_WAIT_V(n) asm volatile("s_waitcnt vmcnt(" #n ")" ::: "memory")
; #define PG8_WAIT_L(n) asm volatile("s_waitcnt lgkmcnt(" #n ")" ::: "memory")
; template <class Epi, class Sched, bool ALIGN_EPI, bool LAST_FUSED = false, bool PERM = false, bool CARRY = false>
; __device__ __forceinline__ void gemm_phase(LAS unsigned char* lds, const int tid, const int K, const int lda, const int ldb, const Sched& S, const Epi& E) {
;     ...
;         for (int t = 0; t < nt; t += 2) {
;             const bool last = (t == nt - 2);
;             const char* a1 = cA + (size_t)(t + 1) * kstep;
;             const char* a2 = last ? nA : cA + (size_t)(t + 2) * kstep; const char* b2 = last ? nB : cB + (size_t)(t + 2) * kstep;
;             const char* a3 = a2 + kstep; const char* b3 = b2 + kstep;
;             PG8_LDB(B0, 0, 0); PG8_LDB(B1, 0, 1); PG8_SCHED; PG8_LDA(At, 0, 0); PG8_STAGE(PG8_SA(1, 1), a1 + hstepA, voffA);
;             PG8_WAIT_V(8); PG8_WAIT_L(0); PG8_BAR; PG8_MMA(0, 0, At, B0); PG8_MMA(0, 1, At, B1); PG8_BAR; PG8_SCHED;
;             PG8_LDA(At, 0, 1); PG8_STAGE(PG8_SB(0, 0), b2, voffB); PG8_STAGE(PG8_SB(0, 1), b2 + hstepB, voffB); PG8_STAGE(PG8_SA(0, 0), a2, voffA);
;             PG8_WAIT_V(8); PG8_WAIT_L(0); PG8_BAR; PG8_MMA(1, 0, At, B0); PG8_MMA(1, 1, At, B1); PG8_BAR; PG8_SCHED;
.LBB0_1662:
	s_add_u32 s52, s38, s48
	s_addc_u32 s53, s39, s49
	s_add_u32 s66, s40, s48
	s_addc_u32 s67, s41, s49
	s_waitcnt lgkmcnt(0)
	s_add_i32 s90, 0, 0x10000
	s_cmp_eq_u32 s3, s89
	s_cselect_b32 s53, s24, s53
	s_cselect_b32 s52, s85, s52
	s_cselect_b32 s67, s86, s67
	s_cselect_b32 s66, s87, s66
	s_add_i32 s92, 0, 0x14000
	v_add_u32_e32 v156, s90, v140
	v_add_u32_e32 v172, s92, v140
	ds_read_b128 v[142:145], v156
	ds_read_b128 v[146:149], v156 offset:1024
	ds_read_b128 v[150:153], v156 offset:2048
	ds_read_b128 v[156:159], v156 offset:3072
	ds_read_b128 v[160:163], v172
	ds_read_b128 v[164:167], v172 offset:1024
	ds_read_b128 v[168:171], v172 offset:2048
	ds_read_b128 v[172:175], v172 offset:3072
	v_lshl_add_u64 v[208:209], s[38:39], 0, v[138:139]
	s_add_i32 m0, s35, 0xc000
	ds_read_b128 v[176:179], v141
	ds_read_b128 v[180:183], v141 offset:1024
	ds_read_b128 v[184:187], v141 offset:2048
	ds_read_b128 v[188:191], v141 offset:3072
	ds_read_b128 v[192:195], v141 offset:4096
	ds_read_b128 v[196:199], v141 offset:5120
	ds_read_b128 v[200:203], v141 offset:6144
	ds_read_b128 v[204:207], v141 offset:7168
	global_load_lds_dwordx4 v[208:209], off
	v_lshl_add_u64 v[208:209], s[38:39], 0, v[128:129]
	s_add_i32 m0, s35, 0xe000
	s_nop 0
	global_load_lds_dwordx4 v[208:209], off
	s_waitcnt vmcnt(8)
	s_waitcnt lgkmcnt(0)
	s_barrier
	s_setprio 1
	s_waitcnt lgkmcnt(0)
	v_mfma_f32_16x16x32_bf16 v[62:65], v[142:145], v[176:179], v[62:65]
	v_mfma_f32_16x16x32_bf16 v[42:45], v[150:153], v[176:179], v[42:45]
	v_mfma_f32_16x16x32_bf16 v[18:21], v[142:145], v[184:187], v[18:21]
	v_mfma_f32_16x16x32_bf16 v[14:17], v[150:153], v[184:187], v[14:17]
	v_mfma_f32_16x16x32_bf16 v[38:41], v[142:145], v[192:195], v[38:41]
	v_mfma_f32_16x16x32_bf16 v[30:33], v[150:153], v[192:195], v[30:33]
	v_mfma_f32_16x16x32_bf16 v[58:61], v[142:145], v[200:203], v[58:61]
	v_mfma_f32_16x16x32_bf16 v[54:57], v[150:153], v[200:203], v[54:57]
	v_mfma_f32_16x16x32_bf16 v[62:65], v[146:149], v[180:183], v[62:65]
	v_mfma_f32_16x16x32_bf16 v[42:45], v[156:159], v[180:183], v[42:45]
	v_mfma_f32_16x16x32_bf16 v[18:21], v[146:149], v[188:191], v[18:21]
	v_mfma_f32_16x16x32_bf16 v[14:17], v[156:159], v[188:191], v[14:17]
	v_mfma_f32_16x16x32_bf16 v[38:41], v[146:149], v[196:199], v[38:41]
	v_mfma_f32_16x16x32_bf16 v[30:33], v[156:159], v[196:199], v[30:33]
	v_mfma_f32_16x16x32_bf16 v[58:61], v[146:149], v[204:207], v[58:61]
	v_mfma_f32_16x16x32_bf16 v[54:57], v[156:159], v[204:207], v[54:57]
	s_setprio 0
	s_setprio 1
	v_mfma_f32_16x16x32_bf16 v[34:37], v[160:163], v[176:179], v[34:37]
	v_mfma_f32_16x16x32_bf16 v[2:5], v[168:171], v[176:179], v[2:5]
	v_mfma_f32_16x16x32_bf16 v[10:13], v[160:163], v[184:187], v[10:13]
	v_mfma_f32_16x16x32_bf16 v[6:9], v[168:171], v[184:187], v[6:9]
	v_mfma_f32_16x16x32_bf16 v[26:29], v[160:163], v[192:195], v[26:29]
	v_mfma_f32_16x16x32_bf16 v[22:25], v[168:171], v[192:195], v[22:25]
	v_mfma_f32_16x16x32_bf16 v[50:53], v[160:163], v[200:203], v[50:53]
	v_mfma_f32_16x16x32_bf16 v[46:49], v[168:171], v[200:203], v[46:49]
	v_mfma_f32_16x16x32_bf16 v[34:37], v[164:167], v[180:183], v[34:37]
	v_mfma_f32_16x16x32_bf16 v[2:5], v[172:175], v[180:183], v[2:5]
	v_mfma_f32_16x16x32_bf16 v[10:13], v[164:167], v[188:191], v[10:13]
	v_mfma_f32_16x16x32_bf16 v[6:9], v[172:175], v[188:191], v[6:9]
	v_mfma_f32_16x16x32_bf16 v[26:29], v[164:167], v[196:199], v[26:29]
	v_mfma_f32_16x16x32_bf16 v[22:25], v[172:175], v[196:199], v[22:25]
	v_mfma_f32_16x16x32_bf16 v[50:53], v[164:167], v[204:207], v[50:53]
	v_mfma_f32_16x16x32_bf16 v[46:49], v[172:175], v[204:207], v[46:49]
	s_setprio 0
	s_barrier
	s_add_i32 s90, s90, s76
	v_lshl_add_u64 v[208:209], s[66:67], 0, v[0:1]
	s_mov_b32 m0, s90
	ds_read_b128 v[176:179], v141 offset:16384
	ds_read_b128 v[180:183], v141 offset:17408
	ds_read_b128 v[184:187], v141 offset:18432
	ds_read_b128 v[188:191], v141 offset:19456
	ds_read_b128 v[192:195], v141 offset:20480
	ds_read_b128 v[196:199], v141 offset:21504
	ds_read_b128 v[200:203], v141 offset:22528
	ds_read_b128 v[204:207], v141 offset:23552
	global_load_lds_dwordx4 v[208:209], off
	s_add_i32 m0, s90, 0x2000
	s_add_u32 s90, s66, 0x100000
	v_lshl_add_u64 v[210:211], s[66:67], 0, v[122:123]
	s_addc_u32 s91, s67, 0
	s_add_i32 s92, s92, s76
	global_load_lds_dwordx4 v[210:211], off
	v_lshl_add_u64 v[212:213], s[90:91], 0, v[0:1]
	s_mov_b32 m0, s92
	v_lshl_add_u64 v[214:215], s[52:53], 0, v[122:123]
	global_load_lds_dwordx4 v[212:213], off
	v_lshl_add_u64 v[212:213], s[90:91], 0, v[122:123]
	s_add_i32 m0, s92, 0x2000
	s_nop 0
	global_load_lds_dwordx4 v[212:213], off
	v_lshl_add_u64 v[212:213], s[52:53], 0, v[0:1]
	s_mov_b32 m0, s35
	s_nop 0
	global_load_lds_dwordx4 v[212:213], off
	s_mov_b32 m0, s28
	s_nop 0
	global_load_lds_dwordx4 v[214:215], off
	s_waitcnt vmcnt(8)
	s_waitcnt lgkmcnt(0)
	s_barrier
; #define PG8_STAGE(bufoff, gbase, voff) do { _Pragma("unroll") for (int _i = 0; _i < 2; ++_i) \
;         __builtin_amdgcn_global_load_lds((const unsigned*)((const char*)(gbase) + (voff)[_i]), (LAS unsigned*)(lds + (bufoff) + ldsw + _i * 8192), 16, 0, 0); } while (0)
; #define PG8_LDA(dst, b, h) do { _Pragma("unroll") for (int m = 0; m < 4; ++m) _Pragma("unroll") for (int k = 0; k < 2; ++k) dst[m][k] = *(const LAS bf16x8*)(lds + PG8_SA(b, h) + aoff + m * 2048 + k * 1024); } while (0)
; #define PG8_LDB(dst, b, h) do { _Pragma("unroll") for (int n = 0; n < 2; ++n) _Pragma("unroll") for (int k = 0; k < 2; ++k) dst[n][k] = *(const LAS bf16x8*)(lds + PG8_SB(b, h) + boff + n * 2048 + k * 1024); } while (0)
; #define PG8_MMA(ai, bj, At, Bt) do { __builtin_amdgcn_s_setprio(1); _Pragma("unroll") for (int m = 0; m < 4; ++m) _Pragma("unroll") for (int n = 0; n < 2; ++n) _Pragma("unroll") for (int k = 0; k < 2; ++k) \
;         acc[ai][bj][m][n] = __builtin_amdgcn_mfma_f32_16x16x32_bf16(Bt[n][k], At[m][k], acc[ai][bj][m][n], 0, 0, 0); __builtin_amdgcn_s_setprio(0); } while (0)
; #define PG8_WAIT_V(n) asm volatile("s_waitcnt vmcnt(" #n ")" ::: "memory")
; #define PG8_WAIT_L(n) asm volatile("s_waitcnt lgkmcnt(" #n ")" ::: "memory")
; #define PG8_BAR __builtin_amdgcn_s_barrier()
; #define PG8_SCHED __builtin_amdgcn_sched_barrier(0)
; template <class Epi, class Sched, bool ALIGN_EPI, bool LAST_FUSED = false, bool PERM = false, bool CARRY = false>
; __device__ __forceinline__ void gemm_phase(LAS unsigned char* lds, const int tid, const int K, const int lda, const int ldb, const Sched& S, const Epi& E) {
;     ...
;             PG8_WAIT_V(8); PG8_WAIT_L(0); PG8_BAR; PG8_MMA(1, 0, At, B0); PG8_MMA(1, 1, At, B1); PG8_BAR; PG8_SCHED;
;             PG8_LDB(B0, 1, 0); PG8_LDB(B1, 1, 1); PG8_SCHED; PG8_LDA(At, 1, 0); PG8_STAGE(PG8_SA(0, 1), a2 + hstepA, voffA);
;             PG8_WAIT_V(8); PG8_WAIT_L(0); PG8_BAR; PG8_MMA(0, 0, At, B0); PG8_MMA(0, 1, At, B1); PG8_BAR; PG8_SCHED;
	s_setprio 1
	s_waitcnt lgkmcnt(0)
	v_mfma_f32_16x16x32_bf16 v[78:81], v[142:145], v[176:179], v[78:81]
	v_mfma_f32_16x16x32_bf16 v[74:77], v[150:153], v[176:179], v[74:77]
	v_mfma_f32_16x16x32_bf16 v[98:101], v[142:145], v[184:187], v[98:101]
	v_mfma_f32_16x16x32_bf16 v[94:97], v[150:153], v[184:187], v[94:97]
	v_mfma_f32_16x16x32_bf16 v[118:121], v[142:145], v[192:195], v[118:121]
	v_mfma_f32_16x16x32_bf16 v[114:117], v[150:153], v[192:195], v[114:117]
	v_mfma_f32_16x16x32_bf16 v[134:137], v[142:145], v[200:203], v[134:137]
	v_mfma_f32_16x16x32_bf16 v[130:133], v[150:153], v[200:203], v[130:133]
	v_mfma_f32_16x16x32_bf16 v[78:81], v[146:149], v[180:183], v[78:81]
	v_mfma_f32_16x16x32_bf16 v[74:77], v[156:159], v[180:183], v[74:77]
	v_mfma_f32_16x16x32_bf16 v[98:101], v[146:149], v[188:191], v[98:101]
	v_mfma_f32_16x16x32_bf16 v[94:97], v[156:159], v[188:191], v[94:97]
	v_mfma_f32_16x16x32_bf16 v[118:121], v[146:149], v[196:199], v[118:121]
	v_mfma_f32_16x16x32_bf16 v[114:117], v[156:159], v[196:199], v[114:117]
	v_mfma_f32_16x16x32_bf16 v[134:137], v[146:149], v[204:207], v[134:137]
	v_mfma_f32_16x16x32_bf16 v[130:133], v[156:159], v[204:207], v[130:133]
	s_setprio 0
	s_setprio 1
	v_mfma_f32_16x16x32_bf16 v[70:73], v[160:163], v[176:179], v[70:73]
	v_mfma_f32_16x16x32_bf16 v[66:69], v[168:171], v[176:179], v[66:69]
	v_mfma_f32_16x16x32_bf16 v[90:93], v[160:163], v[184:187], v[90:93]
	v_mfma_f32_16x16x32_bf16 v[86:89], v[168:171], v[184:187], v[86:89]
	v_mfma_f32_16x16x32_bf16 v[110:113], v[160:163], v[192:195], v[110:113]
	v_mfma_f32_16x16x32_bf16 v[106:109], v[168:171], v[192:195], v[106:109]
	v_mfma_f32_16x16x32_bf16 v[102:105], v[160:163], v[200:203], v[102:105]
	v_mfma_f32_16x16x32_bf16 v[82:85], v[168:171], v[200:203], v[82:85]
	v_mfma_f32_16x16x32_bf16 v[70:73], v[164:167], v[180:183], v[70:73]
	v_mfma_f32_16x16x32_bf16 v[66:69], v[172:175], v[180:183], v[66:69]
	v_mfma_f32_16x16x32_bf16 v[90:93], v[164:167], v[188:191], v[90:93]
	v_mfma_f32_16x16x32_bf16 v[86:89], v[172:175], v[188:191], v[86:89]
	v_mfma_f32_16x16x32_bf16 v[110:113], v[164:167], v[196:199], v[110:113]
	v_mfma_f32_16x16x32_bf16 v[106:109], v[172:175], v[196:199], v[106:109]
	v_mfma_f32_16x16x32_bf16 v[102:105], v[164:167], v[204:207], v[102:105]
	v_mfma_f32_16x16x32_bf16 v[82:85], v[172:175], v[204:207], v[82:85]
	s_setprio 0
	s_barrier
	s_add_i32 s90, 0, 0x18000
	s_add_i32 s91, 0, 0x1c000
	v_add_u32_e32 v156, s90, v140
	v_add_u32_e32 v172, s91, v140
	ds_read_b128 v[142:145], v156
	ds_read_b128 v[146:149], v156 offset:1024
	ds_read_b128 v[150:153], v156 offset:2048
	ds_read_b128 v[156:159], v156 offset:3072
	ds_read_b128 v[160:163], v172
	ds_read_b128 v[164:167], v172 offset:1024
	ds_read_b128 v[168:171], v172 offset:2048
	ds_read_b128 v[172:175], v172 offset:3072
	s_add_u32 s52, s52, 0x100000
	s_addc_u32 s53, s53, 0
	s_mov_b32 m0, s29
	v_lshl_add_u64 v[216:217], s[52:53], 0, v[0:1]
	ds_read_b128 v[176:179], v141 offset:32768
	ds_read_b128 v[180:183], v141 offset:33792
	ds_read_b128 v[184:187], v141 offset:34816
	ds_read_b128 v[188:191], v141 offset:35840
	ds_read_b128 v[192:195], v141 offset:36864
	ds_read_b128 v[196:199], v141 offset:37888
	ds_read_b128 v[200:203], v141 offset:38912
	ds_read_b128 v[204:207], v141 offset:39936
	global_load_lds_dwordx4 v[216:217], off
	v_lshl_add_u64 v[216:217], s[52:53], 0, v[122:123]
	s_mov_b32 m0, s14
	s_nop 0
	global_load_lds_dwordx4 v[216:217], off
	s_waitcnt vmcnt(8)
	s_waitcnt lgkmcnt(0)
	s_barrier
	s_setprio 1
	s_waitcnt lgkmcnt(0)
	v_mfma_f32_16x16x32_bf16 v[62:65], v[142:145], v[176:179], v[62:65]
	v_mfma_f32_16x16x32_bf16 v[42:45], v[150:153], v[176:179], v[42:45]
	v_mfma_f32_16x16x32_bf16 v[18:21], v[142:145], v[184:187], v[18:21]
	v_mfma_f32_16x16x32_bf16 v[14:17], v[150:153], v[184:187], v[14:17]
	v_mfma_f32_16x16x32_bf16 v[38:41], v[142:145], v[192:195], v[38:41]
	v_mfma_f32_16x16x32_bf16 v[30:33], v[150:153], v[192:195], v[30:33]
	v_mfma_f32_16x16x32_bf16 v[58:61], v[142:145], v[200:203], v[58:61]
	v_mfma_f32_16x16x32_bf16 v[54:57], v[150:153], v[200:203], v[54:57]
	v_mfma_f32_16x16x32_bf16 v[62:65], v[146:149], v[180:183], v[62:65]
	v_mfma_f32_16x16x32_bf16 v[42:45], v[156:159], v[180:183], v[42:45]
	v_mfma_f32_16x16x32_bf16 v[18:21], v[146:149], v[188:191], v[18:21]
	v_mfma_f32_16x16x32_bf16 v[14:17], v[156:159], v[188:191], v[14:17]
	v_mfma_f32_16x16x32_bf16 v[38:41], v[146:149], v[196:199], v[38:41]
	v_mfma_f32_16x16x32_bf16 v[30:33], v[156:159], v[196:199], v[30:33]
	v_mfma_f32_16x16x32_bf16 v[58:61], v[146:149], v[204:207], v[58:61]
	v_mfma_f32_16x16x32_bf16 v[54:57], v[156:159], v[204:207], v[54:57]
	s_setprio 0
	s_setprio 1
	v_mfma_f32_16x16x32_bf16 v[34:37], v[160:163], v[176:179], v[34:37]
	v_mfma_f32_16x16x32_bf16 v[2:5], v[168:171], v[176:179], v[2:5]
	v_mfma_f32_16x16x32_bf16 v[10:13], v[160:163], v[184:187], v[10:13]
	v_mfma_f32_16x16x32_bf16 v[6:9], v[168:171], v[184:187], v[6:9]
	v_mfma_f32_16x16x32_bf16 v[26:29], v[160:163], v[192:195], v[26:29]
	v_mfma_f32_16x16x32_bf16 v[22:25], v[168:171], v[192:195], v[22:25]
	v_mfma_f32_16x16x32_bf16 v[50:53], v[160:163], v[200:203], v[50:53]
	v_mfma_f32_16x16x32_bf16 v[46:49], v[168:171], v[200:203], v[46:49]
	v_mfma_f32_16x16x32_bf16 v[34:37], v[164:167], v[180:183], v[34:37]
	v_mfma_f32_16x16x32_bf16 v[2:5], v[172:175], v[180:183], v[2:5]
	v_mfma_f32_16x16x32_bf16 v[10:13], v[164:167], v[188:191], v[10:13]
	v_mfma_f32_16x16x32_bf16 v[6:9], v[172:175], v[188:191], v[6:9]
	v_mfma_f32_16x16x32_bf16 v[26:29], v[164:167], v[196:199], v[26:29]
	v_mfma_f32_16x16x32_bf16 v[22:25], v[172:175], v[196:199], v[22:25]
	v_mfma_f32_16x16x32_bf16 v[50:53], v[164:167], v[204:207], v[50:53]
	v_mfma_f32_16x16x32_bf16 v[46:49], v[172:175], v[204:207], v[46:49]
	s_setprio 0
	s_barrier
; #define PG8_STAGE(bufoff, gbase, voff) do { _Pragma("unroll") for (int _i = 0; _i < 2; ++_i) \
;         __builtin_amdgcn_global_load_lds((const unsigned*)((const char*)(gbase) + (voff)[_i]), (LAS unsigned*)(lds + (bufoff) + ldsw + _i * 8192), 16, 0, 0); } while (0)
; #define PG8_LDA(dst, b, h) do { _Pragma("unroll") for (int m = 0; m < 4; ++m) _Pragma("unroll") for (int k = 0; k < 2; ++k) dst[m][k] = *(const LAS bf16x8*)(lds + PG8_SA(b, h) + aoff + m * 2048 + k * 1024); } while (0)
; #define PG8_LDB(dst, b, h) do { _Pragma("unroll") for (int n = 0; n < 2; ++n) _Pragma("unroll") for (int k = 0; k < 2; ++k) dst[n][k] = *(const LAS bf16x8*)(lds + PG8_SB(b, h) + boff + n * 2048 + k * 1024); } while (0)
; template <class Epi, class Sched, bool ALIGN_EPI, bool LAST_FUSED = false, bool PERM = false, bool CARRY = false>
; __device__ __forceinline__ void gemm_phase(LAS unsigned char* lds, const int tid, const int K, const int lda, const int ldb, const Sched& S, const Epi& E) {
;     ...
;         for (int t = 0; t < nt; t += 2) {
;             const bool last = (t == nt - 2);
;             const char* a1 = cA + (size_t)(t + 1) * kstep;
;             const char* a2 = last ? nA : cA + (size_t)(t + 2) * kstep; const char* b2 = last ? nB : cB + (size_t)(t + 2) * kstep;
;             const char* a3 = a2 + kstep; const char* b3 = b2 + kstep;
;             PG8_LDB(B0, 0, 0); PG8_LDB(B1, 0, 1); PG8_SCHED; PG8_LDA(At, 0, 0); PG8_STAGE(PG8_SA(1, 1), a1 + hstepA, voffA);
;             PG8_WAIT_V(8); PG8_WAIT_L(0); PG8_BAR; PG8_MMA(0, 0, At, B0); PG8_MMA(0, 1, At, B1); PG8_BAR; PG8_SCHED;
;             PG8_LDA(At, 0, 1); PG8_STAGE(PG8_SB(0, 0), b2, voffB); PG8_STAGE(PG8_SB(0, 1), b2 + hstepB, voffB); PG8_STAGE(PG8_SA(0, 0), a2, voffA);
;             PG8_WAIT_V(8); PG8_WAIT_L(0); PG8_BAR; PG8_MMA(1, 0, At, B0); PG8_MMA(1, 1, At, B1); PG8_BAR; PG8_SCHED;
;             PG8_LDB(B0, 1, 0); PG8_LDB(B1, 1, 1); PG8_SCHED; PG8_LDA(At, 1, 0); PG8_STAGE(PG8_SA(0, 1), a2 + hstepA, voffA);
;             PG8_WAIT_V(8); PG8_WAIT_L(0); PG8_BAR; PG8_MMA(0, 0, At, B0); PG8_MMA(0, 1, At, B1); PG8_BAR; PG8_SCHED;
;             PG8_LDA(At, 1, 1); PG8_STAGE(PG8_SB(1, 0), b3, voffB); PG8_STAGE(PG8_SB(1, 1), b3 + hstepB, voffB); PG8_STAGE(PG8_SA(1, 0), a3, voffA);
;             PG8_WAIT_V(8); PG8_WAIT_L(0); PG8_BAR; PG8_MMA(1, 0, At, B0); PG8_MMA(1, 1, At, B1); PG8_BAR; PG8_SCHED;
	s_add_i32 s52, s90, s76
	v_lshl_add_u64 v[208:209], v[208:209], 0, s[68:69]
	s_mov_b32 m0, s52
	ds_read_b128 v[176:179], v141 offset:49152
	ds_read_b128 v[180:183], v141 offset:50176
	ds_read_b128 v[184:187], v141 offset:51200
	ds_read_b128 v[188:191], v141 offset:52224
	ds_read_b128 v[192:195], v141 offset:53248
	ds_read_b128 v[196:199], v141 offset:54272
	ds_read_b128 v[200:203], v141 offset:55296
	ds_read_b128 v[204:207], v141 offset:56320
	global_load_lds_dwordx4 v[208:209], off
	s_add_i32 m0, s52, 0x2000
	s_add_u32 s52, s66, 0x100080
	v_lshl_add_u64 v[208:209], v[210:211], 0, s[68:69]
	s_addc_u32 s53, s67, 0
	s_add_i32 s66, s91, s76
	global_load_lds_dwordx4 v[208:209], off
	v_lshl_add_u64 v[208:209], s[52:53], 0, v[0:1]
	s_mov_b32 m0, s66
	s_nop 0
	global_load_lds_dwordx4 v[208:209], off
	v_lshl_add_u64 v[208:209], s[52:53], 0, v[122:123]
	s_add_i32 m0, s66, 0x2000
	s_nop 0
	global_load_lds_dwordx4 v[208:209], off
	v_lshl_add_u64 v[208:209], v[212:213], 0, s[68:69]
	s_mov_b32 m0, s77
	s_nop 0
	global_load_lds_dwordx4 v[208:209], off
	v_lshl_add_u64 v[208:209], v[214:215], 0, s[68:69]
	s_mov_b32 m0, s79
	s_nop 0
	global_load_lds_dwordx4 v[208:209], off
	s_waitcnt vmcnt(8)
	s_waitcnt lgkmcnt(0)
	s_barrier
	s_setprio 1
	s_waitcnt lgkmcnt(0)
	v_mfma_f32_16x16x32_bf16 v[78:81], v[142:145], v[176:179], v[78:81]
	v_mfma_f32_16x16x32_bf16 v[74:77], v[150:153], v[176:179], v[74:77]
	v_mfma_f32_16x16x32_bf16 v[98:101], v[142:145], v[184:187], v[98:101]
	v_mfma_f32_16x16x32_bf16 v[94:97], v[150:153], v[184:187], v[94:97]
	v_mfma_f32_16x16x32_bf16 v[118:121], v[142:145], v[192:195], v[118:121]
	v_mfma_f32_16x16x32_bf16 v[114:117], v[150:153], v[192:195], v[114:117]
	v_mfma_f32_16x16x32_bf16 v[134:137], v[142:145], v[200:203], v[134:137]
	v_mfma_f32_16x16x32_bf16 v[130:133], v[150:153], v[200:203], v[130:133]
	v_mfma_f32_16x16x32_bf16 v[78:81], v[146:149], v[180:183], v[78:81]
	v_mfma_f32_16x16x32_bf16 v[74:77], v[156:159], v[180:183], v[74:77]
	v_mfma_f32_16x16x32_bf16 v[98:101], v[146:149], v[188:191], v[98:101]
	v_mfma_f32_16x16x32_bf16 v[94:97], v[156:159], v[188:191], v[94:97]
	v_mfma_f32_16x16x32_bf16 v[118:121], v[146:149], v[196:199], v[118:121]
	v_mfma_f32_16x16x32_bf16 v[114:117], v[156:159], v[196:199], v[114:117]
	v_mfma_f32_16x16x32_bf16 v[134:137], v[146:149], v[204:207], v[134:137]
	v_mfma_f32_16x16x32_bf16 v[130:133], v[156:159], v[204:207], v[130:133]
	s_setprio 0
	s_setprio 1
	v_mfma_f32_16x16x32_bf16 v[70:73], v[160:163], v[176:179], v[70:73]
	v_mfma_f32_16x16x32_bf16 v[66:69], v[168:171], v[176:179], v[66:69]
	v_mfma_f32_16x16x32_bf16 v[90:93], v[160:163], v[184:187], v[90:93]
	v_mfma_f32_16x16x32_bf16 v[86:89], v[168:171], v[184:187], v[86:89]
	v_mfma_f32_16x16x32_bf16 v[110:113], v[160:163], v[192:195], v[110:113]
	v_mfma_f32_16x16x32_bf16 v[106:109], v[168:171], v[192:195], v[106:109]
	v_mfma_f32_16x16x32_bf16 v[102:105], v[160:163], v[200:203], v[102:105]
	v_mfma_f32_16x16x32_bf16 v[82:85], v[168:171], v[200:203], v[82:85]
	v_mfma_f32_16x16x32_bf16 v[70:73], v[164:167], v[180:183], v[70:73]
	v_mfma_f32_16x16x32_bf16 v[66:69], v[172:175], v[180:183], v[66:69]
	v_mfma_f32_16x16x32_bf16 v[90:93], v[164:167], v[188:191], v[90:93]
	v_mfma_f32_16x16x32_bf16 v[86:89], v[172:175], v[188:191], v[86:89]
	v_mfma_f32_16x16x32_bf16 v[110:113], v[164:167], v[196:199], v[110:113]
	v_mfma_f32_16x16x32_bf16 v[106:109], v[172:175], v[196:199], v[106:109]
	v_mfma_f32_16x16x32_bf16 v[102:105], v[164:167], v[204:207], v[102:105]
	v_mfma_f32_16x16x32_bf16 v[82:85], v[172:175], v[204:207], v[82:85]
	s_add_i32 s52, s89, 2
	s_add_u32 s48, s48, 0x100
	s_addc_u32 s49, s49, 0
	v_lshl_add_u64 v[138:139], v[138:139], 0, s[72:73]
	v_lshl_add_u64 v[128:129], v[128:129], 0, s[72:73]
	s_cmp_ge_i32 s89, s3
	s_mov_b32 s89, s52
	s_setprio 0
	s_barrier
	s_cbranch_scc0 .LBB0_1662
	s_and_b64 vcc, exec, s[36:37]
	s_cbranch_vccz .LBB0_1665
	s_barrier

; #define PG8_STAGE(bufoff, gbase, voff) do { _Pragma("unroll") for (int _i = 0; _i < 2; ++_i) \
;         __builtin_amdgcn_global_load_lds((const unsigned*)((const char*)(gbase) + (voff)[_i]), (LAS unsigned*)(lds + (bufoff) + ldsw + _i * 8192), 16, 0, 0); } while (0)
; #define PG8_LDA(dst, b, h) do { _Pragma("unroll") for (int m = 0; m < 4; ++m) _Pragma("unroll") for (int k = 0; k < 2; ++k) dst[m][k] = *(const LAS bf16x8*)(lds + PG8_SA(b, h) + aoff + m * 2048 + k * 1024); } while (0)
; #define PG8_LDB(dst, b, h) do { _Pragma("unroll") for (int n = 0; n < 2; ++n) _Pragma("unroll") for (int k = 0; k < 2; ++k) dst[n][k] = *(const LAS bf16x8*)(lds + PG8_SB(b, h) + boff + n * 2048 + k * 1024); } while (0)
; #define PG8_MMA(ai, bj, At, Bt) do { __builtin_amdgcn_s_setprio(1); _Pragma("unroll") for (int m = 0; m < 4; ++m) _Pragma("unroll") for (int n = 0; n < 2; ++n) _Pragma("unroll") for (int k = 0; k < 2; ++k) \
;         acc[ai][bj][m][n] = __builtin_amdgcn_mfma_f32_16x16x32_bf16(Bt[n][k], At[m][k], acc[ai][bj][m][n], 0, 0, 0); __builtin_amdgcn_s_setprio(0); } while (0)
; #define PG8_WAIT_V(n) asm volatile("s_waitcnt vmcnt(" #n ")" ::: "memory")
; #define PG8_WAIT_L(n) asm volatile("s_waitcnt lgkmcnt(" #n ")" ::: "memory")
; template <class Epi, class Sched, bool ALIGN_EPI, bool LAST_FUSED = false, bool PERM = false, bool CARRY = false>
; __device__ __forceinline__ void gemm_phase(LAS unsigned char* lds, const int tid, const int K, const int lda, const int ldb, const Sched& S, const Epi& E) {
;     ...
;         for (int t = 0; t < nt; t += 2) {
;             const bool last = (t == nt - 2);
;             const char* a1 = cA + (size_t)(t + 1) * kstep;
;             const char* a2 = last ? nA : cA + (size_t)(t + 2) * kstep; const char* b2 = last ? nB : cB + (size_t)(t + 2) * kstep;
;             const char* a3 = a2 + kstep; const char* b3 = b2 + kstep;
;             PG8_LDB(B0, 0, 0); PG8_LDB(B1, 0, 1); PG8_SCHED; PG8_LDA(At, 0, 0); PG8_STAGE(PG8_SA(1, 1), a1 + hstepA, voffA);
;             PG8_WAIT_V(8); PG8_WAIT_L(0); PG8_BAR; PG8_MMA(0, 0, At, B0); PG8_MMA(0, 1, At, B1); PG8_BAR; PG8_SCHED;
;             PG8_LDA(At, 0, 1); PG8_STAGE(PG8_SB(0, 0), b2, voffB); PG8_STAGE(PG8_SB(0, 1), b2 + hstepB, voffB); PG8_STAGE(PG8_SA(0, 0), a2, voffA);
;             PG8_WAIT_V(8); PG8_WAIT_L(0); PG8_BAR; PG8_MMA(1, 0, At, B0); PG8_MMA(1, 1, At, B1); PG8_BAR; PG8_SCHED;
.LBB0_1763:
	s_add_u32 s16, s48, 0xfff80080
	s_addc_u32 s17, s49, -1
	s_add_i32 s67, 0, 0x10000
	s_cmp_eq_u32 s41, 28
	s_cselect_b32 s53, s43, s17
	s_cselect_b32 s52, s42, s16
	v_add_u32_e32 v140, s67, v146
	s_cselect_b32 s55, s51, s39
	s_cselect_b32 s54, s50, s27
	s_add_i32 s16, 0, 0x14000
	ds_read_b128 v[148:151], v140
	ds_read_b128 v[152:155], v140 offset:1024
	ds_read_b128 v[156:159], v140 offset:2048
	ds_read_b128 v[160:163], v140 offset:3072
	v_add_u32_e32 v140, s16, v146
	ds_read_b128 v[164:167], v140
	ds_read_b128 v[168:171], v140 offset:1024
	ds_read_b128 v[172:175], v140 offset:2048
	ds_read_b128 v[176:179], v140 offset:3072
	v_lshl_add_u64 v[140:141], s[48:49], 0, v[136:137]
	s_add_i32 m0, s47, 0xc000
	ds_read_b128 v[180:183], v147
	ds_read_b128 v[184:187], v147 offset:1024
	ds_read_b128 v[188:191], v147 offset:2048
	ds_read_b128 v[192:195], v147 offset:3072
	ds_read_b128 v[196:199], v147 offset:4096
	ds_read_b128 v[200:203], v147 offset:5120
	ds_read_b128 v[204:207], v147 offset:6144
	ds_read_b128 v[208:211], v147 offset:7168
	global_load_lds_dwordx4 v[140:141], off
	v_lshl_add_u64 v[140:141], s[48:49], 0, v[138:139]
	s_add_i32 m0, s47, 0xe000
	s_nop 0
	global_load_lds_dwordx4 v[140:141], off
	s_waitcnt vmcnt(8)
	s_waitcnt lgkmcnt(0)
	s_barrier
	s_setprio 1
	s_waitcnt lgkmcnt(0)
	v_mfma_f32_16x16x32_bf16 v[126:129], v[148:151], v[180:183], v[126:129]
	v_mfma_f32_16x16x32_bf16 v[122:125], v[156:159], v[180:183], v[122:125]
	v_mfma_f32_16x16x32_bf16 v[110:113], v[148:151], v[188:191], v[110:113]
	v_mfma_f32_16x16x32_bf16 v[106:109], v[156:159], v[188:191], v[106:109]
	v_mfma_f32_16x16x32_bf16 v[94:97], v[148:151], v[196:199], v[94:97]
	v_mfma_f32_16x16x32_bf16 v[90:93], v[156:159], v[196:199], v[90:93]
	v_mfma_f32_16x16x32_bf16 v[78:81], v[148:151], v[204:207], v[78:81]
	v_mfma_f32_16x16x32_bf16 v[74:77], v[156:159], v[204:207], v[74:77]
	v_mfma_f32_16x16x32_bf16 v[126:129], v[152:155], v[184:187], v[126:129]
	v_mfma_f32_16x16x32_bf16 v[122:125], v[160:163], v[184:187], v[122:125]
	v_mfma_f32_16x16x32_bf16 v[110:113], v[152:155], v[192:195], v[110:113]
	v_mfma_f32_16x16x32_bf16 v[106:109], v[160:163], v[192:195], v[106:109]
	v_mfma_f32_16x16x32_bf16 v[94:97], v[152:155], v[200:203], v[94:97]
	v_mfma_f32_16x16x32_bf16 v[90:93], v[160:163], v[200:203], v[90:93]
	v_mfma_f32_16x16x32_bf16 v[78:81], v[152:155], v[208:211], v[78:81]
	v_mfma_f32_16x16x32_bf16 v[74:77], v[160:163], v[208:211], v[74:77]
	s_setprio 0
	s_setprio 1
	v_mfma_f32_16x16x32_bf16 v[118:121], v[164:167], v[180:183], v[118:121]
	v_mfma_f32_16x16x32_bf16 v[114:117], v[172:175], v[180:183], v[114:117]
	v_mfma_f32_16x16x32_bf16 v[102:105], v[164:167], v[188:191], v[102:105]
	v_mfma_f32_16x16x32_bf16 v[98:101], v[172:175], v[188:191], v[98:101]
	v_mfma_f32_16x16x32_bf16 v[86:89], v[164:167], v[196:199], v[86:89]
	v_mfma_f32_16x16x32_bf16 v[82:85], v[172:175], v[196:199], v[82:85]
	v_mfma_f32_16x16x32_bf16 v[70:73], v[164:167], v[204:207], v[70:73]
	v_mfma_f32_16x16x32_bf16 v[66:69], v[172:175], v[204:207], v[66:69]
	v_mfma_f32_16x16x32_bf16 v[118:121], v[168:171], v[184:187], v[118:121]
	v_mfma_f32_16x16x32_bf16 v[114:117], v[176:179], v[184:187], v[114:117]
	v_mfma_f32_16x16x32_bf16 v[102:105], v[168:171], v[192:195], v[102:105]
	v_mfma_f32_16x16x32_bf16 v[98:101], v[176:179], v[192:195], v[98:101]
	v_mfma_f32_16x16x32_bf16 v[86:89], v[168:171], v[200:203], v[86:89]
	v_mfma_f32_16x16x32_bf16 v[82:85], v[176:179], v[200:203], v[82:85]
	v_mfma_f32_16x16x32_bf16 v[70:73], v[168:171], v[208:211], v[70:73]
	v_mfma_f32_16x16x32_bf16 v[66:69], v[176:179], v[208:211], v[66:69]
	s_setprio 0
	s_barrier
	s_add_i32 s17, s67, s45
	v_lshl_add_u64 v[140:141], s[54:55], 0, v[0:1]
	s_mov_b32 m0, s17
	ds_read_b128 v[180:183], v147 offset:16384
	ds_read_b128 v[184:187], v147 offset:17408
	ds_read_b128 v[188:191], v147 offset:18432
	ds_read_b128 v[192:195], v147 offset:19456
	ds_read_b128 v[196:199], v147 offset:20480
	ds_read_b128 v[200:203], v147 offset:21504
	ds_read_b128 v[204:207], v147 offset:22528
	ds_read_b128 v[208:211], v147 offset:23552
	global_load_lds_dwordx4 v[140:141], off
	s_add_i32 m0, s17, 0x2000
	s_add_u32 s70, s54, 0x80000
	v_lshl_add_u64 v[212:213], s[54:55], 0, v[130:131]
	s_addc_u32 s71, s55, 0
	s_add_i32 s16, s16, s45
	global_load_lds_dwordx4 v[212:213], off
	v_lshl_add_u64 v[214:215], s[70:71], 0, v[0:1]
	s_mov_b32 m0, s16
	v_lshl_add_u64 v[216:217], s[52:53], 0, v[132:133]
	global_load_lds_dwordx4 v[214:215], off
	v_lshl_add_u64 v[214:215], s[70:71], 0, v[130:131]
	s_add_i32 m0, s16, 0x2000
	s_nop 0
	global_load_lds_dwordx4 v[214:215], off
	v_lshl_add_u64 v[214:215], s[52:53], 0, v[134:135]
	s_mov_b32 m0, s47
	s_nop 0
	global_load_lds_dwordx4 v[214:215], off
	s_mov_b32 m0, s57
	s_nop 0
	global_load_lds_dwordx4 v[216:217], off
	s_waitcnt vmcnt(8)
	s_waitcnt lgkmcnt(0)
	s_barrier
; #define PG8_STAGE(bufoff, gbase, voff) do { _Pragma("unroll") for (int _i = 0; _i < 2; ++_i) \
;         __builtin_amdgcn_global_load_lds((const unsigned*)((const char*)(gbase) + (voff)[_i]), (LAS unsigned*)(lds + (bufoff) + ldsw + _i * 8192), 16, 0, 0); } while (0)
; #define PG8_LDA(dst, b, h) do { _Pragma("unroll") for (int m = 0; m < 4; ++m) _Pragma("unroll") for (int k = 0; k < 2; ++k) dst[m][k] = *(const LAS bf16x8*)(lds + PG8_SA(b, h) + aoff + m * 2048 + k * 1024); } while (0)
; #define PG8_LDB(dst, b, h) do { _Pragma("unroll") for (int n = 0; n < 2; ++n) _Pragma("unroll") for (int k = 0; k < 2; ++k) dst[n][k] = *(const LAS bf16x8*)(lds + PG8_SB(b, h) + boff + n * 2048 + k * 1024); } while (0)
; #define PG8_MMA(ai, bj, At, Bt) do { __builtin_amdgcn_s_setprio(1); _Pragma("unroll") for (int m = 0; m < 4; ++m) _Pragma("unroll") for (int n = 0; n < 2; ++n) _Pragma("unroll") for (int k = 0; k < 2; ++k) \
;         acc[ai][bj][m][n] = __builtin_amdgcn_mfma_f32_16x16x32_bf16(Bt[n][k], At[m][k], acc[ai][bj][m][n], 0, 0, 0); __builtin_amdgcn_s_setprio(0); } while (0)
; #define PG8_WAIT_V(n) asm volatile("s_waitcnt vmcnt(" #n ")" ::: "memory")
; #define PG8_WAIT_L(n) asm volatile("s_waitcnt lgkmcnt(" #n ")" ::: "memory")
; #define PG8_BAR __builtin_amdgcn_s_barrier()
; #define PG8_SCHED __builtin_amdgcn_sched_barrier(0)
; template <class Epi, class Sched, bool ALIGN_EPI, bool LAST_FUSED = false, bool PERM = false, bool CARRY = false>
; __device__ __forceinline__ void gemm_phase(LAS unsigned char* lds, const int tid, const int K, const int lda, const int ldb, const Sched& S, const Epi& E) {
;     ...
;             PG8_WAIT_V(8); PG8_WAIT_L(0); PG8_BAR; PG8_MMA(1, 0, At, B0); PG8_MMA(1, 1, At, B1); PG8_BAR; PG8_SCHED;
;             PG8_LDB(B0, 1, 0); PG8_LDB(B1, 1, 1); PG8_SCHED; PG8_LDA(At, 1, 0); PG8_STAGE(PG8_SA(0, 1), a2 + hstepA, voffA);
;             PG8_WAIT_V(8); PG8_WAIT_L(0); PG8_BAR; PG8_MMA(0, 0, At, B0); PG8_MMA(0, 1, At, B1); PG8_BAR; PG8_SCHED;
	s_setprio 1
	s_waitcnt lgkmcnt(0)
	v_mfma_f32_16x16x32_bf16 v[62:65], v[148:151], v[180:183], v[62:65]
	v_mfma_f32_16x16x32_bf16 v[58:61], v[156:159], v[180:183], v[58:61]
	v_mfma_f32_16x16x32_bf16 v[46:49], v[148:151], v[188:191], v[46:49]
	v_mfma_f32_16x16x32_bf16 v[42:45], v[156:159], v[188:191], v[42:45]
	v_mfma_f32_16x16x32_bf16 v[30:33], v[148:151], v[196:199], v[30:33]
	v_mfma_f32_16x16x32_bf16 v[26:29], v[156:159], v[196:199], v[26:29]
	v_mfma_f32_16x16x32_bf16 v[14:17], v[148:151], v[204:207], v[14:17]
	v_mfma_f32_16x16x32_bf16 v[10:13], v[156:159], v[204:207], v[10:13]
	v_mfma_f32_16x16x32_bf16 v[62:65], v[152:155], v[184:187], v[62:65]
	v_mfma_f32_16x16x32_bf16 v[58:61], v[160:163], v[184:187], v[58:61]
	v_mfma_f32_16x16x32_bf16 v[46:49], v[152:155], v[192:195], v[46:49]
	v_mfma_f32_16x16x32_bf16 v[42:45], v[160:163], v[192:195], v[42:45]
	v_mfma_f32_16x16x32_bf16 v[30:33], v[152:155], v[200:203], v[30:33]
	v_mfma_f32_16x16x32_bf16 v[26:29], v[160:163], v[200:203], v[26:29]
	v_mfma_f32_16x16x32_bf16 v[14:17], v[152:155], v[208:211], v[14:17]
	v_mfma_f32_16x16x32_bf16 v[10:13], v[160:163], v[208:211], v[10:13]
	s_setprio 0
	s_setprio 1
	v_mfma_f32_16x16x32_bf16 v[54:57], v[164:167], v[180:183], v[54:57]
	v_mfma_f32_16x16x32_bf16 v[50:53], v[172:175], v[180:183], v[50:53]
	v_mfma_f32_16x16x32_bf16 v[38:41], v[164:167], v[188:191], v[38:41]
	v_mfma_f32_16x16x32_bf16 v[34:37], v[172:175], v[188:191], v[34:37]
	v_mfma_f32_16x16x32_bf16 v[22:25], v[164:167], v[196:199], v[22:25]
	v_mfma_f32_16x16x32_bf16 v[18:21], v[172:175], v[196:199], v[18:21]
	v_mfma_f32_16x16x32_bf16 v[6:9], v[164:167], v[204:207], v[6:9]
	v_mfma_f32_16x16x32_bf16 v[2:5], v[172:175], v[204:207], v[2:5]
	v_mfma_f32_16x16x32_bf16 v[54:57], v[168:171], v[184:187], v[54:57]
	v_mfma_f32_16x16x32_bf16 v[50:53], v[176:179], v[184:187], v[50:53]
	v_mfma_f32_16x16x32_bf16 v[38:41], v[168:171], v[192:195], v[38:41]
	v_mfma_f32_16x16x32_bf16 v[34:37], v[176:179], v[192:195], v[34:37]
	v_mfma_f32_16x16x32_bf16 v[22:25], v[168:171], v[200:203], v[22:25]
	v_mfma_f32_16x16x32_bf16 v[18:21], v[176:179], v[200:203], v[18:21]
	v_mfma_f32_16x16x32_bf16 v[6:9], v[168:171], v[208:211], v[6:9]
	v_mfma_f32_16x16x32_bf16 v[2:5], v[176:179], v[208:211], v[2:5]
	s_setprio 0
	s_barrier
	s_add_i32 s16, 0, 0x18000
	s_add_i32 s17, 0, 0x1c000
	v_add_u32_e32 v160, s16, v146
	v_add_u32_e32 v176, s17, v146
	ds_read_b128 v[148:151], v160
	ds_read_b128 v[152:155], v160 offset:1024
	ds_read_b128 v[156:159], v160 offset:2048
	ds_read_b128 v[160:163], v160 offset:3072
	ds_read_b128 v[164:167], v176
	ds_read_b128 v[168:171], v176 offset:1024
	ds_read_b128 v[172:175], v176 offset:2048
	ds_read_b128 v[176:179], v176 offset:3072
	s_add_u32 s52, s52, 0x80000
	s_addc_u32 s53, s53, 0
	s_mov_b32 m0, s58
	v_lshl_add_u64 v[218:219], s[52:53], 0, v[134:135]
	ds_read_b128 v[180:183], v147 offset:32768
	ds_read_b128 v[184:187], v147 offset:33792
	ds_read_b128 v[188:191], v147 offset:34816
	ds_read_b128 v[192:195], v147 offset:35840
	ds_read_b128 v[196:199], v147 offset:36864
	ds_read_b128 v[200:203], v147 offset:37888
	ds_read_b128 v[204:207], v147 offset:38912
	ds_read_b128 v[208:211], v147 offset:39936
	global_load_lds_dwordx4 v[218:219], off
	v_lshl_add_u64 v[218:219], s[52:53], 0, v[132:133]
	s_mov_b32 m0, s59
	s_nop 0
	global_load_lds_dwordx4 v[218:219], off
	s_waitcnt vmcnt(8)
	s_waitcnt lgkmcnt(0)
	s_barrier
	s_setprio 1
	s_waitcnt lgkmcnt(0)
	v_mfma_f32_16x16x32_bf16 v[126:129], v[148:151], v[180:183], v[126:129]
	v_mfma_f32_16x16x32_bf16 v[122:125], v[156:159], v[180:183], v[122:125]
	v_mfma_f32_16x16x32_bf16 v[110:113], v[148:151], v[188:191], v[110:113]
	v_mfma_f32_16x16x32_bf16 v[106:109], v[156:159], v[188:191], v[106:109]
	v_mfma_f32_16x16x32_bf16 v[94:97], v[148:151], v[196:199], v[94:97]
	v_mfma_f32_16x16x32_bf16 v[90:93], v[156:159], v[196:199], v[90:93]
	v_mfma_f32_16x16x32_bf16 v[78:81], v[148:151], v[204:207], v[78:81]
	v_mfma_f32_16x16x32_bf16 v[74:77], v[156:159], v[204:207], v[74:77]
	v_mfma_f32_16x16x32_bf16 v[126:129], v[152:155], v[184:187], v[126:129]
	v_mfma_f32_16x16x32_bf16 v[122:125], v[160:163], v[184:187], v[122:125]
	v_mfma_f32_16x16x32_bf16 v[110:113], v[152:155], v[192:195], v[110:113]
	v_mfma_f32_16x16x32_bf16 v[106:109], v[160:163], v[192:195], v[106:109]
	v_mfma_f32_16x16x32_bf16 v[94:97], v[152:155], v[200:203], v[94:97]
	v_mfma_f32_16x16x32_bf16 v[90:93], v[160:163], v[200:203], v[90:93]
	v_mfma_f32_16x16x32_bf16 v[78:81], v[152:155], v[208:211], v[78:81]
	v_mfma_f32_16x16x32_bf16 v[74:77], v[160:163], v[208:211], v[74:77]
	s_setprio 0
	s_setprio 1
	v_mfma_f32_16x16x32_bf16 v[118:121], v[164:167], v[180:183], v[118:121]
	v_mfma_f32_16x16x32_bf16 v[114:117], v[172:175], v[180:183], v[114:117]
	v_mfma_f32_16x16x32_bf16 v[102:105], v[164:167], v[188:191], v[102:105]
	v_mfma_f32_16x16x32_bf16 v[98:101], v[172:175], v[188:191], v[98:101]
	v_mfma_f32_16x16x32_bf16 v[86:89], v[164:167], v[196:199], v[86:89]
	v_mfma_f32_16x16x32_bf16 v[82:85], v[172:175], v[196:199], v[82:85]
	v_mfma_f32_16x16x32_bf16 v[70:73], v[164:167], v[204:207], v[70:73]
	v_mfma_f32_16x16x32_bf16 v[66:69], v[172:175], v[204:207], v[66:69]
	v_mfma_f32_16x16x32_bf16 v[118:121], v[168:171], v[184:187], v[118:121]
	v_mfma_f32_16x16x32_bf16 v[114:117], v[176:179], v[184:187], v[114:117]
	v_mfma_f32_16x16x32_bf16 v[102:105], v[168:171], v[192:195], v[102:105]
	v_mfma_f32_16x16x32_bf16 v[98:101], v[176:179], v[192:195], v[98:101]
	v_mfma_f32_16x16x32_bf16 v[86:89], v[168:171], v[200:203], v[86:89]
	v_mfma_f32_16x16x32_bf16 v[82:85], v[176:179], v[200:203], v[82:85]
	v_mfma_f32_16x16x32_bf16 v[70:73], v[168:171], v[208:211], v[70:73]
	v_mfma_f32_16x16x32_bf16 v[66:69], v[176:179], v[208:211], v[66:69]
	s_setprio 0
	s_barrier
; #define PG8_STAGE(bufoff, gbase, voff) do { _Pragma("unroll") for (int _i = 0; _i < 2; ++_i) \
;         __builtin_amdgcn_global_load_lds((const unsigned*)((const char*)(gbase) + (voff)[_i]), (LAS unsigned*)(lds + (bufoff) + ldsw + _i * 8192), 16, 0, 0); } while (0)
; #define PG8_LDA(dst, b, h) do { _Pragma("unroll") for (int m = 0; m < 4; ++m) _Pragma("unroll") for (int k = 0; k < 2; ++k) dst[m][k] = *(const LAS bf16x8*)(lds + PG8_SA(b, h) + aoff + m * 2048 + k * 1024); } while (0)
; #define PG8_LDB(dst, b, h) do { _Pragma("unroll") for (int n = 0; n < 2; ++n) _Pragma("unroll") for (int k = 0; k < 2; ++k) dst[n][k] = *(const LAS bf16x8*)(lds + PG8_SB(b, h) + boff + n * 2048 + k * 1024); } while (0)
; template <class Epi, class Sched, bool ALIGN_EPI, bool LAST_FUSED = false, bool PERM = false, bool CARRY = false>
; __device__ __forceinline__ void gemm_phase(LAS unsigned char* lds, const int tid, const int K, const int lda, const int ldb, const Sched& S, const Epi& E) {
;     ...
;         for (int t = 0; t < nt; t += 2) {
;             const bool last = (t == nt - 2);
;             const char* a1 = cA + (size_t)(t + 1) * kstep;
;             const char* a2 = last ? nA : cA + (size_t)(t + 2) * kstep; const char* b2 = last ? nB : cB + (size_t)(t + 2) * kstep;
;             const char* a3 = a2 + kstep; const char* b3 = b2 + kstep;
;             PG8_LDB(B0, 0, 0); PG8_LDB(B1, 0, 1); PG8_SCHED; PG8_LDA(At, 0, 0); PG8_STAGE(PG8_SA(1, 1), a1 + hstepA, voffA);
;             PG8_WAIT_V(8); PG8_WAIT_L(0); PG8_BAR; PG8_MMA(0, 0, At, B0); PG8_MMA(0, 1, At, B1); PG8_BAR; PG8_SCHED;
;             PG8_LDA(At, 0, 1); PG8_STAGE(PG8_SB(0, 0), b2, voffB); PG8_STAGE(PG8_SB(0, 1), b2 + hstepB, voffB); PG8_STAGE(PG8_SA(0, 0), a2, voffA);
;             PG8_WAIT_V(8); PG8_WAIT_L(0); PG8_BAR; PG8_MMA(1, 0, At, B0); PG8_MMA(1, 1, At, B1); PG8_BAR; PG8_SCHED;
;             PG8_LDB(B0, 1, 0); PG8_LDB(B1, 1, 1); PG8_SCHED; PG8_LDA(At, 1, 0); PG8_STAGE(PG8_SA(0, 1), a2 + hstepA, voffA);
;             PG8_WAIT_V(8); PG8_WAIT_L(0); PG8_BAR; PG8_MMA(0, 0, At, B0); PG8_MMA(0, 1, At, B1); PG8_BAR; PG8_SCHED;
;             PG8_LDA(At, 1, 1); PG8_STAGE(PG8_SB(1, 0), b3, voffB); PG8_STAGE(PG8_SB(1, 1), b3 + hstepB, voffB); PG8_STAGE(PG8_SA(1, 0), a3, voffA);
;             PG8_WAIT_V(8); PG8_WAIT_L(0); PG8_BAR; PG8_MMA(1, 0, At, B0); PG8_MMA(1, 1, At, B1); PG8_BAR; PG8_SCHED;
	s_add_i32 s16, s16, s45
	v_lshl_add_u64 v[140:141], v[140:141], 0, s[68:69]
	s_mov_b32 m0, s16
	ds_read_b128 v[180:183], v147 offset:49152
	ds_read_b128 v[184:187], v147 offset:50176
	ds_read_b128 v[188:191], v147 offset:51200
	ds_read_b128 v[192:195], v147 offset:52224
	ds_read_b128 v[196:199], v147 offset:53248
	ds_read_b128 v[200:203], v147 offset:54272
	ds_read_b128 v[204:207], v147 offset:55296
	ds_read_b128 v[208:211], v147 offset:56320
	global_load_lds_dwordx4 v[140:141], off
	s_add_i32 m0, s16, 0x2000
	s_add_u32 s52, s54, 0x80080
	v_lshl_add_u64 v[140:141], v[212:213], 0, s[68:69]
	s_addc_u32 s53, s55, 0
	s_add_i32 s16, s17, s45
	global_load_lds_dwordx4 v[140:141], off
	v_lshl_add_u64 v[140:141], s[52:53], 0, v[0:1]
	s_mov_b32 m0, s16
	s_nop 0
	global_load_lds_dwordx4 v[140:141], off
	v_lshl_add_u64 v[140:141], s[52:53], 0, v[130:131]
	s_add_i32 m0, s16, 0x2000
	s_nop 0
	global_load_lds_dwordx4 v[140:141], off
	v_lshl_add_u64 v[140:141], v[214:215], 0, s[68:69]
	s_mov_b32 m0, s61
	s_nop 0
	global_load_lds_dwordx4 v[140:141], off
	v_lshl_add_u64 v[140:141], v[216:217], 0, s[68:69]
	s_mov_b32 m0, s62
	s_nop 0
	global_load_lds_dwordx4 v[140:141], off
	s_waitcnt vmcnt(8)
	s_waitcnt lgkmcnt(0)
	s_barrier
	s_setprio 1
	s_waitcnt lgkmcnt(0)
	v_mfma_f32_16x16x32_bf16 v[62:65], v[148:151], v[180:183], v[62:65]
	v_mfma_f32_16x16x32_bf16 v[58:61], v[156:159], v[180:183], v[58:61]
	v_mfma_f32_16x16x32_bf16 v[46:49], v[148:151], v[188:191], v[46:49]
	v_mfma_f32_16x16x32_bf16 v[42:45], v[156:159], v[188:191], v[42:45]
	v_mfma_f32_16x16x32_bf16 v[30:33], v[148:151], v[196:199], v[30:33]
	v_mfma_f32_16x16x32_bf16 v[26:29], v[156:159], v[196:199], v[26:29]
	v_mfma_f32_16x16x32_bf16 v[14:17], v[148:151], v[204:207], v[14:17]
	v_mfma_f32_16x16x32_bf16 v[10:13], v[156:159], v[204:207], v[10:13]
	v_mfma_f32_16x16x32_bf16 v[62:65], v[152:155], v[184:187], v[62:65]
	v_mfma_f32_16x16x32_bf16 v[58:61], v[160:163], v[184:187], v[58:61]
	v_mfma_f32_16x16x32_bf16 v[46:49], v[152:155], v[192:195], v[46:49]
	v_mfma_f32_16x16x32_bf16 v[42:45], v[160:163], v[192:195], v[42:45]
	v_mfma_f32_16x16x32_bf16 v[30:33], v[152:155], v[200:203], v[30:33]
	v_mfma_f32_16x16x32_bf16 v[26:29], v[160:163], v[200:203], v[26:29]
	v_mfma_f32_16x16x32_bf16 v[14:17], v[152:155], v[208:211], v[14:17]
	v_mfma_f32_16x16x32_bf16 v[10:13], v[160:163], v[208:211], v[10:13]
	s_setprio 0
	s_setprio 1
	v_mfma_f32_16x16x32_bf16 v[54:57], v[164:167], v[180:183], v[54:57]
	v_mfma_f32_16x16x32_bf16 v[50:53], v[172:175], v[180:183], v[50:53]
	v_mfma_f32_16x16x32_bf16 v[38:41], v[164:167], v[188:191], v[38:41]
	v_mfma_f32_16x16x32_bf16 v[34:37], v[172:175], v[188:191], v[34:37]
	v_mfma_f32_16x16x32_bf16 v[22:25], v[164:167], v[196:199], v[22:25]
	v_mfma_f32_16x16x32_bf16 v[18:21], v[172:175], v[196:199], v[18:21]
	v_mfma_f32_16x16x32_bf16 v[6:9], v[164:167], v[204:207], v[6:9]
	v_mfma_f32_16x16x32_bf16 v[2:5], v[172:175], v[204:207], v[2:5]
	v_mfma_f32_16x16x32_bf16 v[54:57], v[168:171], v[184:187], v[54:57]
	v_mfma_f32_16x16x32_bf16 v[50:53], v[176:179], v[184:187], v[50:53]
	v_mfma_f32_16x16x32_bf16 v[38:41], v[168:171], v[192:195], v[38:41]
	v_mfma_f32_16x16x32_bf16 v[34:37], v[176:179], v[192:195], v[34:37]
	v_mfma_f32_16x16x32_bf16 v[22:25], v[168:171], v[200:203], v[22:25]
	v_mfma_f32_16x16x32_bf16 v[18:21], v[176:179], v[200:203], v[18:21]
	v_mfma_f32_16x16x32_bf16 v[6:9], v[168:171], v[208:211], v[6:9]
	v_mfma_f32_16x16x32_bf16 v[2:5], v[176:179], v[208:211], v[2:5]
	s_add_i32 s41, s41, 2
	s_add_u32 s48, s48, 0x100
	s_addc_u32 s49, s49, 0
	s_add_u32 s27, s27, 0x100
	s_addc_u32 s39, s39, 0
	s_cmp_gt_u32 s41, 29
	s_setprio 0
	s_barrier
	s_cbranch_scc0 .LBB0_1763
	s_and_b64 vcc, exec, s[36:37]
	s_cbranch_vccz .LBB0_1766
	s_barrier

; #define PG8_STAGE(bufoff, gbase, voff) do { _Pragma("unroll") for (int _i = 0; _i < 2; ++_i) \
;         __builtin_amdgcn_global_load_lds((const unsigned*)((const char*)(gbase) + (voff)[_i]), (LAS unsigned*)(lds + (bufoff) + ldsw + _i * 8192), 16, 0, 0); } while (0)
; #define PG8_LDA(dst, b, h) do { _Pragma("unroll") for (int m = 0; m < 4; ++m) _Pragma("unroll") for (int k = 0; k < 2; ++k) dst[m][k] = *(const LAS bf16x8*)(lds + PG8_SA(b, h) + aoff + m * 2048 + k * 1024); } while (0)
; #define PG8_LDB(dst, b, h) do { _Pragma("unroll") for (int n = 0; n < 2; ++n) _Pragma("unroll") for (int k = 0; k < 2; ++k) dst[n][k] = *(const LAS bf16x8*)(lds + PG8_SB(b, h) + boff + n * 2048 + k * 1024); } while (0)
; #define PG8_MMA(ai, bj, At, Bt) do { __builtin_amdgcn_s_setprio(1); _Pragma("unroll") for (int m = 0; m < 4; ++m) _Pragma("unroll") for (int n = 0; n < 2; ++n) _Pragma("unroll") for (int k = 0; k < 2; ++k) \
;         acc[ai][bj][m][n] = __builtin_amdgcn_mfma_f32_16x16x32_bf16(Bt[n][k], At[m][k], acc[ai][bj][m][n], 0, 0, 0); __builtin_amdgcn_s_setprio(0); } while (0)
; #define PG8_WAIT_V(n) asm volatile("s_waitcnt vmcnt(" #n ")" ::: "memory")
; #define PG8_WAIT_L(n) asm volatile("s_waitcnt lgkmcnt(" #n ")" ::: "memory")
; template <class Epi, class Sched, bool ALIGN_EPI, bool LAST_FUSED = false, bool PERM = false, bool CARRY = false>
; __device__ __forceinline__ void gemm_phase(LAS unsigned char* lds, const int tid, const int K, const int lda, const int ldb, const Sched& S, const Epi& E) {
;     ...
;         for (int t = 0; t < nt; t += 2) {
;             const bool last = (t == nt - 2);
;             const char* a1 = cA + (size_t)(t + 1) * kstep;
;             const char* a2 = last ? nA : cA + (size_t)(t + 2) * kstep; const char* b2 = last ? nB : cB + (size_t)(t + 2) * kstep;
;             const char* a3 = a2 + kstep; const char* b3 = b2 + kstep;
;             PG8_LDB(B0, 0, 0); PG8_LDB(B1, 0, 1); PG8_SCHED; PG8_LDA(At, 0, 0); PG8_STAGE(PG8_SA(1, 1), a1 + hstepA, voffA);
;             PG8_WAIT_V(8); PG8_WAIT_L(0); PG8_BAR; PG8_MMA(0, 0, At, B0); PG8_MMA(0, 1, At, B1); PG8_BAR; PG8_SCHED;
;             PG8_LDA(At, 0, 1); PG8_STAGE(PG8_SB(0, 0), b2, voffB); PG8_STAGE(PG8_SB(0, 1), b2 + hstepB, voffB); PG8_STAGE(PG8_SA(0, 0), a2, voffA);
;             PG8_WAIT_V(8); PG8_WAIT_L(0); PG8_BAR; PG8_MMA(1, 0, At, B0); PG8_MMA(1, 1, At, B1); PG8_BAR; PG8_SCHED;
.LBB0_1854:
	s_add_u32 s16, s66, vcc_lo
	s_addc_u32 s17, s67, vcc_hi
	s_add_u32 s52, s50, vcc_lo
	s_addc_u32 s53, s51, vcc_hi
	s_add_i32 s92, 0, 0x10000
	s_cmp_eq_u32 s87, s60
	s_cselect_b32 s57, s24, s17
	s_cselect_b32 s56, s91, s16
	v_add_u32_e32 v154, s92, v140
	s_cselect_b32 s53, s70, s53
	s_cselect_b32 s52, s71, s52
	s_add_i32 s93, 0, 0x14000
	ds_read_b128 v[142:145], v154
	ds_read_b128 v[146:149], v154 offset:1024
	ds_read_b128 v[150:153], v154 offset:2048
	ds_read_b128 v[158:161], v154 offset:3072
	v_add_u32_e32 v154, s93, v140
	ds_read_b128 v[162:165], v154
	ds_read_b128 v[166:169], v154 offset:1024
	ds_read_b128 v[170:173], v154 offset:2048
	ds_read_b128 v[174:177], v154 offset:3072
	v_lshl_add_u64 v[154:155], s[66:67], 0, v[138:139]
	s_add_i32 m0, s28, 0xc000
	ds_read_b128 v[178:181], v141
	ds_read_b128 v[182:185], v141 offset:1024
	ds_read_b128 v[186:189], v141 offset:2048
	ds_read_b128 v[190:193], v141 offset:3072
	ds_read_b128 v[194:197], v141 offset:4096
	ds_read_b128 v[198:201], v141 offset:5120
	ds_read_b128 v[202:205], v141 offset:6144
	ds_read_b128 v[206:209], v141 offset:7168
	global_load_lds_dwordx4 v[154:155], off
	v_lshl_add_u64 v[154:155], s[66:67], 0, v[128:129]
	s_add_i32 m0, s28, 0xe000
	s_nop 0
	global_load_lds_dwordx4 v[154:155], off
	s_waitcnt vmcnt(8)
	s_waitcnt lgkmcnt(0)
	s_barrier
	s_setprio 1
	s_waitcnt lgkmcnt(0)
	v_mfma_f32_16x16x32_bf16 v[118:121], v[142:145], v[178:181], v[118:121]
	v_mfma_f32_16x16x32_bf16 v[114:117], v[150:153], v[178:181], v[114:117]
	v_mfma_f32_16x16x32_bf16 v[110:113], v[142:145], v[186:189], v[110:113]
	v_mfma_f32_16x16x32_bf16 v[106:109], v[150:153], v[186:189], v[106:109]
	v_mfma_f32_16x16x32_bf16 v[86:89], v[142:145], v[194:197], v[86:89]
	v_mfma_f32_16x16x32_bf16 v[82:85], v[150:153], v[194:197], v[82:85]
	v_mfma_f32_16x16x32_bf16 v[78:81], v[142:145], v[202:205], v[78:81]
	v_mfma_f32_16x16x32_bf16 v[74:77], v[150:153], v[202:205], v[74:77]
	v_mfma_f32_16x16x32_bf16 v[118:121], v[146:149], v[182:185], v[118:121]
	v_mfma_f32_16x16x32_bf16 v[114:117], v[158:161], v[182:185], v[114:117]
	v_mfma_f32_16x16x32_bf16 v[110:113], v[146:149], v[190:193], v[110:113]
	v_mfma_f32_16x16x32_bf16 v[106:109], v[158:161], v[190:193], v[106:109]
	v_mfma_f32_16x16x32_bf16 v[86:89], v[146:149], v[198:201], v[86:89]
	v_mfma_f32_16x16x32_bf16 v[82:85], v[158:161], v[198:201], v[82:85]
	v_mfma_f32_16x16x32_bf16 v[78:81], v[146:149], v[206:209], v[78:81]
	v_mfma_f32_16x16x32_bf16 v[74:77], v[158:161], v[206:209], v[74:77]
	s_setprio 0
	s_setprio 1
	v_mfma_f32_16x16x32_bf16 v[98:101], v[162:165], v[178:181], v[98:101]
	v_mfma_f32_16x16x32_bf16 v[102:105], v[170:173], v[178:181], v[102:105]
	v_mfma_f32_16x16x32_bf16 v[90:93], v[162:165], v[186:189], v[90:93]
	v_mfma_f32_16x16x32_bf16 v[94:97], v[170:173], v[186:189], v[94:97]
	v_mfma_f32_16x16x32_bf16 v[66:69], v[162:165], v[194:197], v[66:69]
	v_mfma_f32_16x16x32_bf16 v[70:73], v[170:173], v[194:197], v[70:73]
	v_mfma_f32_16x16x32_bf16 v[50:53], v[162:165], v[202:205], v[50:53]
	v_mfma_f32_16x16x32_bf16 v[54:57], v[170:173], v[202:205], v[54:57]
	v_mfma_f32_16x16x32_bf16 v[98:101], v[166:169], v[182:185], v[98:101]
	v_mfma_f32_16x16x32_bf16 v[102:105], v[174:177], v[182:185], v[102:105]
	v_mfma_f32_16x16x32_bf16 v[90:93], v[166:169], v[190:193], v[90:93]
	v_mfma_f32_16x16x32_bf16 v[94:97], v[174:177], v[190:193], v[94:97]
	v_mfma_f32_16x16x32_bf16 v[66:69], v[166:169], v[198:201], v[66:69]
	v_mfma_f32_16x16x32_bf16 v[70:73], v[174:177], v[198:201], v[70:73]
	v_mfma_f32_16x16x32_bf16 v[50:53], v[166:169], v[206:209], v[50:53]
	v_mfma_f32_16x16x32_bf16 v[54:57], v[174:177], v[206:209], v[54:57]
	s_setprio 0
	s_barrier
	s_add_i32 s16, s92, s95
	v_lshl_add_u64 v[154:155], s[52:53], 0, v[0:1]
	s_mov_b32 m0, s16
	ds_read_b128 v[178:181], v141 offset:16384
	ds_read_b128 v[182:185], v141 offset:17408
	ds_read_b128 v[186:189], v141 offset:18432
	ds_read_b128 v[190:193], v141 offset:19456
	ds_read_b128 v[194:197], v141 offset:20480
	ds_read_b128 v[198:201], v141 offset:21504
	ds_read_b128 v[202:205], v141 offset:22528
	ds_read_b128 v[206:209], v141 offset:23552
	global_load_lds_dwordx4 v[154:155], off
	s_add_i32 m0, s16, 0x2000
	s_add_u32 s16, s52, 0x200000
	v_lshl_add_u64 v[210:211], s[52:53], 0, v[122:123]
	s_addc_u32 s17, s53, 0
	s_add_i32 s92, s93, s95
	global_load_lds_dwordx4 v[210:211], off
	v_lshl_add_u64 v[212:213], s[16:17], 0, v[0:1]
	s_mov_b32 m0, s92
	v_lshl_add_u64 v[214:215], s[56:57], 0, v[122:123]
	global_load_lds_dwordx4 v[212:213], off
	v_lshl_add_u64 v[212:213], s[16:17], 0, v[122:123]
	s_add_i32 m0, s92, 0x2000
	s_nop 0
	global_load_lds_dwordx4 v[212:213], off
	v_lshl_add_u64 v[212:213], s[56:57], 0, v[0:1]
	s_mov_b32 m0, s28
	s_nop 0
	global_load_lds_dwordx4 v[212:213], off
	s_mov_b32 m0, s29
	s_nop 0
	global_load_lds_dwordx4 v[214:215], off
	s_waitcnt vmcnt(8)
	s_waitcnt lgkmcnt(0)
	s_barrier
; #define PG8_STAGE(bufoff, gbase, voff) do { _Pragma("unroll") for (int _i = 0; _i < 2; ++_i) \
;         __builtin_amdgcn_global_load_lds((const unsigned*)((const char*)(gbase) + (voff)[_i]), (LAS unsigned*)(lds + (bufoff) + ldsw + _i * 8192), 16, 0, 0); } while (0)
; #define PG8_LDA(dst, b, h) do { _Pragma("unroll") for (int m = 0; m < 4; ++m) _Pragma("unroll") for (int k = 0; k < 2; ++k) dst[m][k] = *(const LAS bf16x8*)(lds + PG8_SA(b, h) + aoff + m * 2048 + k * 1024); } while (0)
; #define PG8_LDB(dst, b, h) do { _Pragma("unroll") for (int n = 0; n < 2; ++n) _Pragma("unroll") for (int k = 0; k < 2; ++k) dst[n][k] = *(const LAS bf16x8*)(lds + PG8_SB(b, h) + boff + n * 2048 + k * 1024); } while (0)
; #define PG8_MMA(ai, bj, At, Bt) do { __builtin_amdgcn_s_setprio(1); _Pragma("unroll") for (int m = 0; m < 4; ++m) _Pragma("unroll") for (int n = 0; n < 2; ++n) _Pragma("unroll") for (int k = 0; k < 2; ++k) \
;         acc[ai][bj][m][n] = __builtin_amdgcn_mfma_f32_16x16x32_bf16(Bt[n][k], At[m][k], acc[ai][bj][m][n], 0, 0, 0); __builtin_amdgcn_s_setprio(0); } while (0)
; #define PG8_WAIT_V(n) asm volatile("s_waitcnt vmcnt(" #n ")" ::: "memory")
; #define PG8_WAIT_L(n) asm volatile("s_waitcnt lgkmcnt(" #n ")" ::: "memory")
; #define PG8_BAR __builtin_amdgcn_s_barrier()
; #define PG8_SCHED __builtin_amdgcn_sched_barrier(0)
; template <class Epi, class Sched, bool ALIGN_EPI, bool LAST_FUSED = false, bool PERM = false, bool CARRY = false>
; __device__ __forceinline__ void gemm_phase(LAS unsigned char* lds, const int tid, const int K, const int lda, const int ldb, const Sched& S, const Epi& E) {
;     ...
;             PG8_WAIT_V(8); PG8_WAIT_L(0); PG8_BAR; PG8_MMA(1, 0, At, B0); PG8_MMA(1, 1, At, B1); PG8_BAR; PG8_SCHED;
;             PG8_LDB(B0, 1, 0); PG8_LDB(B1, 1, 1); PG8_SCHED; PG8_LDA(At, 1, 0); PG8_STAGE(PG8_SA(0, 1), a2 + hstepA, voffA);
;             PG8_WAIT_V(8); PG8_WAIT_L(0); PG8_BAR; PG8_MMA(0, 0, At, B0); PG8_MMA(0, 1, At, B1); PG8_BAR; PG8_SCHED;
	s_setprio 1
	s_waitcnt lgkmcnt(0)
	v_mfma_f32_16x16x32_bf16 v[62:65], v[142:145], v[178:181], v[62:65]
	v_mfma_f32_16x16x32_bf16 v[58:61], v[150:153], v[178:181], v[58:61]
	v_mfma_f32_16x16x32_bf16 v[38:41], v[142:145], v[186:189], v[38:41]
	v_mfma_f32_16x16x32_bf16 v[34:37], v[150:153], v[186:189], v[34:37]
	v_mfma_f32_16x16x32_bf16 v[22:25], v[142:145], v[194:197], v[22:25]
	v_mfma_f32_16x16x32_bf16 v[18:21], v[150:153], v[194:197], v[18:21]
	v_mfma_f32_16x16x32_bf16 v[134:137], v[142:145], v[202:205], v[134:137]
	v_mfma_f32_16x16x32_bf16 v[130:133], v[150:153], v[202:205], v[130:133]
	v_mfma_f32_16x16x32_bf16 v[62:65], v[146:149], v[182:185], v[62:65]
	v_mfma_f32_16x16x32_bf16 v[58:61], v[158:161], v[182:185], v[58:61]
	v_mfma_f32_16x16x32_bf16 v[38:41], v[146:149], v[190:193], v[38:41]
	v_mfma_f32_16x16x32_bf16 v[34:37], v[158:161], v[190:193], v[34:37]
	v_mfma_f32_16x16x32_bf16 v[22:25], v[146:149], v[198:201], v[22:25]
	v_mfma_f32_16x16x32_bf16 v[18:21], v[158:161], v[198:201], v[18:21]
	v_mfma_f32_16x16x32_bf16 v[134:137], v[146:149], v[206:209], v[134:137]
	v_mfma_f32_16x16x32_bf16 v[130:133], v[158:161], v[206:209], v[130:133]
	s_setprio 0
	s_setprio 1
	v_mfma_f32_16x16x32_bf16 v[42:45], v[162:165], v[178:181], v[42:45]
	v_mfma_f32_16x16x32_bf16 v[46:49], v[170:173], v[178:181], v[46:49]
	v_mfma_f32_16x16x32_bf16 v[26:29], v[162:165], v[186:189], v[26:29]
	v_mfma_f32_16x16x32_bf16 v[30:33], v[170:173], v[186:189], v[30:33]
	v_mfma_f32_16x16x32_bf16 v[14:17], v[162:165], v[194:197], v[14:17]
	v_mfma_f32_16x16x32_bf16 v[10:13], v[170:173], v[194:197], v[10:13]
	v_mfma_f32_16x16x32_bf16 v[6:9], v[162:165], v[202:205], v[6:9]
	v_mfma_f32_16x16x32_bf16 v[2:5], v[170:173], v[202:205], v[2:5]
	v_mfma_f32_16x16x32_bf16 v[42:45], v[166:169], v[182:185], v[42:45]
	v_mfma_f32_16x16x32_bf16 v[46:49], v[174:177], v[182:185], v[46:49]
	v_mfma_f32_16x16x32_bf16 v[26:29], v[166:169], v[190:193], v[26:29]
	v_mfma_f32_16x16x32_bf16 v[30:33], v[174:177], v[190:193], v[30:33]
	v_mfma_f32_16x16x32_bf16 v[14:17], v[166:169], v[198:201], v[14:17]
	v_mfma_f32_16x16x32_bf16 v[10:13], v[174:177], v[198:201], v[10:13]
	v_mfma_f32_16x16x32_bf16 v[6:9], v[166:169], v[206:209], v[6:9]
	v_mfma_f32_16x16x32_bf16 v[2:5], v[174:177], v[206:209], v[2:5]
	s_setprio 0
	s_barrier
	s_add_i32 s92, 0, 0x18000
	s_add_i32 s93, 0, 0x1c000
	v_add_u32_e32 v158, s92, v140
	v_add_u32_e32 v174, s93, v140
	ds_read_b128 v[142:145], v158
	ds_read_b128 v[146:149], v158 offset:1024
	ds_read_b128 v[150:153], v158 offset:2048
	ds_read_b128 v[158:161], v158 offset:3072
	ds_read_b128 v[162:165], v174
	ds_read_b128 v[166:169], v174 offset:1024
	ds_read_b128 v[170:173], v174 offset:2048
	ds_read_b128 v[174:177], v174 offset:3072
	s_add_u32 s16, s56, 0x200000
	s_addc_u32 s17, s57, 0
	s_mov_b32 m0, s14
	v_lshl_add_u64 v[216:217], s[16:17], 0, v[0:1]
	ds_read_b128 v[178:181], v141 offset:32768
	ds_read_b128 v[182:185], v141 offset:33792
	ds_read_b128 v[186:189], v141 offset:34816
	ds_read_b128 v[190:193], v141 offset:35840
	ds_read_b128 v[194:197], v141 offset:36864
	ds_read_b128 v[198:201], v141 offset:37888
	ds_read_b128 v[202:205], v141 offset:38912
	ds_read_b128 v[206:209], v141 offset:39936
	global_load_lds_dwordx4 v[216:217], off
	v_lshl_add_u64 v[216:217], s[16:17], 0, v[122:123]
	s_mov_b32 m0, s22
	s_nop 0
	global_load_lds_dwordx4 v[216:217], off
	s_waitcnt vmcnt(8)
	s_waitcnt lgkmcnt(0)
	s_barrier
	s_setprio 1
	s_waitcnt lgkmcnt(0)
	v_mfma_f32_16x16x32_bf16 v[118:121], v[142:145], v[178:181], v[118:121]
	v_mfma_f32_16x16x32_bf16 v[114:117], v[150:153], v[178:181], v[114:117]
	v_mfma_f32_16x16x32_bf16 v[110:113], v[142:145], v[186:189], v[110:113]
	v_mfma_f32_16x16x32_bf16 v[106:109], v[150:153], v[186:189], v[106:109]
	v_mfma_f32_16x16x32_bf16 v[86:89], v[142:145], v[194:197], v[86:89]
	v_mfma_f32_16x16x32_bf16 v[82:85], v[150:153], v[194:197], v[82:85]
	v_mfma_f32_16x16x32_bf16 v[78:81], v[142:145], v[202:205], v[78:81]
	v_mfma_f32_16x16x32_bf16 v[74:77], v[150:153], v[202:205], v[74:77]
	v_mfma_f32_16x16x32_bf16 v[118:121], v[146:149], v[182:185], v[118:121]
	v_mfma_f32_16x16x32_bf16 v[114:117], v[158:161], v[182:185], v[114:117]
	v_mfma_f32_16x16x32_bf16 v[110:113], v[146:149], v[190:193], v[110:113]
	v_mfma_f32_16x16x32_bf16 v[106:109], v[158:161], v[190:193], v[106:109]
	v_mfma_f32_16x16x32_bf16 v[86:89], v[146:149], v[198:201], v[86:89]
	v_mfma_f32_16x16x32_bf16 v[82:85], v[158:161], v[198:201], v[82:85]
	v_mfma_f32_16x16x32_bf16 v[78:81], v[146:149], v[206:209], v[78:81]
	v_mfma_f32_16x16x32_bf16 v[74:77], v[158:161], v[206:209], v[74:77]
	s_setprio 0
	s_setprio 1
	v_mfma_f32_16x16x32_bf16 v[98:101], v[162:165], v[178:181], v[98:101]
	v_mfma_f32_16x16x32_bf16 v[102:105], v[170:173], v[178:181], v[102:105]
	v_mfma_f32_16x16x32_bf16 v[90:93], v[162:165], v[186:189], v[90:93]
	v_mfma_f32_16x16x32_bf16 v[94:97], v[170:173], v[186:189], v[94:97]
	v_mfma_f32_16x16x32_bf16 v[66:69], v[162:165], v[194:197], v[66:69]
	v_mfma_f32_16x16x32_bf16 v[70:73], v[170:173], v[194:197], v[70:73]
	v_mfma_f32_16x16x32_bf16 v[50:53], v[162:165], v[202:205], v[50:53]
	v_mfma_f32_16x16x32_bf16 v[54:57], v[170:173], v[202:205], v[54:57]
	v_mfma_f32_16x16x32_bf16 v[98:101], v[166:169], v[182:185], v[98:101]
	v_mfma_f32_16x16x32_bf16 v[102:105], v[174:177], v[182:185], v[102:105]
	v_mfma_f32_16x16x32_bf16 v[90:93], v[166:169], v[190:193], v[90:93]
	v_mfma_f32_16x16x32_bf16 v[94:97], v[174:177], v[190:193], v[94:97]
	v_mfma_f32_16x16x32_bf16 v[66:69], v[166:169], v[198:201], v[66:69]
	v_mfma_f32_16x16x32_bf16 v[70:73], v[174:177], v[198:201], v[70:73]
	v_mfma_f32_16x16x32_bf16 v[50:53], v[166:169], v[206:209], v[50:53]
	v_mfma_f32_16x16x32_bf16 v[54:57], v[174:177], v[206:209], v[54:57]
	s_setprio 0
	s_barrier
; #define PG8_STAGE(bufoff, gbase, voff) do { _Pragma("unroll") for (int _i = 0; _i < 2; ++_i) \
;         __builtin_amdgcn_global_load_lds((const unsigned*)((const char*)(gbase) + (voff)[_i]), (LAS unsigned*)(lds + (bufoff) + ldsw + _i * 8192), 16, 0, 0); } while (0)
; #define PG8_LDA(dst, b, h) do { _Pragma("unroll") for (int m = 0; m < 4; ++m) _Pragma("unroll") for (int k = 0; k < 2; ++k) dst[m][k] = *(const LAS bf16x8*)(lds + PG8_SA(b, h) + aoff + m * 2048 + k * 1024); } while (0)
; #define PG8_LDB(dst, b, h) do { _Pragma("unroll") for (int n = 0; n < 2; ++n) _Pragma("unroll") for (int k = 0; k < 2; ++k) dst[n][k] = *(const LAS bf16x8*)(lds + PG8_SB(b, h) + boff + n * 2048 + k * 1024); } while (0)
; template <class Epi, class Sched, bool ALIGN_EPI, bool LAST_FUSED = false, bool PERM = false, bool CARRY = false>
; __device__ __forceinline__ void gemm_phase(LAS unsigned char* lds, const int tid, const int K, const int lda, const int ldb, const Sched& S, const Epi& E) {
;     ...
;         for (int t = 0; t < nt; t += 2) {
;             const bool last = (t == nt - 2);
;             const char* a1 = cA + (size_t)(t + 1) * kstep;
;             const char* a2 = last ? nA : cA + (size_t)(t + 2) * kstep; const char* b2 = last ? nB : cB + (size_t)(t + 2) * kstep;
;             const char* a3 = a2 + kstep; const char* b3 = b2 + kstep;
;             PG8_LDB(B0, 0, 0); PG8_LDB(B1, 0, 1); PG8_SCHED; PG8_LDA(At, 0, 0); PG8_STAGE(PG8_SA(1, 1), a1 + hstepA, voffA);
;             PG8_WAIT_V(8); PG8_WAIT_L(0); PG8_BAR; PG8_MMA(0, 0, At, B0); PG8_MMA(0, 1, At, B1); PG8_BAR; PG8_SCHED;
;             PG8_LDA(At, 0, 1); PG8_STAGE(PG8_SB(0, 0), b2, voffB); PG8_STAGE(PG8_SB(0, 1), b2 + hstepB, voffB); PG8_STAGE(PG8_SA(0, 0), a2, voffA);
;             PG8_WAIT_V(8); PG8_WAIT_L(0); PG8_BAR; PG8_MMA(1, 0, At, B0); PG8_MMA(1, 1, At, B1); PG8_BAR; PG8_SCHED;
;             PG8_LDB(B0, 1, 0); PG8_LDB(B1, 1, 1); PG8_SCHED; PG8_LDA(At, 1, 0); PG8_STAGE(PG8_SA(0, 1), a2 + hstepA, voffA);
;             PG8_WAIT_V(8); PG8_WAIT_L(0); PG8_BAR; PG8_MMA(0, 0, At, B0); PG8_MMA(0, 1, At, B1); PG8_BAR; PG8_SCHED;
;             PG8_LDA(At, 1, 1); PG8_STAGE(PG8_SB(1, 0), b3, voffB); PG8_STAGE(PG8_SB(1, 1), b3 + hstepB, voffB); PG8_STAGE(PG8_SA(1, 0), a3, voffA);
;             PG8_WAIT_V(8); PG8_WAIT_L(0); PG8_BAR; PG8_MMA(1, 0, At, B0); PG8_MMA(1, 1, At, B1); PG8_BAR; PG8_SCHED;
	s_add_i32 s16, s92, s95
	v_lshl_add_u64 v[154:155], v[154:155], 0, s[68:69]
	s_mov_b32 m0, s16
	ds_read_b128 v[178:181], v141 offset:49152
	ds_read_b128 v[182:185], v141 offset:50176
	ds_read_b128 v[186:189], v141 offset:51200
	ds_read_b128 v[190:193], v141 offset:52224
	ds_read_b128 v[194:197], v141 offset:53248
	ds_read_b128 v[198:201], v141 offset:54272
	ds_read_b128 v[202:205], v141 offset:55296
	ds_read_b128 v[206:209], v141 offset:56320
	global_load_lds_dwordx4 v[154:155], off
	s_add_i32 m0, s16, 0x2000
	s_add_u32 s16, s52, 0x200080
	v_lshl_add_u64 v[154:155], v[210:211], 0, s[68:69]
	s_addc_u32 s17, s53, 0
	s_add_i32 s52, s93, s95
	global_load_lds_dwordx4 v[154:155], off
	v_lshl_add_u64 v[154:155], s[16:17], 0, v[0:1]
	s_mov_b32 m0, s52
	s_nop 0
	global_load_lds_dwordx4 v[154:155], off
	v_lshl_add_u64 v[154:155], s[16:17], 0, v[122:123]
	s_add_i32 m0, s52, 0x2000
	s_nop 0
	global_load_lds_dwordx4 v[154:155], off
	v_lshl_add_u64 v[154:155], v[212:213], 0, s[68:69]
	s_mov_b32 m0, s96
	s_nop 0
	global_load_lds_dwordx4 v[154:155], off
	v_lshl_add_u64 v[154:155], v[214:215], 0, s[68:69]
	s_mov_b32 m0, s97
	s_nop 0
	global_load_lds_dwordx4 v[154:155], off
	s_waitcnt vmcnt(8)
	s_waitcnt lgkmcnt(0)
	s_barrier
	s_setprio 1
	s_waitcnt lgkmcnt(0)
	v_mfma_f32_16x16x32_bf16 v[62:65], v[142:145], v[178:181], v[62:65]
	v_mfma_f32_16x16x32_bf16 v[58:61], v[150:153], v[178:181], v[58:61]
	v_mfma_f32_16x16x32_bf16 v[38:41], v[142:145], v[186:189], v[38:41]
	v_mfma_f32_16x16x32_bf16 v[34:37], v[150:153], v[186:189], v[34:37]
	v_mfma_f32_16x16x32_bf16 v[22:25], v[142:145], v[194:197], v[22:25]
	v_mfma_f32_16x16x32_bf16 v[18:21], v[150:153], v[194:197], v[18:21]
	v_mfma_f32_16x16x32_bf16 v[134:137], v[142:145], v[202:205], v[134:137]
	v_mfma_f32_16x16x32_bf16 v[130:133], v[150:153], v[202:205], v[130:133]
	v_mfma_f32_16x16x32_bf16 v[62:65], v[146:149], v[182:185], v[62:65]
	v_mfma_f32_16x16x32_bf16 v[58:61], v[158:161], v[182:185], v[58:61]
	v_mfma_f32_16x16x32_bf16 v[38:41], v[146:149], v[190:193], v[38:41]
	v_mfma_f32_16x16x32_bf16 v[34:37], v[158:161], v[190:193], v[34:37]
	v_mfma_f32_16x16x32_bf16 v[22:25], v[146:149], v[198:201], v[22:25]
	v_mfma_f32_16x16x32_bf16 v[18:21], v[158:161], v[198:201], v[18:21]
	v_mfma_f32_16x16x32_bf16 v[134:137], v[146:149], v[206:209], v[134:137]
	v_mfma_f32_16x16x32_bf16 v[130:133], v[158:161], v[206:209], v[130:133]
	s_setprio 0
	s_setprio 1
	v_mfma_f32_16x16x32_bf16 v[42:45], v[162:165], v[178:181], v[42:45]
	v_mfma_f32_16x16x32_bf16 v[46:49], v[170:173], v[178:181], v[46:49]
	v_mfma_f32_16x16x32_bf16 v[26:29], v[162:165], v[186:189], v[26:29]
	v_mfma_f32_16x16x32_bf16 v[30:33], v[170:173], v[186:189], v[30:33]
	v_mfma_f32_16x16x32_bf16 v[14:17], v[162:165], v[194:197], v[14:17]
	v_mfma_f32_16x16x32_bf16 v[10:13], v[170:173], v[194:197], v[10:13]
	v_mfma_f32_16x16x32_bf16 v[6:9], v[162:165], v[202:205], v[6:9]
	v_mfma_f32_16x16x32_bf16 v[2:5], v[170:173], v[202:205], v[2:5]
	v_mfma_f32_16x16x32_bf16 v[42:45], v[166:169], v[182:185], v[42:45]
	v_mfma_f32_16x16x32_bf16 v[46:49], v[174:177], v[182:185], v[46:49]
	v_mfma_f32_16x16x32_bf16 v[26:29], v[166:169], v[190:193], v[26:29]
	v_mfma_f32_16x16x32_bf16 v[30:33], v[174:177], v[190:193], v[30:33]
	v_mfma_f32_16x16x32_bf16 v[14:17], v[166:169], v[198:201], v[14:17]
	v_mfma_f32_16x16x32_bf16 v[10:13], v[174:177], v[198:201], v[10:13]
	v_mfma_f32_16x16x32_bf16 v[6:9], v[166:169], v[206:209], v[6:9]
	v_mfma_f32_16x16x32_bf16 v[2:5], v[174:177], v[206:209], v[2:5]
	s_add_i32 s16, s60, 2
	s_add_u32 vcc_lo, vcc_lo, 0x100
	s_addc_u32 vcc_hi, vcc_hi, 0
	v_lshl_add_u64 v[138:139], v[138:139], 0, s[72:73]
	v_lshl_add_u64 v[128:129], v[128:129], 0, s[72:73]
	s_cmp_ge_i32 s60, s87
	s_mov_b32 s60, s16
	s_setprio 0
	s_barrier
	s_cbranch_scc0 .LBB0_1854
	s_and_b64 vcc, exec, s[40:41]
	s_cbranch_vccz .LBB0_1857
	s_barrier
